# indexer tile steps slimmed: flag inversion via s_not instead of a VALU round trip, head-sum accumulates directly into the score register, no-op flag branches and the (provably dead on the MFMA path) d
# speedup vs baseline: 1.0069x; 1.0060x over previous
.Lixj111:
.LBB0_1147:
.LBB0_1149:
	s_waitcnt lgkmcnt(0)
	ds_read_b128 v[112:115], v131 offset:0x4800
	ds_read_b128 v[88:91], v131 offset:0x4820
	ds_read_b128 v[80:83], v131 offset:0x4840
	ds_read_b128 v[116:119], v131 offset:0x4860
	s_cmp_gt_u32 s95, 5
	s_cselect_b64 s[66:67], -1, 0
	s_cmp_lt_u32 s95, 6
	s_cbranch_scc1 .Lixc110
	v_mfma_f32_32x32x16_bf16 v[0:15], v[32:35], v[104:107], 0
	v_cndmask_b32_e64 v105, 0, 1, s[64:65]
	v_cmp_ne_u32_e64 s[50:51], 1, v105
	s_andn2_b64 vcc, exec, s[64:65]
	v_max_i32_e32 v105, 0, v16
	v_fma_f32 v106, v48, v105, 0
	v_max_i32_e32 v105, 0, v17
	v_fmac_f32_e32 v106, v49, v105
	v_max_i32_e32 v105, 0, v18
	v_fmac_f32_e32 v106, v50, v105
	v_max_i32_e32 v105, 0, v19
	v_fmac_f32_e32 v106, v51, v105
	v_max_i32_e32 v105, 0, v20
	v_fmac_f32_e32 v106, v52, v105
	v_mfma_f32_32x32x16_bf16 v[0:15], v[36:39], v[100:103], v[0:15]
	v_max_i32_e32 v105, 0, v21
	v_fmac_f32_e32 v106, v53, v105
	v_max_i32_e32 v105, 0, v22
	v_fmac_f32_e32 v106, v54, v105
	v_max_i32_e32 v105, 0, v23
	v_fmac_f32_e32 v106, v55, v105
	v_max_i32_e32 v105, 0, v24
	v_fmac_f32_e32 v106, v56, v105
	v_max_i32_e32 v105, 0, v25
	v_fmac_f32_e32 v106, v57, v105
	v_mfma_f32_32x32x16_bf16 v[0:15], v[40:43], v[96:99], v[0:15]
	v_max_i32_e32 v105, 0, v26
	v_fmac_f32_e32 v106, v58, v105
	v_max_i32_e32 v105, 0, v27
	v_fmac_f32_e32 v106, v59, v105
	v_max_i32_e32 v105, 0, v28
	v_fmac_f32_e32 v106, v60, v105
	v_max_i32_e32 v105, 0, v29
	v_fmac_f32_e32 v106, v61, v105
	v_mfma_f32_32x32x16_bf16 v[0:15], v[44:47], v[108:111], v[0:15]
	v_max_i32_e32 v105, 0, v30
	v_fmac_f32_e32 v106, v62, v105
	v_max_i32_e32 v105, 0, v31
	v_fmac_f32_e32 v106, v63, v105
	s_cmp_eq_u32 s58, 3
	v_or_b32_e32 v105, 64, v130
	s_cselect_b64 s[64:65], -1, 0
	v_cmp_gt_i32_e32 vcc, v105, v203
	s_and_b64 vcc, s[64:65], vcc
	s_nop 0
	v_cndmask_b32_e32 v202, v106, v197, vcc
.Lixj110:
.LBB0_1153:
.LBB0_1155:
	s_waitcnt lgkmcnt(0)
	ds_read_b128 v[96:99], v131 offset:0x5a00
	ds_read_b128 v[92:95], v131 offset:0x5a20
	ds_read_b128 v[84:87], v131 offset:0x5a40
	ds_read_b128 v[104:107], v131 offset:0x5a60
	s_cmp_gt_u32 s95, 7
	s_cselect_b64 s[64:65], -1, 0
	s_cmp_lt_u32 s95, 8
	s_cbranch_scc1 .Lixc109
	v_mfma_f32_32x32x16_bf16 v[16:31], v[32:35], v[112:115], 0
	v_cndmask_b32_e64 v113, 0, 1, s[66:67]
	v_cmp_ne_u32_e64 s[50:51], 1, v113
	s_andn2_b64 vcc, exec, s[66:67]
	v_max_i32_e32 v113, 0, v0
	v_fma_f32 v114, v48, v113, 0
	v_max_i32_e32 v113, 0, v1
	v_fmac_f32_e32 v114, v49, v113
	v_max_i32_e32 v113, 0, v2
	v_fmac_f32_e32 v114, v50, v113
	v_max_i32_e32 v113, 0, v3
	v_fmac_f32_e32 v114, v51, v113
	v_max_i32_e32 v113, 0, v4
	v_fmac_f32_e32 v114, v52, v113
	v_mfma_f32_32x32x16_bf16 v[16:31], v[36:39], v[88:91], v[16:31]
	v_max_i32_e32 v113, 0, v5
	v_fmac_f32_e32 v114, v53, v113
	v_max_i32_e32 v113, 0, v6
	v_fmac_f32_e32 v114, v54, v113
	v_max_i32_e32 v113, 0, v7
	v_fmac_f32_e32 v114, v55, v113
	v_max_i32_e32 v113, 0, v8
	v_fmac_f32_e32 v114, v56, v113
	v_max_i32_e32 v113, 0, v9
	v_fmac_f32_e32 v114, v57, v113
	v_mfma_f32_32x32x16_bf16 v[16:31], v[40:43], v[80:83], v[16:31]
	v_max_i32_e32 v113, 0, v10
	v_fmac_f32_e32 v114, v58, v113
	v_max_i32_e32 v113, 0, v11
	v_fmac_f32_e32 v114, v59, v113
	v_max_i32_e32 v113, 0, v12
	v_fmac_f32_e32 v114, v60, v113
	v_max_i32_e32 v113, 0, v13
	v_fmac_f32_e32 v114, v61, v113
	v_mfma_f32_32x32x16_bf16 v[16:31], v[44:47], v[116:119], v[16:31]
	v_max_i32_e32 v113, 0, v14
	v_fmac_f32_e32 v114, v62, v113
	v_max_i32_e32 v113, 0, v15
	v_fmac_f32_e32 v114, v63, v113
	s_cmp_eq_u32 s58, 4
	v_or_b32_e32 v113, 0x60, v130
	s_cselect_b64 s[66:67], -1, 0
	v_cmp_gt_i32_e32 vcc, v113, v203
	s_and_b64 vcc, s[66:67], vcc
	s_nop 0
	v_cndmask_b32_e32 v112, v114, v197, vcc
.Lixj109:
.LBB0_1159:
.LBB0_1161:
	s_waitcnt lgkmcnt(0)
	ds_read_b128 v[100:103], v131 offset:0x6c00
	ds_read_b128 v[88:91], v131 offset:0x6c20
	ds_read_b128 v[80:83], v131 offset:0x6c40
	ds_read_b128 v[108:111], v131 offset:0x6c60
	s_cmp_gt_u32 s95, 9
	s_cselect_b64 s[66:67], -1, 0
	s_cmp_lt_u32 s95, 10
	s_cbranch_scc1 .Lixc108
	v_mfma_f32_32x32x16_bf16 v[0:15], v[32:35], v[96:99], 0
	v_cndmask_b32_e64 v97, 0, 1, s[64:65]
	v_cmp_ne_u32_e64 s[50:51], 1, v97
	s_andn2_b64 vcc, exec, s[64:65]
	v_max_i32_e32 v97, 0, v16
	v_fma_f32 v98, v48, v97, 0
	v_max_i32_e32 v97, 0, v17
	v_fmac_f32_e32 v98, v49, v97
	v_max_i32_e32 v97, 0, v18
	v_fmac_f32_e32 v98, v50, v97
	v_max_i32_e32 v97, 0, v19
	v_fmac_f32_e32 v98, v51, v97
	v_max_i32_e32 v97, 0, v20
	v_fmac_f32_e32 v98, v52, v97
	v_mfma_f32_32x32x16_bf16 v[0:15], v[36:39], v[92:95], v[0:15]
	v_max_i32_e32 v97, 0, v21
	v_fmac_f32_e32 v98, v53, v97
	v_max_i32_e32 v97, 0, v22
	v_fmac_f32_e32 v98, v54, v97
	v_max_i32_e32 v97, 0, v23
	v_fmac_f32_e32 v98, v55, v97
	v_max_i32_e32 v97, 0, v24
	v_fmac_f32_e32 v98, v56, v97
	v_max_i32_e32 v97, 0, v25
	v_fmac_f32_e32 v98, v57, v97
	v_mfma_f32_32x32x16_bf16 v[0:15], v[40:43], v[84:87], v[0:15]
	v_max_i32_e32 v97, 0, v26
	v_fmac_f32_e32 v98, v58, v97
	v_max_i32_e32 v97, 0, v27
	v_fmac_f32_e32 v98, v59, v97
	v_max_i32_e32 v97, 0, v28
	v_fmac_f32_e32 v98, v60, v97
	v_max_i32_e32 v97, 0, v29
	v_fmac_f32_e32 v98, v61, v97
	v_mfma_f32_32x32x16_bf16 v[0:15], v[44:47], v[104:107], v[0:15]
	v_max_i32_e32 v97, 0, v30
	v_fmac_f32_e32 v98, v62, v97
	v_max_i32_e32 v97, 0, v31
	v_fmac_f32_e32 v98, v63, v97
	s_cmp_eq_u32 s58, 5
	v_or_b32_e32 v97, 0x80, v130
	s_cselect_b64 s[64:65], -1, 0
	v_cmp_gt_i32_e32 vcc, v97, v203
	s_and_b64 vcc, s[64:65], vcc
	s_nop 0
	v_cndmask_b32_e32 v113, v98, v197, vcc
.Lixj108:
.LBB0_1165:
.LBB0_1167:
	s_waitcnt lgkmcnt(0)
	ds_read_b128 v[96:99], v131 offset:0x7e00
	ds_read_b128 v[92:95], v131 offset:0x7e20
	ds_read_b128 v[84:87], v131 offset:0x7e40
	ds_read_b128 v[104:107], v131 offset:0x7e60
	s_cmp_gt_u32 s95, 11
	s_cselect_b64 s[64:65], -1, 0
	s_cmp_lt_u32 s95, 12
	s_cbranch_scc1 .Lixc107
	v_mfma_f32_32x32x16_bf16 v[16:31], v[32:35], v[100:103], 0
	v_cndmask_b32_e64 v101, 0, 1, s[66:67]
	v_cmp_ne_u32_e64 s[50:51], 1, v101
	s_andn2_b64 vcc, exec, s[66:67]
	v_max_i32_e32 v101, 0, v0
	v_fma_f32 v102, v48, v101, 0
	v_max_i32_e32 v101, 0, v1
	v_fmac_f32_e32 v102, v49, v101
	v_max_i32_e32 v101, 0, v2
	v_fmac_f32_e32 v102, v50, v101
	v_max_i32_e32 v101, 0, v3
	v_fmac_f32_e32 v102, v51, v101
	v_max_i32_e32 v101, 0, v4
	v_fmac_f32_e32 v102, v52, v101
	v_mfma_f32_32x32x16_bf16 v[16:31], v[36:39], v[88:91], v[16:31]
	v_max_i32_e32 v101, 0, v5
	v_fmac_f32_e32 v102, v53, v101
	v_max_i32_e32 v101, 0, v6
	v_fmac_f32_e32 v102, v54, v101
	v_max_i32_e32 v101, 0, v7
	v_fmac_f32_e32 v102, v55, v101
	v_max_i32_e32 v101, 0, v8
	v_fmac_f32_e32 v102, v56, v101
	v_max_i32_e32 v101, 0, v9
	v_fmac_f32_e32 v102, v57, v101
	v_mfma_f32_32x32x16_bf16 v[16:31], v[40:43], v[80:83], v[16:31]
	v_max_i32_e32 v101, 0, v10
	v_fmac_f32_e32 v102, v58, v101
	v_max_i32_e32 v101, 0, v11
	v_fmac_f32_e32 v102, v59, v101
	v_max_i32_e32 v101, 0, v12
	v_fmac_f32_e32 v102, v60, v101
	v_max_i32_e32 v101, 0, v13
	v_fmac_f32_e32 v102, v61, v101
	v_mfma_f32_32x32x16_bf16 v[16:31], v[44:47], v[108:111], v[16:31]
	v_max_i32_e32 v101, 0, v14
	v_fmac_f32_e32 v102, v62, v101
	v_max_i32_e32 v101, 0, v15
	v_fmac_f32_e32 v102, v63, v101
	s_cmp_eq_u32 s58, 6
	v_or_b32_e32 v101, 0xa0, v130
	s_cselect_b64 s[66:67], -1, 0
	v_cmp_gt_i32_e32 vcc, v101, v203
	s_and_b64 vcc, s[66:67], vcc
	s_nop 0
	v_cndmask_b32_e32 v114, v102, v197, vcc
.Lixj107:
.LBB0_1171:
.LBB0_1173:
	s_waitcnt lgkmcnt(0)
	s_cmp_lt_u32 s95, 14
	s_cbranch_scc1 .Lixc106
	v_mfma_f32_32x32x16_bf16 v[0:15], v[32:35], v[96:99], 0
	s_not_b64 s[50:51], s[64:65]
	v_max_i32_e32 v97, 0, v16
	v_fma_f32 v115, v48, v97, 0
	v_max_i32_e32 v97, 0, v17
	v_fmac_f32_e32 v115, v49, v97
	v_max_i32_e32 v97, 0, v18
	v_fmac_f32_e32 v115, v50, v97
	v_max_i32_e32 v97, 0, v19
	v_fmac_f32_e32 v115, v51, v97
	v_max_i32_e32 v97, 0, v20
	v_fmac_f32_e32 v115, v52, v97
	v_mfma_f32_32x32x16_bf16 v[0:15], v[36:39], v[92:95], v[0:15]
	v_max_i32_e32 v97, 0, v21
	v_fmac_f32_e32 v115, v53, v97
	v_max_i32_e32 v97, 0, v22
	v_fmac_f32_e32 v115, v54, v97
	v_max_i32_e32 v97, 0, v23
	v_fmac_f32_e32 v115, v55, v97
	v_max_i32_e32 v97, 0, v24
	v_fmac_f32_e32 v115, v56, v97
	v_max_i32_e32 v97, 0, v25
	v_fmac_f32_e32 v115, v57, v97
	v_mfma_f32_32x32x16_bf16 v[0:15], v[40:43], v[84:87], v[0:15]
	v_max_i32_e32 v97, 0, v26
	v_fmac_f32_e32 v115, v58, v97
	v_max_i32_e32 v97, 0, v27
	v_fmac_f32_e32 v115, v59, v97
	v_max_i32_e32 v97, 0, v28
	v_fmac_f32_e32 v115, v60, v97
	v_max_i32_e32 v97, 0, v29
	v_fmac_f32_e32 v115, v61, v97
	v_mfma_f32_32x32x16_bf16 v[0:15], v[44:47], v[104:107], v[0:15]
	v_max_i32_e32 v97, 0, v30
	v_fmac_f32_e32 v115, v62, v97
	v_max_i32_e32 v97, 0, v31
	v_fmac_f32_e32 v115, v63, v97
.Lixj106:
.LBB0_1177:
.LBB0_1179:
	v_cndmask_b32_e64 v16, 0, 1, s[62:63]
	v_cmp_ne_u32_e64 s[50:51], 1, v16
	s_andn2_b64 vcc, exec, s[62:63]
	s_cbranch_vccnz .LBB0_1181
	s_waitcnt vmcnt(3)
	ds_write_b128 v193, v[64:67] offset:36864
	s_waitcnt vmcnt(2)
	ds_write_b128 v194, v[68:71] offset:36864
	s_waitcnt vmcnt(1)
	ds_write_b128 v195, v[72:75] offset:36864
	s_waitcnt vmcnt(0)
	ds_write_b128 v196, v[76:79] offset:36864

.Lixj105:
	s_waitcnt lgkmcnt(0)
	ds_read_b128 v[96:99], v134 offset:0x3600
	ds_read_b128 v[88:91], v134 offset:0x3620
	ds_read_b128 v[80:83], v134 offset:0x3640
	ds_read_b128 v[104:107], v134 offset:0x3660
	s_cmp_gt_u32 s95, 19
	s_cselect_b64 s[64:65], -1, 0
	s_cmp_lt_u32 s95, 20
	s_cbranch_scc1 .Lixc104
	v_mfma_f32_32x32x16_bf16 v[16:31], v[32:35], v[108:111], 0
	s_not_b64 s[52:53], s[66:67]
	v_max_i32_e32 v109, 0, v0
	v_fma_f32 v118, v48, v109, 0
	v_max_i32_e32 v109, 0, v1
	v_fmac_f32_e32 v118, v49, v109
	v_max_i32_e32 v109, 0, v2
	v_fmac_f32_e32 v118, v50, v109
	v_max_i32_e32 v109, 0, v3
	v_fmac_f32_e32 v118, v51, v109
	v_max_i32_e32 v109, 0, v4
	v_fmac_f32_e32 v118, v52, v109
	v_mfma_f32_32x32x16_bf16 v[16:31], v[36:39], v[100:103], v[16:31]
	v_max_i32_e32 v109, 0, v5
	v_fmac_f32_e32 v118, v53, v109
	v_max_i32_e32 v109, 0, v6
	v_fmac_f32_e32 v118, v54, v109
	v_max_i32_e32 v109, 0, v7
	v_fmac_f32_e32 v118, v55, v109
	v_max_i32_e32 v109, 0, v8
	v_fmac_f32_e32 v118, v56, v109
	v_max_i32_e32 v109, 0, v9
	v_fmac_f32_e32 v118, v57, v109
	v_mfma_f32_32x32x16_bf16 v[16:31], v[40:43], v[92:95], v[16:31]
	v_max_i32_e32 v109, 0, v10
	v_fmac_f32_e32 v118, v58, v109
	v_max_i32_e32 v109, 0, v11
	v_fmac_f32_e32 v118, v59, v109
	v_max_i32_e32 v109, 0, v12
	v_fmac_f32_e32 v118, v60, v109
	v_max_i32_e32 v109, 0, v13
	v_fmac_f32_e32 v118, v61, v109
	v_mfma_f32_32x32x16_bf16 v[16:31], v[44:47], v[84:87], v[16:31]
	v_max_i32_e32 v109, 0, v14
	v_fmac_f32_e32 v118, v62, v109
	v_max_i32_e32 v109, 0, v15
	v_fmac_f32_e32 v118, v63, v109
.Lixj104:
.LBB0_1194:
.LBB0_1196:
	s_waitcnt lgkmcnt(0)
	ds_read_b128 v[100:103], v134 offset:0x4800
	ds_read_b128 v[92:95], v134 offset:0x4820
	ds_read_b128 v[84:87], v134 offset:0x4840
	ds_read_b128 v[108:111], v134 offset:0x4860
	s_cmp_gt_u32 s95, 21
	s_cselect_b64 s[66:67], -1, 0
	s_cmp_lt_u32 s95, 22
	s_cbranch_scc1 .Lixc103
	v_mfma_f32_32x32x16_bf16 v[0:15], v[32:35], v[96:99], 0
	s_not_b64 s[52:53], s[64:65]
	v_max_i32_e32 v97, 0, v16
	v_fma_f32 v119, v48, v97, 0
	v_max_i32_e32 v97, 0, v17
	v_fmac_f32_e32 v119, v49, v97
	v_max_i32_e32 v97, 0, v18
	v_fmac_f32_e32 v119, v50, v97
	v_max_i32_e32 v97, 0, v19
	v_fmac_f32_e32 v119, v51, v97
	v_max_i32_e32 v97, 0, v20
	v_fmac_f32_e32 v119, v52, v97
	v_mfma_f32_32x32x16_bf16 v[0:15], v[36:39], v[88:91], v[0:15]
	v_max_i32_e32 v97, 0, v21
	v_fmac_f32_e32 v119, v53, v97
	v_max_i32_e32 v97, 0, v22
	v_fmac_f32_e32 v119, v54, v97
	v_max_i32_e32 v97, 0, v23
	v_fmac_f32_e32 v119, v55, v97
	v_max_i32_e32 v97, 0, v24
	v_fmac_f32_e32 v119, v56, v97
	v_max_i32_e32 v97, 0, v25
	v_fmac_f32_e32 v119, v57, v97
	v_mfma_f32_32x32x16_bf16 v[0:15], v[40:43], v[80:83], v[0:15]
	v_max_i32_e32 v97, 0, v26
	v_fmac_f32_e32 v119, v58, v97
	v_max_i32_e32 v97, 0, v27
	v_fmac_f32_e32 v119, v59, v97
	v_max_i32_e32 v97, 0, v28
	v_fmac_f32_e32 v119, v60, v97
	v_max_i32_e32 v97, 0, v29
	v_fmac_f32_e32 v119, v61, v97
	v_mfma_f32_32x32x16_bf16 v[0:15], v[44:47], v[104:107], v[0:15]
	v_max_i32_e32 v97, 0, v30
	v_fmac_f32_e32 v119, v62, v97
	v_max_i32_e32 v97, 0, v31
	v_fmac_f32_e32 v119, v63, v97
.Lixj103:
.LBB0_1200:
.LBB0_1202:
	s_waitcnt lgkmcnt(0)
	ds_read_b128 v[96:99], v134 offset:0x5a00
	ds_read_b128 v[88:91], v134 offset:0x5a20
	ds_read_b128 v[80:83], v134 offset:0x5a40
	ds_read_b128 v[104:107], v134 offset:0x5a60
	s_cmp_gt_u32 s95, 23
	s_cselect_b64 s[64:65], -1, 0
	s_cmp_lt_u32 s95, 24
	s_cbranch_scc1 .Lixc102
	v_mfma_f32_32x32x16_bf16 v[16:31], v[32:35], v[100:103], 0
	s_not_b64 s[52:53], s[66:67]
	v_max_i32_e32 v101, 0, v0
	v_fma_f32 v205, v48, v101, 0
	v_max_i32_e32 v101, 0, v1
	v_fmac_f32_e32 v205, v49, v101
	v_max_i32_e32 v101, 0, v2
	v_fmac_f32_e32 v205, v50, v101
	v_max_i32_e32 v101, 0, v3
	v_fmac_f32_e32 v205, v51, v101
	v_max_i32_e32 v101, 0, v4
	v_fmac_f32_e32 v205, v52, v101
	v_mfma_f32_32x32x16_bf16 v[16:31], v[36:39], v[92:95], v[16:31]
	v_max_i32_e32 v101, 0, v5
	v_fmac_f32_e32 v205, v53, v101
	v_max_i32_e32 v101, 0, v6
	v_fmac_f32_e32 v205, v54, v101
	v_max_i32_e32 v101, 0, v7
	v_fmac_f32_e32 v205, v55, v101
	v_max_i32_e32 v101, 0, v8
	v_fmac_f32_e32 v205, v56, v101
	v_max_i32_e32 v101, 0, v9
	v_fmac_f32_e32 v205, v57, v101
	v_mfma_f32_32x32x16_bf16 v[16:31], v[40:43], v[84:87], v[16:31]
	v_max_i32_e32 v101, 0, v10
	v_fmac_f32_e32 v205, v58, v101
	v_max_i32_e32 v101, 0, v11
	v_fmac_f32_e32 v205, v59, v101
	v_max_i32_e32 v101, 0, v12
	v_fmac_f32_e32 v205, v60, v101
	v_max_i32_e32 v101, 0, v13
	v_fmac_f32_e32 v205, v61, v101
	v_mfma_f32_32x32x16_bf16 v[16:31], v[44:47], v[108:111], v[16:31]
	v_max_i32_e32 v101, 0, v14
	v_fmac_f32_e32 v205, v62, v101
	v_max_i32_e32 v101, 0, v15
	v_fmac_f32_e32 v205, v63, v101
.Lixj102:
.LBB0_1206:
.LBB0_1208:
	s_waitcnt lgkmcnt(0)
	ds_read_b128 v[100:103], v134 offset:0x6c00
	ds_read_b128 v[92:95], v134 offset:0x6c20
	ds_read_b128 v[84:87], v134 offset:0x6c40
	ds_read_b128 v[108:111], v134 offset:0x6c60
	s_cmp_gt_u32 s95, 25
	s_cselect_b64 s[66:67], -1, 0
	s_cmp_lt_u32 s95, 26
	s_cbranch_scc1 .Lixc101
	v_mfma_f32_32x32x16_bf16 v[0:15], v[32:35], v[96:99], 0
	s_not_b64 s[52:53], s[64:65]
	v_max_i32_e32 v97, 0, v16
	v_fma_f32 v206, v48, v97, 0
	v_max_i32_e32 v97, 0, v17
	v_fmac_f32_e32 v206, v49, v97
	v_max_i32_e32 v97, 0, v18
	v_fmac_f32_e32 v206, v50, v97
	v_max_i32_e32 v97, 0, v19
	v_fmac_f32_e32 v206, v51, v97
	v_max_i32_e32 v97, 0, v20
	v_fmac_f32_e32 v206, v52, v97
	v_mfma_f32_32x32x16_bf16 v[0:15], v[36:39], v[88:91], v[0:15]
	v_max_i32_e32 v97, 0, v21
	v_fmac_f32_e32 v206, v53, v97
	v_max_i32_e32 v97, 0, v22
	v_fmac_f32_e32 v206, v54, v97
	v_max_i32_e32 v97, 0, v23
	v_fmac_f32_e32 v206, v55, v97
	v_max_i32_e32 v97, 0, v24
	v_fmac_f32_e32 v206, v56, v97
	v_max_i32_e32 v97, 0, v25
	v_fmac_f32_e32 v206, v57, v97
	v_mfma_f32_32x32x16_bf16 v[0:15], v[40:43], v[80:83], v[0:15]
	v_max_i32_e32 v97, 0, v26
	v_fmac_f32_e32 v206, v58, v97
	v_max_i32_e32 v97, 0, v27
	v_fmac_f32_e32 v206, v59, v97
	v_max_i32_e32 v97, 0, v28
	v_fmac_f32_e32 v206, v60, v97
	v_max_i32_e32 v97, 0, v29
	v_fmac_f32_e32 v206, v61, v97
	v_mfma_f32_32x32x16_bf16 v[0:15], v[44:47], v[104:107], v[0:15]
	v_max_i32_e32 v97, 0, v30
	v_fmac_f32_e32 v206, v62, v97
	v_max_i32_e32 v97, 0, v31
	v_fmac_f32_e32 v206, v63, v97
.Lixj101:
.LBB0_1212:
.LBB0_1214:
	s_waitcnt lgkmcnt(0)
	ds_read_b128 v[96:99], v134 offset:0x7e00
	ds_read_b128 v[88:91], v134 offset:0x7e20
	ds_read_b128 v[80:83], v134 offset:0x7e40
	ds_read_b128 v[104:107], v134 offset:0x7e60
	s_cmp_gt_u32 s95, 27
	s_cselect_b64 s[64:65], -1, 0
	s_cmp_lt_u32 s95, 28
	s_cbranch_scc1 .Lixc100
	v_mfma_f32_32x32x16_bf16 v[16:31], v[32:35], v[100:103], 0
	s_not_b64 s[52:53], s[66:67]
	v_max_i32_e32 v101, 0, v0
	v_fma_f32 v207, v48, v101, 0
	v_max_i32_e32 v101, 0, v1
	v_fmac_f32_e32 v207, v49, v101
	v_max_i32_e32 v101, 0, v2
	v_fmac_f32_e32 v207, v50, v101
	v_max_i32_e32 v101, 0, v3
	v_fmac_f32_e32 v207, v51, v101
	v_max_i32_e32 v101, 0, v4
	v_fmac_f32_e32 v207, v52, v101
	v_mfma_f32_32x32x16_bf16 v[16:31], v[36:39], v[92:95], v[16:31]
	v_max_i32_e32 v101, 0, v5
	v_fmac_f32_e32 v207, v53, v101
	v_max_i32_e32 v101, 0, v6
	v_fmac_f32_e32 v207, v54, v101
	v_max_i32_e32 v101, 0, v7
	v_fmac_f32_e32 v207, v55, v101
	v_max_i32_e32 v101, 0, v8
	v_fmac_f32_e32 v207, v56, v101
	v_max_i32_e32 v101, 0, v9
	v_fmac_f32_e32 v207, v57, v101
	v_mfma_f32_32x32x16_bf16 v[16:31], v[40:43], v[84:87], v[16:31]
	v_max_i32_e32 v101, 0, v10
	v_fmac_f32_e32 v207, v58, v101
	v_max_i32_e32 v101, 0, v11
	v_fmac_f32_e32 v207, v59, v101
	v_max_i32_e32 v101, 0, v12
	v_fmac_f32_e32 v207, v60, v101
	v_max_i32_e32 v101, 0, v13
	v_fmac_f32_e32 v207, v61, v101
	v_mfma_f32_32x32x16_bf16 v[16:31], v[44:47], v[108:111], v[16:31]
	v_max_i32_e32 v101, 0, v14
	v_fmac_f32_e32 v207, v62, v101
	v_max_i32_e32 v101, 0, v15
	v_fmac_f32_e32 v207, v63, v101
.Lixj100:
.LBB0_1218:
.LBB0_1220:
	s_waitcnt lgkmcnt(0)
	s_cmp_lt_u32 s95, 30
	s_cbranch_scc1 .Lixc99
	v_mfma_f32_32x32x16_bf16 v[0:15], v[32:35], v[96:99], 0
	s_not_b64 s[52:53], s[64:65]
	s_nop 1
	v_max_i32_e32 v97, 0, v16
	v_fma_f32 v208, v48, v97, 0
	v_max_i32_e32 v97, 0, v17
	v_fmac_f32_e32 v208, v49, v97
	v_max_i32_e32 v97, 0, v18
	v_fmac_f32_e32 v208, v50, v97
	v_max_i32_e32 v97, 0, v19
	v_fmac_f32_e32 v208, v51, v97
	v_max_i32_e32 v97, 0, v20
	v_fmac_f32_e32 v208, v52, v97
	v_mfma_f32_32x32x16_bf16 v[0:15], v[36:39], v[88:91], v[0:15]
	v_max_i32_e32 v97, 0, v21
	v_fmac_f32_e32 v208, v53, v97
	v_max_i32_e32 v97, 0, v22
	v_fmac_f32_e32 v208, v54, v97
	v_max_i32_e32 v97, 0, v23
	v_fmac_f32_e32 v208, v55, v97
	v_max_i32_e32 v97, 0, v24
	v_fmac_f32_e32 v208, v56, v97
	v_max_i32_e32 v97, 0, v25
	v_fmac_f32_e32 v208, v57, v97
	v_mfma_f32_32x32x16_bf16 v[0:15], v[40:43], v[80:83], v[0:15]
	v_max_i32_e32 v97, 0, v26
	v_fmac_f32_e32 v208, v58, v97
	v_max_i32_e32 v97, 0, v27
	v_fmac_f32_e32 v208, v59, v97
	v_max_i32_e32 v97, 0, v28
	v_fmac_f32_e32 v208, v60, v97
	v_max_i32_e32 v97, 0, v29
	v_fmac_f32_e32 v208, v61, v97
	v_mfma_f32_32x32x16_bf16 v[0:15], v[44:47], v[104:107], v[0:15]
	v_max_i32_e32 v97, 0, v30
	v_fmac_f32_e32 v208, v62, v97
	v_max_i32_e32 v97, 0, v31
	v_fmac_f32_e32 v208, v63, v97
.Lixj99:
.LBB0_1224:
.LBB0_1226:
	s_andn2_b64 vcc, exec, s[62:63]
	s_cbranch_vccnz .LBB0_1228
	s_waitcnt vmcnt(3)
	ds_write_b128 v193, v[64:67]
	s_waitcnt vmcnt(2)
	ds_write_b128 v194, v[68:71]
	s_waitcnt vmcnt(1)
	ds_write_b128 v195, v[72:75]
	s_waitcnt vmcnt(0)
	ds_write_b128 v196, v[76:79]

.Lixj98:
	s_waitcnt lgkmcnt(0)
	ds_read_b128 v[96:99], v131 offset:0x3600
	ds_read_b128 v[88:91], v131 offset:0x3620
	ds_read_b128 v[80:83], v131 offset:0x3640
	ds_read_b128 v[104:107], v131 offset:0x3660
	s_cmp_gt_u32 s95, 35
	s_cselect_b64 s[64:65], -1, 0
	s_cmp_lt_u32 s95, 36
	s_cbranch_scc1 .Lixc97
	v_mfma_f32_32x32x16_bf16 v[16:31], v[32:35], v[108:111], 0
	s_not_b64 s[52:53], s[66:67]
	v_max_i32_e32 v109, 0, v0
	v_fma_f32 v211, v48, v109, 0
	v_max_i32_e32 v109, 0, v1
	v_fmac_f32_e32 v211, v49, v109
	v_max_i32_e32 v109, 0, v2
	v_fmac_f32_e32 v211, v50, v109
	v_max_i32_e32 v109, 0, v3
	v_fmac_f32_e32 v211, v51, v109
	v_max_i32_e32 v109, 0, v4
	v_fmac_f32_e32 v211, v52, v109
	v_mfma_f32_32x32x16_bf16 v[16:31], v[36:39], v[100:103], v[16:31]
	v_max_i32_e32 v109, 0, v5
	v_fmac_f32_e32 v211, v53, v109
	v_max_i32_e32 v109, 0, v6
	v_fmac_f32_e32 v211, v54, v109
	v_max_i32_e32 v109, 0, v7
	v_fmac_f32_e32 v211, v55, v109
	v_max_i32_e32 v109, 0, v8
	v_fmac_f32_e32 v211, v56, v109
	v_max_i32_e32 v109, 0, v9
	v_fmac_f32_e32 v211, v57, v109
	v_mfma_f32_32x32x16_bf16 v[16:31], v[40:43], v[92:95], v[16:31]
	v_max_i32_e32 v109, 0, v10
	v_fmac_f32_e32 v211, v58, v109
	v_max_i32_e32 v109, 0, v11
	v_fmac_f32_e32 v211, v59, v109
	v_max_i32_e32 v109, 0, v12
	v_fmac_f32_e32 v211, v60, v109
	v_max_i32_e32 v109, 0, v13
	v_fmac_f32_e32 v211, v61, v109
	v_mfma_f32_32x32x16_bf16 v[16:31], v[44:47], v[84:87], v[16:31]
	v_max_i32_e32 v109, 0, v14
	v_fmac_f32_e32 v211, v62, v109
	v_max_i32_e32 v109, 0, v15
	v_fmac_f32_e32 v211, v63, v109
.Lixj97:
.LBB0_1238:
.LBB0_1240:
	s_waitcnt lgkmcnt(0)
	ds_read_b128 v[100:103], v131 offset:0x4800
	ds_read_b128 v[92:95], v131 offset:0x4820
	ds_read_b128 v[84:87], v131 offset:0x4840
	ds_read_b128 v[108:111], v131 offset:0x4860
	s_cmp_gt_u32 s95, 37
	s_cselect_b64 s[66:67], -1, 0
	s_cmp_lt_u32 s95, 38
	s_cbranch_scc1 .Lixc96
	v_mfma_f32_32x32x16_bf16 v[0:15], v[32:35], v[96:99], 0
	s_not_b64 s[52:53], s[64:65]
	v_max_i32_e32 v97, 0, v16
	v_fma_f32 v212, v48, v97, 0
	v_max_i32_e32 v97, 0, v17
	v_fmac_f32_e32 v212, v49, v97
	v_max_i32_e32 v97, 0, v18
	v_fmac_f32_e32 v212, v50, v97
	v_max_i32_e32 v97, 0, v19
	v_fmac_f32_e32 v212, v51, v97
	v_max_i32_e32 v97, 0, v20
	v_fmac_f32_e32 v212, v52, v97
	v_mfma_f32_32x32x16_bf16 v[0:15], v[36:39], v[88:91], v[0:15]
	v_max_i32_e32 v97, 0, v21
	v_fmac_f32_e32 v212, v53, v97
	v_max_i32_e32 v97, 0, v22
	v_fmac_f32_e32 v212, v54, v97
	v_max_i32_e32 v97, 0, v23
	v_fmac_f32_e32 v212, v55, v97
	v_max_i32_e32 v97, 0, v24
	v_fmac_f32_e32 v212, v56, v97
	v_max_i32_e32 v97, 0, v25
	v_fmac_f32_e32 v212, v57, v97
	v_mfma_f32_32x32x16_bf16 v[0:15], v[40:43], v[80:83], v[0:15]
	v_max_i32_e32 v97, 0, v26
	v_fmac_f32_e32 v212, v58, v97
	v_max_i32_e32 v97, 0, v27
	v_fmac_f32_e32 v212, v59, v97
	v_max_i32_e32 v97, 0, v28
	v_fmac_f32_e32 v212, v60, v97
	v_max_i32_e32 v97, 0, v29
	v_fmac_f32_e32 v212, v61, v97
	v_mfma_f32_32x32x16_bf16 v[0:15], v[44:47], v[104:107], v[0:15]
	v_max_i32_e32 v97, 0, v30
	v_fmac_f32_e32 v212, v62, v97
	v_max_i32_e32 v97, 0, v31
	v_fmac_f32_e32 v212, v63, v97
.Lixj96:
.LBB0_1244:
.LBB0_1246:
	s_waitcnt lgkmcnt(0)
	ds_read_b128 v[96:99], v131 offset:0x5a00
	ds_read_b128 v[88:91], v131 offset:0x5a20
	ds_read_b128 v[80:83], v131 offset:0x5a40
	ds_read_b128 v[104:107], v131 offset:0x5a60
	s_cmp_gt_u32 s95, 39
	s_cselect_b64 s[64:65], -1, 0
	s_cmp_lt_u32 s95, 40
	s_cbranch_scc1 .Lixc95
	v_mfma_f32_32x32x16_bf16 v[16:31], v[32:35], v[100:103], 0
	s_not_b64 s[52:53], s[66:67]
	v_max_i32_e32 v101, 0, v0
	v_fma_f32 v213, v48, v101, 0
	v_max_i32_e32 v101, 0, v1
	v_fmac_f32_e32 v213, v49, v101
	v_max_i32_e32 v101, 0, v2
	v_fmac_f32_e32 v213, v50, v101
	v_max_i32_e32 v101, 0, v3
	v_fmac_f32_e32 v213, v51, v101
	v_max_i32_e32 v101, 0, v4
	v_fmac_f32_e32 v213, v52, v101
	v_mfma_f32_32x32x16_bf16 v[16:31], v[36:39], v[92:95], v[16:31]
	v_max_i32_e32 v101, 0, v5
	v_fmac_f32_e32 v213, v53, v101
	v_max_i32_e32 v101, 0, v6
	v_fmac_f32_e32 v213, v54, v101
	v_max_i32_e32 v101, 0, v7
	v_fmac_f32_e32 v213, v55, v101
	v_max_i32_e32 v101, 0, v8
	v_fmac_f32_e32 v213, v56, v101
	v_max_i32_e32 v101, 0, v9
	v_fmac_f32_e32 v213, v57, v101
	v_mfma_f32_32x32x16_bf16 v[16:31], v[40:43], v[84:87], v[16:31]
	v_max_i32_e32 v101, 0, v10
	v_fmac_f32_e32 v213, v58, v101
	v_max_i32_e32 v101, 0, v11
	v_fmac_f32_e32 v213, v59, v101
	v_max_i32_e32 v101, 0, v12
	v_fmac_f32_e32 v213, v60, v101
	v_max_i32_e32 v101, 0, v13
	v_fmac_f32_e32 v213, v61, v101
	v_mfma_f32_32x32x16_bf16 v[16:31], v[44:47], v[108:111], v[16:31]
	v_max_i32_e32 v101, 0, v14
	v_fmac_f32_e32 v213, v62, v101
	v_max_i32_e32 v101, 0, v15
	v_fmac_f32_e32 v213, v63, v101
.Lixj95:
.LBB0_1250:
.LBB0_1252:
	s_waitcnt lgkmcnt(0)
	ds_read_b128 v[100:103], v131 offset:0x6c00
	ds_read_b128 v[92:95], v131 offset:0x6c20
	ds_read_b128 v[84:87], v131 offset:0x6c40
	ds_read_b128 v[108:111], v131 offset:0x6c60
	s_cmp_gt_u32 s95, 41
	s_cselect_b64 s[66:67], -1, 0
	s_cmp_lt_u32 s95, 42
	s_cbranch_scc1 .Lixc94
	v_mfma_f32_32x32x16_bf16 v[0:15], v[32:35], v[96:99], 0
	s_not_b64 s[52:53], s[64:65]
	v_max_i32_e32 v97, 0, v16
	v_fma_f32 v214, v48, v97, 0
	v_max_i32_e32 v97, 0, v17
	v_fmac_f32_e32 v214, v49, v97
	v_max_i32_e32 v97, 0, v18
	v_fmac_f32_e32 v214, v50, v97
	v_max_i32_e32 v97, 0, v19
	v_fmac_f32_e32 v214, v51, v97
	v_max_i32_e32 v97, 0, v20
	v_fmac_f32_e32 v214, v52, v97
	v_mfma_f32_32x32x16_bf16 v[0:15], v[36:39], v[88:91], v[0:15]
	v_max_i32_e32 v97, 0, v21
	v_fmac_f32_e32 v214, v53, v97
	v_max_i32_e32 v97, 0, v22
	v_fmac_f32_e32 v214, v54, v97
	v_max_i32_e32 v97, 0, v23
	v_fmac_f32_e32 v214, v55, v97
	v_max_i32_e32 v97, 0, v24
	v_fmac_f32_e32 v214, v56, v97
	v_max_i32_e32 v97, 0, v25
	v_fmac_f32_e32 v214, v57, v97
	v_mfma_f32_32x32x16_bf16 v[0:15], v[40:43], v[80:83], v[0:15]
	v_max_i32_e32 v97, 0, v26
	v_fmac_f32_e32 v214, v58, v97
	v_max_i32_e32 v97, 0, v27
	v_fmac_f32_e32 v214, v59, v97
	v_max_i32_e32 v97, 0, v28
	v_fmac_f32_e32 v214, v60, v97
	v_max_i32_e32 v97, 0, v29
	v_fmac_f32_e32 v214, v61, v97
	v_mfma_f32_32x32x16_bf16 v[0:15], v[44:47], v[104:107], v[0:15]
	v_max_i32_e32 v97, 0, v30
	v_fmac_f32_e32 v214, v62, v97
	v_max_i32_e32 v97, 0, v31
	v_fmac_f32_e32 v214, v63, v97
.Lixj94:
.LBB0_1256:
.LBB0_1258:
	s_waitcnt lgkmcnt(0)
	ds_read_b128 v[96:99], v131 offset:0x7e00
	ds_read_b128 v[88:91], v131 offset:0x7e20
	ds_read_b128 v[80:83], v131 offset:0x7e40
	ds_read_b128 v[104:107], v131 offset:0x7e60
	s_cmp_gt_u32 s95, 43
	s_cselect_b64 s[64:65], -1, 0
	s_cmp_lt_u32 s95, 44
	s_cbranch_scc1 .Lixc93
	v_mfma_f32_32x32x16_bf16 v[16:31], v[32:35], v[100:103], 0
	s_not_b64 s[52:53], s[66:67]
	v_max_i32_e32 v101, 0, v0
	v_fma_f32 v216, v48, v101, 0
	v_max_i32_e32 v101, 0, v1
	v_fmac_f32_e32 v216, v49, v101
	v_max_i32_e32 v101, 0, v2
	v_fmac_f32_e32 v216, v50, v101
	v_max_i32_e32 v101, 0, v3
	v_fmac_f32_e32 v216, v51, v101
	v_max_i32_e32 v101, 0, v4
	v_fmac_f32_e32 v216, v52, v101
	v_mfma_f32_32x32x16_bf16 v[16:31], v[36:39], v[92:95], v[16:31]
	v_max_i32_e32 v101, 0, v5
	v_fmac_f32_e32 v216, v53, v101
	v_max_i32_e32 v101, 0, v6
	v_fmac_f32_e32 v216, v54, v101
	v_max_i32_e32 v101, 0, v7
	v_fmac_f32_e32 v216, v55, v101
	v_max_i32_e32 v101, 0, v8
	v_fmac_f32_e32 v216, v56, v101
	v_max_i32_e32 v101, 0, v9
	v_fmac_f32_e32 v216, v57, v101
	v_mfma_f32_32x32x16_bf16 v[16:31], v[40:43], v[84:87], v[16:31]
	v_max_i32_e32 v101, 0, v10
	v_fmac_f32_e32 v216, v58, v101
	v_max_i32_e32 v101, 0, v11
	v_fmac_f32_e32 v216, v59, v101
	v_max_i32_e32 v101, 0, v12
	v_fmac_f32_e32 v216, v60, v101
	v_max_i32_e32 v101, 0, v13
	v_fmac_f32_e32 v216, v61, v101
	v_mfma_f32_32x32x16_bf16 v[16:31], v[44:47], v[108:111], v[16:31]
	v_max_i32_e32 v101, 0, v14
	v_fmac_f32_e32 v216, v62, v101
	v_max_i32_e32 v101, 0, v15
	v_fmac_f32_e32 v216, v63, v101
.Lixj93:
.LBB0_1262:
.LBB0_1264:
	s_waitcnt lgkmcnt(0)
	s_cmp_lt_u32 s95, 46
	s_cbranch_scc1 .Lixc92
	v_mfma_f32_32x32x16_bf16 v[0:15], v[32:35], v[96:99], 0
	s_not_b64 s[52:53], s[64:65]
	s_nop 1
	v_max_i32_e32 v97, 0, v16
	v_fma_f32 v217, v48, v97, 0
	v_max_i32_e32 v97, 0, v17
	v_fmac_f32_e32 v217, v49, v97
	v_max_i32_e32 v97, 0, v18
	v_fmac_f32_e32 v217, v50, v97
	v_max_i32_e32 v97, 0, v19
	v_fmac_f32_e32 v217, v51, v97
	v_max_i32_e32 v97, 0, v20
	v_fmac_f32_e32 v217, v52, v97
	v_mfma_f32_32x32x16_bf16 v[0:15], v[36:39], v[88:91], v[0:15]
	v_max_i32_e32 v97, 0, v21
	v_fmac_f32_e32 v217, v53, v97
	v_max_i32_e32 v97, 0, v22
	v_fmac_f32_e32 v217, v54, v97
	v_max_i32_e32 v97, 0, v23
	v_fmac_f32_e32 v217, v55, v97
	v_max_i32_e32 v97, 0, v24
	v_fmac_f32_e32 v217, v56, v97
	v_max_i32_e32 v97, 0, v25
	v_fmac_f32_e32 v217, v57, v97
	v_mfma_f32_32x32x16_bf16 v[0:15], v[40:43], v[80:83], v[0:15]
	v_max_i32_e32 v97, 0, v26
	v_fmac_f32_e32 v217, v58, v97
	v_max_i32_e32 v97, 0, v27
	v_fmac_f32_e32 v217, v59, v97
	v_max_i32_e32 v97, 0, v28
	v_fmac_f32_e32 v217, v60, v97
	v_max_i32_e32 v97, 0, v29
	v_fmac_f32_e32 v217, v61, v97
	v_mfma_f32_32x32x16_bf16 v[0:15], v[44:47], v[104:107], v[0:15]
	v_max_i32_e32 v97, 0, v30
	v_fmac_f32_e32 v217, v62, v97
	v_max_i32_e32 v97, 0, v31
	v_fmac_f32_e32 v217, v63, v97
.Lixj92:
.LBB0_1268:
.LBB0_1270:
	s_andn2_b64 vcc, exec, s[62:63]
	s_cbranch_vccnz .LBB0_1272
	s_waitcnt vmcnt(3)
	ds_write_b128 v193, v[64:67] offset:36864
	s_waitcnt vmcnt(2)
	ds_write_b128 v194, v[68:71] offset:36864
	s_waitcnt vmcnt(1)
	ds_write_b128 v195, v[72:75] offset:36864
	s_waitcnt vmcnt(0)
	ds_write_b128 v196, v[76:79] offset:36864

.Lixj91:
	s_waitcnt lgkmcnt(0)
	ds_read_b128 v[96:99], v134 offset:0x3600
	ds_read_b128 v[88:91], v134 offset:0x3620
	ds_read_b128 v[80:83], v134 offset:0x3640
	ds_read_b128 v[104:107], v134 offset:0x3660
	s_cmp_gt_u32 s95, 51
	s_cselect_b64 s[64:65], -1, 0
	s_cmp_lt_u32 s95, 52
	s_cbranch_scc1 .Lixc90
	v_mfma_f32_32x32x16_bf16 v[16:31], v[32:35], v[108:111], 0
	s_not_b64 s[52:53], s[66:67]
	v_max_i32_e32 v109, 0, v0
	v_fma_f32 v220, v48, v109, 0
	v_max_i32_e32 v109, 0, v1
	v_fmac_f32_e32 v220, v49, v109
	v_max_i32_e32 v109, 0, v2
	v_fmac_f32_e32 v220, v50, v109
	v_max_i32_e32 v109, 0, v3
	v_fmac_f32_e32 v220, v51, v109
	v_max_i32_e32 v109, 0, v4
	v_fmac_f32_e32 v220, v52, v109
	v_mfma_f32_32x32x16_bf16 v[16:31], v[36:39], v[100:103], v[16:31]
	v_max_i32_e32 v109, 0, v5
	v_fmac_f32_e32 v220, v53, v109
	v_max_i32_e32 v109, 0, v6
	v_fmac_f32_e32 v220, v54, v109
	v_max_i32_e32 v109, 0, v7
	v_fmac_f32_e32 v220, v55, v109
	v_max_i32_e32 v109, 0, v8
	v_fmac_f32_e32 v220, v56, v109
	v_max_i32_e32 v109, 0, v9
	v_fmac_f32_e32 v220, v57, v109
	v_mfma_f32_32x32x16_bf16 v[16:31], v[40:43], v[92:95], v[16:31]
	v_max_i32_e32 v109, 0, v10
	v_fmac_f32_e32 v220, v58, v109
	v_max_i32_e32 v109, 0, v11
	v_fmac_f32_e32 v220, v59, v109
	v_max_i32_e32 v109, 0, v12
	v_fmac_f32_e32 v220, v60, v109
	v_max_i32_e32 v109, 0, v13
	v_fmac_f32_e32 v220, v61, v109
	v_mfma_f32_32x32x16_bf16 v[16:31], v[44:47], v[84:87], v[16:31]
	v_max_i32_e32 v109, 0, v14
	v_fmac_f32_e32 v220, v62, v109
	v_max_i32_e32 v109, 0, v15
	v_fmac_f32_e32 v220, v63, v109
.Lixj90:
.LBB0_1282:
.LBB0_1284:
	s_waitcnt lgkmcnt(0)
	ds_read_b128 v[100:103], v134 offset:0x4800
	ds_read_b128 v[92:95], v134 offset:0x4820
	ds_read_b128 v[84:87], v134 offset:0x4840
	ds_read_b128 v[108:111], v134 offset:0x4860
	s_cmp_gt_u32 s95, 53
	s_cselect_b64 s[66:67], -1, 0
	s_cmp_lt_u32 s95, 54
	s_cbranch_scc1 .Lixc89
	v_mfma_f32_32x32x16_bf16 v[0:15], v[32:35], v[96:99], 0
	s_not_b64 s[52:53], s[64:65]
	v_max_i32_e32 v97, 0, v16
	v_fma_f32 v221, v48, v97, 0
	v_max_i32_e32 v97, 0, v17
	v_fmac_f32_e32 v221, v49, v97
	v_max_i32_e32 v97, 0, v18
	v_fmac_f32_e32 v221, v50, v97
	v_max_i32_e32 v97, 0, v19
	v_fmac_f32_e32 v221, v51, v97
	v_max_i32_e32 v97, 0, v20
	v_fmac_f32_e32 v221, v52, v97
	v_mfma_f32_32x32x16_bf16 v[0:15], v[36:39], v[88:91], v[0:15]
	v_max_i32_e32 v97, 0, v21
	v_fmac_f32_e32 v221, v53, v97
	v_max_i32_e32 v97, 0, v22
	v_fmac_f32_e32 v221, v54, v97
	v_max_i32_e32 v97, 0, v23
	v_fmac_f32_e32 v221, v55, v97
	v_max_i32_e32 v97, 0, v24
	v_fmac_f32_e32 v221, v56, v97
	v_max_i32_e32 v97, 0, v25
	v_fmac_f32_e32 v221, v57, v97
	v_mfma_f32_32x32x16_bf16 v[0:15], v[40:43], v[80:83], v[0:15]
	v_max_i32_e32 v97, 0, v26
	v_fmac_f32_e32 v221, v58, v97
	v_max_i32_e32 v97, 0, v27
	v_fmac_f32_e32 v221, v59, v97
	v_max_i32_e32 v97, 0, v28
	v_fmac_f32_e32 v221, v60, v97
	v_max_i32_e32 v97, 0, v29
	v_fmac_f32_e32 v221, v61, v97
	v_mfma_f32_32x32x16_bf16 v[0:15], v[44:47], v[104:107], v[0:15]
	v_max_i32_e32 v97, 0, v30
	v_fmac_f32_e32 v221, v62, v97
	v_max_i32_e32 v97, 0, v31
	v_fmac_f32_e32 v221, v63, v97
.Lixj89:
.LBB0_1288:
.LBB0_1290:
	s_waitcnt lgkmcnt(0)
	ds_read_b128 v[96:99], v134 offset:0x5a00
	ds_read_b128 v[88:91], v134 offset:0x5a20
	ds_read_b128 v[80:83], v134 offset:0x5a40
	ds_read_b128 v[104:107], v134 offset:0x5a60
	s_cmp_gt_u32 s95, 55
	s_cselect_b64 s[64:65], -1, 0
	s_cmp_lt_u32 s95, 56
	s_cbranch_scc1 .Lixc88
	v_mfma_f32_32x32x16_bf16 v[16:31], v[32:35], v[100:103], 0
	s_not_b64 s[52:53], s[66:67]
	v_max_i32_e32 v101, 0, v0
	v_fma_f32 v222, v48, v101, 0
	v_max_i32_e32 v101, 0, v1
	v_fmac_f32_e32 v222, v49, v101
	v_max_i32_e32 v101, 0, v2
	v_fmac_f32_e32 v222, v50, v101
	v_max_i32_e32 v101, 0, v3
	v_fmac_f32_e32 v222, v51, v101
	v_max_i32_e32 v101, 0, v4
	v_fmac_f32_e32 v222, v52, v101
	v_mfma_f32_32x32x16_bf16 v[16:31], v[36:39], v[92:95], v[16:31]
	v_max_i32_e32 v101, 0, v5
	v_fmac_f32_e32 v222, v53, v101
	v_max_i32_e32 v101, 0, v6
	v_fmac_f32_e32 v222, v54, v101
	v_max_i32_e32 v101, 0, v7
	v_fmac_f32_e32 v222, v55, v101
	v_max_i32_e32 v101, 0, v8
	v_fmac_f32_e32 v222, v56, v101
	v_max_i32_e32 v101, 0, v9
	v_fmac_f32_e32 v222, v57, v101
	v_mfma_f32_32x32x16_bf16 v[16:31], v[40:43], v[84:87], v[16:31]
	v_max_i32_e32 v101, 0, v10
	v_fmac_f32_e32 v222, v58, v101
	v_max_i32_e32 v101, 0, v11
	v_fmac_f32_e32 v222, v59, v101
	v_max_i32_e32 v101, 0, v12
	v_fmac_f32_e32 v222, v60, v101
	v_max_i32_e32 v101, 0, v13
	v_fmac_f32_e32 v222, v61, v101
	v_mfma_f32_32x32x16_bf16 v[16:31], v[44:47], v[108:111], v[16:31]
	v_max_i32_e32 v101, 0, v14
	v_fmac_f32_e32 v222, v62, v101
	v_max_i32_e32 v101, 0, v15
	v_fmac_f32_e32 v222, v63, v101
.Lixj88:
.LBB0_1294:
.LBB0_1296:
	s_waitcnt lgkmcnt(0)
	ds_read_b128 v[100:103], v134 offset:0x6c00
	ds_read_b128 v[92:95], v134 offset:0x6c20
	ds_read_b128 v[84:87], v134 offset:0x6c40
	ds_read_b128 v[108:111], v134 offset:0x6c60
	s_cmp_gt_u32 s95, 57
	s_cselect_b64 s[66:67], -1, 0
	s_cmp_lt_u32 s95, 58
	s_cbranch_scc1 .Lixc87
	v_mfma_f32_32x32x16_bf16 v[0:15], v[32:35], v[96:99], 0
	s_not_b64 s[52:53], s[64:65]
	v_max_i32_e32 v97, 0, v16
	v_fma_f32 v223, v48, v97, 0
	v_max_i32_e32 v97, 0, v17
	v_fmac_f32_e32 v223, v49, v97
	v_max_i32_e32 v97, 0, v18
	v_fmac_f32_e32 v223, v50, v97
	v_max_i32_e32 v97, 0, v19
	v_fmac_f32_e32 v223, v51, v97
	v_max_i32_e32 v97, 0, v20
	v_fmac_f32_e32 v223, v52, v97
	v_mfma_f32_32x32x16_bf16 v[0:15], v[36:39], v[88:91], v[0:15]
	v_max_i32_e32 v97, 0, v21
	v_fmac_f32_e32 v223, v53, v97
	v_max_i32_e32 v97, 0, v22
	v_fmac_f32_e32 v223, v54, v97
	v_max_i32_e32 v97, 0, v23
	v_fmac_f32_e32 v223, v55, v97
	v_max_i32_e32 v97, 0, v24
	v_fmac_f32_e32 v223, v56, v97
	v_max_i32_e32 v97, 0, v25
	v_fmac_f32_e32 v223, v57, v97
	v_mfma_f32_32x32x16_bf16 v[0:15], v[40:43], v[80:83], v[0:15]
	v_max_i32_e32 v97, 0, v26
	v_fmac_f32_e32 v223, v58, v97
	v_max_i32_e32 v97, 0, v27
	v_fmac_f32_e32 v223, v59, v97
	v_max_i32_e32 v97, 0, v28
	v_fmac_f32_e32 v223, v60, v97
	v_max_i32_e32 v97, 0, v29
	v_fmac_f32_e32 v223, v61, v97
	v_mfma_f32_32x32x16_bf16 v[0:15], v[44:47], v[104:107], v[0:15]
	v_max_i32_e32 v97, 0, v30
	v_fmac_f32_e32 v223, v62, v97
	v_max_i32_e32 v97, 0, v31
	v_fmac_f32_e32 v223, v63, v97
.Lixj87:
.LBB0_1300:
.LBB0_1302:
	s_waitcnt lgkmcnt(0)
	ds_read_b128 v[96:99], v134 offset:0x7e00
	ds_read_b128 v[88:91], v134 offset:0x7e20
	ds_read_b128 v[80:83], v134 offset:0x7e40
	ds_read_b128 v[104:107], v134 offset:0x7e60
	s_cmp_gt_u32 s95, 59
	s_cselect_b64 s[64:65], -1, 0
	s_cmp_lt_u32 s95, 60
	s_cbranch_scc1 .Lixc86
	v_mfma_f32_32x32x16_bf16 v[16:31], v[32:35], v[100:103], 0
	s_not_b64 s[52:53], s[66:67]
	v_max_i32_e32 v101, 0, v0
	v_fma_f32 v224, v48, v101, 0
	v_max_i32_e32 v101, 0, v1
	v_fmac_f32_e32 v224, v49, v101
	v_max_i32_e32 v101, 0, v2
	v_fmac_f32_e32 v224, v50, v101
	v_max_i32_e32 v101, 0, v3
	v_fmac_f32_e32 v224, v51, v101
	v_max_i32_e32 v101, 0, v4
	v_fmac_f32_e32 v224, v52, v101
	v_mfma_f32_32x32x16_bf16 v[16:31], v[36:39], v[92:95], v[16:31]
	v_max_i32_e32 v101, 0, v5
	v_fmac_f32_e32 v224, v53, v101
	v_max_i32_e32 v101, 0, v6
	v_fmac_f32_e32 v224, v54, v101
	v_max_i32_e32 v101, 0, v7
	v_fmac_f32_e32 v224, v55, v101
	v_max_i32_e32 v101, 0, v8
	v_fmac_f32_e32 v224, v56, v101
	v_max_i32_e32 v101, 0, v9
	v_fmac_f32_e32 v224, v57, v101
	v_mfma_f32_32x32x16_bf16 v[16:31], v[40:43], v[84:87], v[16:31]
	v_max_i32_e32 v101, 0, v10
	v_fmac_f32_e32 v224, v58, v101
	v_max_i32_e32 v101, 0, v11
	v_fmac_f32_e32 v224, v59, v101
	v_max_i32_e32 v101, 0, v12
	v_fmac_f32_e32 v224, v60, v101
	v_max_i32_e32 v101, 0, v13
	v_fmac_f32_e32 v224, v61, v101
	v_mfma_f32_32x32x16_bf16 v[16:31], v[44:47], v[108:111], v[16:31]
	v_max_i32_e32 v101, 0, v14
	v_fmac_f32_e32 v224, v62, v101
	v_max_i32_e32 v101, 0, v15
	v_fmac_f32_e32 v224, v63, v101
.Lixj86:
.LBB0_1306:
.LBB0_1308:
	s_waitcnt lgkmcnt(0)
	s_cmp_lt_u32 s95, 62
	s_cbranch_scc1 .Lixc85
	v_mfma_f32_32x32x16_bf16 v[0:15], v[32:35], v[96:99], 0
	s_not_b64 s[52:53], s[64:65]
	s_nop 1
	v_max_i32_e32 v97, 0, v16
	v_fma_f32 v225, v48, v97, 0
	v_max_i32_e32 v97, 0, v17
	v_fmac_f32_e32 v225, v49, v97
	v_max_i32_e32 v97, 0, v18
	v_fmac_f32_e32 v225, v50, v97
	v_max_i32_e32 v97, 0, v19
	v_fmac_f32_e32 v225, v51, v97
	v_max_i32_e32 v97, 0, v20
	v_fmac_f32_e32 v225, v52, v97
	v_mfma_f32_32x32x16_bf16 v[0:15], v[36:39], v[88:91], v[0:15]
	v_max_i32_e32 v97, 0, v21
	v_fmac_f32_e32 v225, v53, v97
	v_max_i32_e32 v97, 0, v22
	v_fmac_f32_e32 v225, v54, v97
	v_max_i32_e32 v97, 0, v23
	v_fmac_f32_e32 v225, v55, v97
	v_max_i32_e32 v97, 0, v24
	v_fmac_f32_e32 v225, v56, v97
	v_max_i32_e32 v97, 0, v25
	v_fmac_f32_e32 v225, v57, v97
	v_mfma_f32_32x32x16_bf16 v[0:15], v[40:43], v[80:83], v[0:15]
	v_max_i32_e32 v97, 0, v26
	v_fmac_f32_e32 v225, v58, v97
	v_max_i32_e32 v97, 0, v27
	v_fmac_f32_e32 v225, v59, v97
	v_max_i32_e32 v97, 0, v28
	v_fmac_f32_e32 v225, v60, v97
	v_max_i32_e32 v97, 0, v29
	v_fmac_f32_e32 v225, v61, v97
	v_mfma_f32_32x32x16_bf16 v[0:15], v[44:47], v[104:107], v[0:15]
	v_max_i32_e32 v97, 0, v30
	v_fmac_f32_e32 v225, v62, v97
	v_max_i32_e32 v97, 0, v31
	v_fmac_f32_e32 v225, v63, v97

.Lixj84:
	s_waitcnt lgkmcnt(0)
	ds_read_b128 v[96:99], v131 offset:0x3600
	ds_read_b128 v[88:91], v131 offset:0x3620
	ds_read_b128 v[80:83], v131 offset:0x3640
	ds_read_b128 v[104:107], v131 offset:0x3660
	s_cmpk_gt_u32 s95, 0x43
	s_cselect_b64 s[64:65], -1, 0
	s_cmpk_lt_u32 s95, 0x44
	s_cbranch_scc1 .Lixc83
	v_mfma_f32_32x32x16_bf16 v[16:31], v[32:35], v[108:111], 0
	s_not_b64 s[52:53], s[66:67]
	v_max_i32_e32 v109, 0, v0
	v_fma_f32 v228, v48, v109, 0
	v_max_i32_e32 v109, 0, v1
	v_fmac_f32_e32 v228, v49, v109
	v_max_i32_e32 v109, 0, v2
	v_fmac_f32_e32 v228, v50, v109
	v_max_i32_e32 v109, 0, v3
	v_fmac_f32_e32 v228, v51, v109
	v_max_i32_e32 v109, 0, v4
	v_fmac_f32_e32 v228, v52, v109
	v_mfma_f32_32x32x16_bf16 v[16:31], v[36:39], v[100:103], v[16:31]
	v_max_i32_e32 v109, 0, v5
	v_fmac_f32_e32 v228, v53, v109
	v_max_i32_e32 v109, 0, v6
	v_fmac_f32_e32 v228, v54, v109
	v_max_i32_e32 v109, 0, v7
	v_fmac_f32_e32 v228, v55, v109
	v_max_i32_e32 v109, 0, v8
	v_fmac_f32_e32 v228, v56, v109
	v_max_i32_e32 v109, 0, v9
	v_fmac_f32_e32 v228, v57, v109
	v_mfma_f32_32x32x16_bf16 v[16:31], v[40:43], v[92:95], v[16:31]
	v_max_i32_e32 v109, 0, v10
	v_fmac_f32_e32 v228, v58, v109
	v_max_i32_e32 v109, 0, v11
	v_fmac_f32_e32 v228, v59, v109
	v_max_i32_e32 v109, 0, v12
	v_fmac_f32_e32 v228, v60, v109
	v_max_i32_e32 v109, 0, v13
	v_fmac_f32_e32 v228, v61, v109
	v_mfma_f32_32x32x16_bf16 v[16:31], v[44:47], v[84:87], v[16:31]
	v_max_i32_e32 v109, 0, v14
	v_fmac_f32_e32 v228, v62, v109
	v_max_i32_e32 v109, 0, v15
	v_fmac_f32_e32 v228, v63, v109
.Lixj83:
.LBB0_1326:
.LBB0_1328:
	s_waitcnt lgkmcnt(0)
	ds_read_b128 v[100:103], v131 offset:0x4800
	ds_read_b128 v[92:95], v131 offset:0x4820
	ds_read_b128 v[84:87], v131 offset:0x4840
	ds_read_b128 v[108:111], v131 offset:0x4860
	s_cmpk_gt_u32 s95, 0x45
	s_cselect_b64 s[66:67], -1, 0
	s_cmpk_lt_u32 s95, 0x46
	s_cbranch_scc1 .Lixc82
	v_mfma_f32_32x32x16_bf16 v[0:15], v[32:35], v[96:99], 0
	s_not_b64 s[52:53], s[64:65]
	v_max_i32_e32 v97, 0, v16
	v_fma_f32 v229, v48, v97, 0
	v_max_i32_e32 v97, 0, v17
	v_fmac_f32_e32 v229, v49, v97
	v_max_i32_e32 v97, 0, v18
	v_fmac_f32_e32 v229, v50, v97
	v_max_i32_e32 v97, 0, v19
	v_fmac_f32_e32 v229, v51, v97
	v_max_i32_e32 v97, 0, v20
	v_fmac_f32_e32 v229, v52, v97
	v_mfma_f32_32x32x16_bf16 v[0:15], v[36:39], v[88:91], v[0:15]
	v_max_i32_e32 v97, 0, v21
	v_fmac_f32_e32 v229, v53, v97
	v_max_i32_e32 v97, 0, v22
	v_fmac_f32_e32 v229, v54, v97
	v_max_i32_e32 v97, 0, v23
	v_fmac_f32_e32 v229, v55, v97
	v_max_i32_e32 v97, 0, v24
	v_fmac_f32_e32 v229, v56, v97
	v_max_i32_e32 v97, 0, v25
	v_fmac_f32_e32 v229, v57, v97
	v_mfma_f32_32x32x16_bf16 v[0:15], v[40:43], v[80:83], v[0:15]
	v_max_i32_e32 v97, 0, v26
	v_fmac_f32_e32 v229, v58, v97
	v_max_i32_e32 v97, 0, v27
	v_fmac_f32_e32 v229, v59, v97
	v_max_i32_e32 v97, 0, v28
	v_fmac_f32_e32 v229, v60, v97
	v_max_i32_e32 v97, 0, v29
	v_fmac_f32_e32 v229, v61, v97
	v_mfma_f32_32x32x16_bf16 v[0:15], v[44:47], v[104:107], v[0:15]
	v_max_i32_e32 v97, 0, v30
	v_fmac_f32_e32 v229, v62, v97
	v_max_i32_e32 v97, 0, v31
	v_fmac_f32_e32 v229, v63, v97
.Lixj82:
.LBB0_1332:
.LBB0_1334:
	s_waitcnt lgkmcnt(0)
	ds_read_b128 v[96:99], v131 offset:0x5a00
	ds_read_b128 v[88:91], v131 offset:0x5a20
	ds_read_b128 v[80:83], v131 offset:0x5a40
	ds_read_b128 v[104:107], v131 offset:0x5a60
	s_cmpk_gt_u32 s95, 0x47
	s_cselect_b64 s[64:65], -1, 0
	s_cmpk_lt_u32 s95, 0x48
	s_cbranch_scc1 .Lixc81
	v_mfma_f32_32x32x16_bf16 v[16:31], v[32:35], v[100:103], 0
	s_not_b64 s[52:53], s[66:67]
	v_max_i32_e32 v101, 0, v0
	v_fma_f32 v230, v48, v101, 0
	v_max_i32_e32 v101, 0, v1
	v_fmac_f32_e32 v230, v49, v101
	v_max_i32_e32 v101, 0, v2
	v_fmac_f32_e32 v230, v50, v101
	v_max_i32_e32 v101, 0, v3
	v_fmac_f32_e32 v230, v51, v101
	v_max_i32_e32 v101, 0, v4
	v_fmac_f32_e32 v230, v52, v101
	v_mfma_f32_32x32x16_bf16 v[16:31], v[36:39], v[92:95], v[16:31]
	v_max_i32_e32 v101, 0, v5
	v_fmac_f32_e32 v230, v53, v101
	v_max_i32_e32 v101, 0, v6
	v_fmac_f32_e32 v230, v54, v101
	v_max_i32_e32 v101, 0, v7
	v_fmac_f32_e32 v230, v55, v101
	v_max_i32_e32 v101, 0, v8
	v_fmac_f32_e32 v230, v56, v101
	v_max_i32_e32 v101, 0, v9
	v_fmac_f32_e32 v230, v57, v101
	v_mfma_f32_32x32x16_bf16 v[16:31], v[40:43], v[84:87], v[16:31]
	v_max_i32_e32 v101, 0, v10
	v_fmac_f32_e32 v230, v58, v101
	v_max_i32_e32 v101, 0, v11
	v_fmac_f32_e32 v230, v59, v101
	v_max_i32_e32 v101, 0, v12
	v_fmac_f32_e32 v230, v60, v101
	v_max_i32_e32 v101, 0, v13
	v_fmac_f32_e32 v230, v61, v101
	v_mfma_f32_32x32x16_bf16 v[16:31], v[44:47], v[108:111], v[16:31]
	v_max_i32_e32 v101, 0, v14
	v_fmac_f32_e32 v230, v62, v101
	v_max_i32_e32 v101, 0, v15
	v_fmac_f32_e32 v230, v63, v101
.Lixj81:
.LBB0_1338:
.LBB0_1340:
	s_waitcnt lgkmcnt(0)
	ds_read_b128 v[100:103], v131 offset:0x6c00
	ds_read_b128 v[92:95], v131 offset:0x6c20
	ds_read_b128 v[84:87], v131 offset:0x6c40
	ds_read_b128 v[108:111], v131 offset:0x6c60
	s_cmpk_gt_u32 s95, 0x49
	s_cselect_b64 s[66:67], -1, 0
	s_cmpk_lt_u32 s95, 0x4a
	s_cbranch_scc1 .Lixc80
	v_mfma_f32_32x32x16_bf16 v[0:15], v[32:35], v[96:99], 0
	s_not_b64 s[52:53], s[64:65]
	v_max_i32_e32 v97, 0, v16
	v_fma_f32 v231, v48, v97, 0
	v_max_i32_e32 v97, 0, v17
	v_fmac_f32_e32 v231, v49, v97
	v_max_i32_e32 v97, 0, v18
	v_fmac_f32_e32 v231, v50, v97
	v_max_i32_e32 v97, 0, v19
	v_fmac_f32_e32 v231, v51, v97
	v_max_i32_e32 v97, 0, v20
	v_fmac_f32_e32 v231, v52, v97
	v_mfma_f32_32x32x16_bf16 v[0:15], v[36:39], v[88:91], v[0:15]
	v_max_i32_e32 v97, 0, v21
	v_fmac_f32_e32 v231, v53, v97
	v_max_i32_e32 v97, 0, v22
	v_fmac_f32_e32 v231, v54, v97
	v_max_i32_e32 v97, 0, v23
	v_fmac_f32_e32 v231, v55, v97
	v_max_i32_e32 v97, 0, v24
	v_fmac_f32_e32 v231, v56, v97
	v_max_i32_e32 v97, 0, v25
	v_fmac_f32_e32 v231, v57, v97
	v_mfma_f32_32x32x16_bf16 v[0:15], v[40:43], v[80:83], v[0:15]
	v_max_i32_e32 v97, 0, v26
	v_fmac_f32_e32 v231, v58, v97
	v_max_i32_e32 v97, 0, v27
	v_fmac_f32_e32 v231, v59, v97
	v_max_i32_e32 v97, 0, v28
	v_fmac_f32_e32 v231, v60, v97
	v_max_i32_e32 v97, 0, v29
	v_fmac_f32_e32 v231, v61, v97
	v_mfma_f32_32x32x16_bf16 v[0:15], v[44:47], v[104:107], v[0:15]
	v_max_i32_e32 v97, 0, v30
	v_fmac_f32_e32 v231, v62, v97
	v_max_i32_e32 v97, 0, v31
	v_fmac_f32_e32 v231, v63, v97
.Lixj80:
.LBB0_1344:
.LBB0_1346:
	s_waitcnt lgkmcnt(0)
	ds_read_b128 v[96:99], v131 offset:0x7e00
	ds_read_b128 v[88:91], v131 offset:0x7e20
	ds_read_b128 v[80:83], v131 offset:0x7e40
	ds_read_b128 v[104:107], v131 offset:0x7e60
	s_cmpk_gt_u32 s95, 0x4b
	s_cselect_b64 s[64:65], -1, 0
	s_cmpk_lt_u32 s95, 0x4c
	s_cbranch_scc1 .Lixc79
	v_mfma_f32_32x32x16_bf16 v[16:31], v[32:35], v[100:103], 0
	s_not_b64 s[52:53], s[66:67]
	v_max_i32_e32 v101, 0, v0
	v_fma_f32 v232, v48, v101, 0
	v_max_i32_e32 v101, 0, v1
	v_fmac_f32_e32 v232, v49, v101
	v_max_i32_e32 v101, 0, v2
	v_fmac_f32_e32 v232, v50, v101
	v_max_i32_e32 v101, 0, v3
	v_fmac_f32_e32 v232, v51, v101
	v_max_i32_e32 v101, 0, v4
	v_fmac_f32_e32 v232, v52, v101
	v_mfma_f32_32x32x16_bf16 v[16:31], v[36:39], v[92:95], v[16:31]
	v_max_i32_e32 v101, 0, v5
	v_fmac_f32_e32 v232, v53, v101
	v_max_i32_e32 v101, 0, v6
	v_fmac_f32_e32 v232, v54, v101
	v_max_i32_e32 v101, 0, v7
	v_fmac_f32_e32 v232, v55, v101
	v_max_i32_e32 v101, 0, v8
	v_fmac_f32_e32 v232, v56, v101
	v_max_i32_e32 v101, 0, v9
	v_fmac_f32_e32 v232, v57, v101
	v_mfma_f32_32x32x16_bf16 v[16:31], v[40:43], v[84:87], v[16:31]
	v_max_i32_e32 v101, 0, v10
	v_fmac_f32_e32 v232, v58, v101
	v_max_i32_e32 v101, 0, v11
	v_fmac_f32_e32 v232, v59, v101
	v_max_i32_e32 v101, 0, v12
	v_fmac_f32_e32 v232, v60, v101
	v_max_i32_e32 v101, 0, v13
	v_fmac_f32_e32 v232, v61, v101
	v_mfma_f32_32x32x16_bf16 v[16:31], v[44:47], v[108:111], v[16:31]
	v_max_i32_e32 v101, 0, v14
	v_fmac_f32_e32 v232, v62, v101
	v_max_i32_e32 v101, 0, v15
	v_fmac_f32_e32 v232, v63, v101
.Lixj79:
.LBB0_1350:
.LBB0_1352:
	s_waitcnt lgkmcnt(0)
	s_cmpk_lt_u32 s95, 0x4e
	s_cbranch_scc1 .Lixc78
	v_mfma_f32_32x32x16_bf16 v[0:15], v[32:35], v[96:99], 0
	s_not_b64 s[52:53], s[64:65]
	s_nop 1
	v_max_i32_e32 v97, 0, v16
	v_fma_f32 v233, v48, v97, 0
	v_max_i32_e32 v97, 0, v17
	v_fmac_f32_e32 v233, v49, v97
	v_max_i32_e32 v97, 0, v18
	v_fmac_f32_e32 v233, v50, v97
	v_max_i32_e32 v97, 0, v19
	v_fmac_f32_e32 v233, v51, v97
	v_max_i32_e32 v97, 0, v20
	v_fmac_f32_e32 v233, v52, v97
	v_mfma_f32_32x32x16_bf16 v[0:15], v[36:39], v[88:91], v[0:15]
	v_max_i32_e32 v97, 0, v21
	v_fmac_f32_e32 v233, v53, v97
	v_max_i32_e32 v97, 0, v22
	v_fmac_f32_e32 v233, v54, v97
	v_max_i32_e32 v97, 0, v23
	v_fmac_f32_e32 v233, v55, v97
	v_max_i32_e32 v97, 0, v24
	v_fmac_f32_e32 v233, v56, v97
	v_max_i32_e32 v97, 0, v25
	v_fmac_f32_e32 v233, v57, v97
	v_mfma_f32_32x32x16_bf16 v[0:15], v[40:43], v[80:83], v[0:15]
	v_max_i32_e32 v97, 0, v26
	v_fmac_f32_e32 v233, v58, v97
	v_max_i32_e32 v97, 0, v27
	v_fmac_f32_e32 v233, v59, v97
	v_max_i32_e32 v97, 0, v28
	v_fmac_f32_e32 v233, v60, v97
	v_max_i32_e32 v97, 0, v29
	v_fmac_f32_e32 v233, v61, v97
	v_mfma_f32_32x32x16_bf16 v[0:15], v[44:47], v[104:107], v[0:15]
	v_max_i32_e32 v97, 0, v30
	v_fmac_f32_e32 v233, v62, v97
	v_max_i32_e32 v97, 0, v31
	v_fmac_f32_e32 v233, v63, v97

.Lixj77:
	s_waitcnt lgkmcnt(0)
	ds_read_b128 v[96:99], v134 offset:0x3600
	ds_read_b128 v[88:91], v134 offset:0x3620
	ds_read_b128 v[80:83], v134 offset:0x3640
	ds_read_b128 v[104:107], v134 offset:0x3660
	s_cmpk_gt_u32 s95, 0x53
	s_cselect_b64 s[64:65], -1, 0
	s_cmpk_lt_u32 s95, 0x54
	s_cbranch_scc1 .Lixc76
	v_mfma_f32_32x32x16_bf16 v[16:31], v[32:35], v[108:111], 0
	s_not_b64 s[52:53], s[66:67]
	v_max_i32_e32 v109, 0, v0
	v_fma_f32 v236, v48, v109, 0
	v_max_i32_e32 v109, 0, v1
	v_fmac_f32_e32 v236, v49, v109
	v_max_i32_e32 v109, 0, v2
	v_fmac_f32_e32 v236, v50, v109
	v_max_i32_e32 v109, 0, v3
	v_fmac_f32_e32 v236, v51, v109
	v_max_i32_e32 v109, 0, v4
	v_fmac_f32_e32 v236, v52, v109
	v_mfma_f32_32x32x16_bf16 v[16:31], v[36:39], v[100:103], v[16:31]
	v_max_i32_e32 v109, 0, v5
	v_fmac_f32_e32 v236, v53, v109
	v_max_i32_e32 v109, 0, v6
	v_fmac_f32_e32 v236, v54, v109
	v_max_i32_e32 v109, 0, v7
	v_fmac_f32_e32 v236, v55, v109
	v_max_i32_e32 v109, 0, v8
	v_fmac_f32_e32 v236, v56, v109
	v_max_i32_e32 v109, 0, v9
	v_fmac_f32_e32 v236, v57, v109
	v_mfma_f32_32x32x16_bf16 v[16:31], v[40:43], v[92:95], v[16:31]
	v_max_i32_e32 v109, 0, v10
	v_fmac_f32_e32 v236, v58, v109
	v_max_i32_e32 v109, 0, v11
	v_fmac_f32_e32 v236, v59, v109
	v_max_i32_e32 v109, 0, v12
	v_fmac_f32_e32 v236, v60, v109
	v_max_i32_e32 v109, 0, v13
	v_fmac_f32_e32 v236, v61, v109
	v_mfma_f32_32x32x16_bf16 v[16:31], v[44:47], v[84:87], v[16:31]
	v_max_i32_e32 v109, 0, v14
	v_fmac_f32_e32 v236, v62, v109
	v_max_i32_e32 v109, 0, v15
	v_fmac_f32_e32 v236, v63, v109
.Lixj76:
.LBB0_1370:
.LBB0_1372:
	s_waitcnt lgkmcnt(0)
	ds_read_b128 v[100:103], v134 offset:0x4800
	ds_read_b128 v[92:95], v134 offset:0x4820
	ds_read_b128 v[84:87], v134 offset:0x4840
	ds_read_b128 v[108:111], v134 offset:0x4860
	s_cmpk_gt_u32 s95, 0x55
	s_cselect_b64 s[66:67], -1, 0
	s_cmpk_lt_u32 s95, 0x56
	s_cbranch_scc1 .Lixc75
	v_mfma_f32_32x32x16_bf16 v[0:15], v[32:35], v[96:99], 0
	s_not_b64 s[52:53], s[64:65]
	v_max_i32_e32 v97, 0, v16
	v_fma_f32 v237, v48, v97, 0
	v_max_i32_e32 v97, 0, v17
	v_fmac_f32_e32 v237, v49, v97
	v_max_i32_e32 v97, 0, v18
	v_fmac_f32_e32 v237, v50, v97
	v_max_i32_e32 v97, 0, v19
	v_fmac_f32_e32 v237, v51, v97
	v_max_i32_e32 v97, 0, v20
	v_fmac_f32_e32 v237, v52, v97
	v_mfma_f32_32x32x16_bf16 v[0:15], v[36:39], v[88:91], v[0:15]
	v_max_i32_e32 v97, 0, v21
	v_fmac_f32_e32 v237, v53, v97
	v_max_i32_e32 v97, 0, v22
	v_fmac_f32_e32 v237, v54, v97
	v_max_i32_e32 v97, 0, v23
	v_fmac_f32_e32 v237, v55, v97
	v_max_i32_e32 v97, 0, v24
	v_fmac_f32_e32 v237, v56, v97
	v_max_i32_e32 v97, 0, v25
	v_fmac_f32_e32 v237, v57, v97
	v_mfma_f32_32x32x16_bf16 v[0:15], v[40:43], v[80:83], v[0:15]
	v_max_i32_e32 v97, 0, v26
	v_fmac_f32_e32 v237, v58, v97
	v_max_i32_e32 v97, 0, v27
	v_fmac_f32_e32 v237, v59, v97
	v_max_i32_e32 v97, 0, v28
	v_fmac_f32_e32 v237, v60, v97
	v_max_i32_e32 v97, 0, v29
	v_fmac_f32_e32 v237, v61, v97
	v_mfma_f32_32x32x16_bf16 v[0:15], v[44:47], v[104:107], v[0:15]
	v_max_i32_e32 v97, 0, v30
	v_fmac_f32_e32 v237, v62, v97
	v_max_i32_e32 v97, 0, v31
	v_fmac_f32_e32 v237, v63, v97
.Lixj75:
.LBB0_1376:
.LBB0_1378:
	s_waitcnt lgkmcnt(0)
	ds_read_b128 v[96:99], v134 offset:0x5a00
	ds_read_b128 v[88:91], v134 offset:0x5a20
	ds_read_b128 v[80:83], v134 offset:0x5a40
	ds_read_b128 v[104:107], v134 offset:0x5a60
	s_cmpk_gt_u32 s95, 0x57
	s_cselect_b64 s[64:65], -1, 0
	s_cmpk_lt_u32 s95, 0x58
	s_cbranch_scc1 .Lixc74
	v_mfma_f32_32x32x16_bf16 v[16:31], v[32:35], v[100:103], 0
	s_not_b64 s[52:53], s[66:67]
	v_max_i32_e32 v101, 0, v0
	v_fma_f32 v238, v48, v101, 0
	v_max_i32_e32 v101, 0, v1
	v_fmac_f32_e32 v238, v49, v101
	v_max_i32_e32 v101, 0, v2
	v_fmac_f32_e32 v238, v50, v101
	v_max_i32_e32 v101, 0, v3
	v_fmac_f32_e32 v238, v51, v101
	v_max_i32_e32 v101, 0, v4
	v_fmac_f32_e32 v238, v52, v101
	v_mfma_f32_32x32x16_bf16 v[16:31], v[36:39], v[92:95], v[16:31]
	v_max_i32_e32 v101, 0, v5
	v_fmac_f32_e32 v238, v53, v101
	v_max_i32_e32 v101, 0, v6
	v_fmac_f32_e32 v238, v54, v101
	v_max_i32_e32 v101, 0, v7
	v_fmac_f32_e32 v238, v55, v101
	v_max_i32_e32 v101, 0, v8
	v_fmac_f32_e32 v238, v56, v101
	v_max_i32_e32 v101, 0, v9
	v_fmac_f32_e32 v238, v57, v101
	v_mfma_f32_32x32x16_bf16 v[16:31], v[40:43], v[84:87], v[16:31]
	v_max_i32_e32 v101, 0, v10
	v_fmac_f32_e32 v238, v58, v101
	v_max_i32_e32 v101, 0, v11
	v_fmac_f32_e32 v238, v59, v101
	v_max_i32_e32 v101, 0, v12
	v_fmac_f32_e32 v238, v60, v101
	v_max_i32_e32 v101, 0, v13
	v_fmac_f32_e32 v238, v61, v101
	v_mfma_f32_32x32x16_bf16 v[16:31], v[44:47], v[108:111], v[16:31]
	v_max_i32_e32 v101, 0, v14
	v_fmac_f32_e32 v238, v62, v101
	v_max_i32_e32 v101, 0, v15
	v_fmac_f32_e32 v238, v63, v101
.Lixj74:
.LBB0_1382:
.LBB0_1384:
	s_waitcnt lgkmcnt(0)
	ds_read_b128 v[100:103], v134 offset:0x6c00
	ds_read_b128 v[92:95], v134 offset:0x6c20
	ds_read_b128 v[84:87], v134 offset:0x6c40
	ds_read_b128 v[108:111], v134 offset:0x6c60
	s_cmpk_gt_u32 s95, 0x59
	s_cselect_b64 s[66:67], -1, 0
	s_cmpk_lt_u32 s95, 0x5a
	s_cbranch_scc1 .Lixc73
	v_mfma_f32_32x32x16_bf16 v[0:15], v[32:35], v[96:99], 0
	s_not_b64 s[52:53], s[64:65]
	v_max_i32_e32 v97, 0, v16
	v_fma_f32 v239, v48, v97, 0
	v_max_i32_e32 v97, 0, v17
	v_fmac_f32_e32 v239, v49, v97
	v_max_i32_e32 v97, 0, v18
	v_fmac_f32_e32 v239, v50, v97
	v_max_i32_e32 v97, 0, v19
	v_fmac_f32_e32 v239, v51, v97
	v_max_i32_e32 v97, 0, v20
	v_fmac_f32_e32 v239, v52, v97
	v_mfma_f32_32x32x16_bf16 v[0:15], v[36:39], v[88:91], v[0:15]
	v_max_i32_e32 v97, 0, v21
	v_fmac_f32_e32 v239, v53, v97
	v_max_i32_e32 v97, 0, v22
	v_fmac_f32_e32 v239, v54, v97
	v_max_i32_e32 v97, 0, v23
	v_fmac_f32_e32 v239, v55, v97
	v_max_i32_e32 v97, 0, v24
	v_fmac_f32_e32 v239, v56, v97
	v_max_i32_e32 v97, 0, v25
	v_fmac_f32_e32 v239, v57, v97
	v_mfma_f32_32x32x16_bf16 v[0:15], v[40:43], v[80:83], v[0:15]
	v_max_i32_e32 v97, 0, v26
	v_fmac_f32_e32 v239, v58, v97
	v_max_i32_e32 v97, 0, v27
	v_fmac_f32_e32 v239, v59, v97
	v_max_i32_e32 v97, 0, v28
	v_fmac_f32_e32 v239, v60, v97
	v_max_i32_e32 v97, 0, v29
	v_fmac_f32_e32 v239, v61, v97
	v_mfma_f32_32x32x16_bf16 v[0:15], v[44:47], v[104:107], v[0:15]
	v_max_i32_e32 v97, 0, v30
	v_fmac_f32_e32 v239, v62, v97
	v_max_i32_e32 v97, 0, v31
	v_fmac_f32_e32 v239, v63, v97
.Lixj73:
.LBB0_1388:
.LBB0_1390:
	s_waitcnt lgkmcnt(0)
	ds_read_b128 v[96:99], v134 offset:0x7e00
	ds_read_b128 v[88:91], v134 offset:0x7e20
	ds_read_b128 v[80:83], v134 offset:0x7e40
	ds_read_b128 v[104:107], v134 offset:0x7e60
	s_cmpk_gt_u32 s95, 0x5b
	s_cselect_b64 s[64:65], -1, 0
	s_cmpk_lt_u32 s95, 0x5c
	s_cbranch_scc1 .Lixc72
	v_mfma_f32_32x32x16_bf16 v[16:31], v[32:35], v[100:103], 0
	v_cndmask_b32_e64 v101, 0, 1, s[66:67]
	v_cmp_ne_u32_e64 s[52:53], 1, v101
	s_andn2_b64 vcc, exec, s[66:67]
	v_max_i32_e32 v101, 0, v0
	v_fma_f32 v102, v48, v101, 0
	v_max_i32_e32 v101, 0, v1
	v_fmac_f32_e32 v102, v49, v101
	v_max_i32_e32 v101, 0, v2
	v_fmac_f32_e32 v102, v50, v101
	v_max_i32_e32 v101, 0, v3
	v_fmac_f32_e32 v102, v51, v101
	v_max_i32_e32 v101, 0, v4
	v_fmac_f32_e32 v102, v52, v101
	v_mfma_f32_32x32x16_bf16 v[16:31], v[36:39], v[92:95], v[16:31]
	v_max_i32_e32 v101, 0, v5
	v_fmac_f32_e32 v102, v53, v101
	v_max_i32_e32 v101, 0, v6
	v_fmac_f32_e32 v102, v54, v101
	v_max_i32_e32 v101, 0, v7
	v_fmac_f32_e32 v102, v55, v101
	v_max_i32_e32 v101, 0, v8
	v_fmac_f32_e32 v102, v56, v101
	v_max_i32_e32 v101, 0, v9
	v_fmac_f32_e32 v102, v57, v101
	v_mfma_f32_32x32x16_bf16 v[16:31], v[40:43], v[84:87], v[16:31]
	v_max_i32_e32 v101, 0, v10
	v_fmac_f32_e32 v102, v58, v101
	v_max_i32_e32 v101, 0, v11
	v_fmac_f32_e32 v102, v59, v101
	v_max_i32_e32 v101, 0, v12
	v_fmac_f32_e32 v102, v60, v101
	v_max_i32_e32 v101, 0, v13
	v_fmac_f32_e32 v102, v61, v101
	v_mfma_f32_32x32x16_bf16 v[16:31], v[44:47], v[108:111], v[16:31]
	v_max_i32_e32 v101, 0, v14
	s_cmp_eq_u32 s58, 46
	v_fmac_f32_e32 v102, v62, v101
	v_max_i32_e32 v101, 0, v15
	s_cselect_b64 s[66:67], -1, 0
	v_cmp_gt_i32_e32 vcc, v172, v203
	v_fmac_f32_e32 v102, v63, v101
	s_and_b64 vcc, s[66:67], vcc
	v_cndmask_b32_e32 v240, v102, v197, vcc
.Lixj72:
.LBB0_1394:
.LBB0_1396:
	s_waitcnt lgkmcnt(0)
	s_cmpk_lt_u32 s95, 0x5e
	s_cbranch_scc1 .Lixc71
	v_mfma_f32_32x32x16_bf16 v[0:15], v[32:35], v[96:99], 0
	s_not_b64 s[52:53], s[64:65]
	v_max_i32_e32 v97, 0, v16
	v_fma_f32 v241, v48, v97, 0
	v_max_i32_e32 v97, 0, v17
	v_fmac_f32_e32 v241, v49, v97
	v_max_i32_e32 v97, 0, v18
	v_fmac_f32_e32 v241, v50, v97
	v_max_i32_e32 v97, 0, v19
	v_fmac_f32_e32 v241, v51, v97
	v_max_i32_e32 v97, 0, v20
	v_fmac_f32_e32 v241, v52, v97
	v_mfma_f32_32x32x16_bf16 v[0:15], v[36:39], v[88:91], v[0:15]
	v_max_i32_e32 v97, 0, v21
	v_fmac_f32_e32 v241, v53, v97
	v_max_i32_e32 v97, 0, v22
	v_fmac_f32_e32 v241, v54, v97
	v_max_i32_e32 v97, 0, v23
	v_fmac_f32_e32 v241, v55, v97
	v_max_i32_e32 v97, 0, v24
	v_fmac_f32_e32 v241, v56, v97
	v_max_i32_e32 v97, 0, v25
	v_fmac_f32_e32 v241, v57, v97
	v_mfma_f32_32x32x16_bf16 v[0:15], v[40:43], v[80:83], v[0:15]
	v_max_i32_e32 v97, 0, v26
	v_fmac_f32_e32 v241, v58, v97
	v_max_i32_e32 v97, 0, v27
	v_fmac_f32_e32 v241, v59, v97
	v_max_i32_e32 v97, 0, v28
	v_fmac_f32_e32 v241, v60, v97
	v_max_i32_e32 v97, 0, v29
	v_fmac_f32_e32 v241, v61, v97
	v_mfma_f32_32x32x16_bf16 v[0:15], v[44:47], v[104:107], v[0:15]
	v_max_i32_e32 v97, 0, v30
	v_fmac_f32_e32 v241, v62, v97
	v_max_i32_e32 v97, 0, v31
	v_fmac_f32_e32 v241, v63, v97

.Lixj70:
	s_waitcnt lgkmcnt(0)
	ds_read_b128 v[96:99], v131 offset:0x3600
	ds_read_b128 v[88:91], v131 offset:0x3620
	ds_read_b128 v[80:83], v131 offset:0x3640
	ds_read_b128 v[104:107], v131 offset:0x3660
	s_cmpk_gt_u32 s95, 0x63
	s_cselect_b64 s[60:61], -1, 0
	s_cmpk_lt_u32 s95, 0x64
	s_cbranch_scc1 .Lixc69
	v_mfma_f32_32x32x16_bf16 v[16:31], v[32:35], v[108:111], 0
	s_not_b64 s[52:53], s[64:65]
	v_max_i32_e32 v109, 0, v0
	v_fma_f32 v244, v48, v109, 0
	v_max_i32_e32 v109, 0, v1
	v_fmac_f32_e32 v244, v49, v109
	v_max_i32_e32 v109, 0, v2
	v_fmac_f32_e32 v244, v50, v109
	v_max_i32_e32 v109, 0, v3
	v_fmac_f32_e32 v244, v51, v109
	v_max_i32_e32 v109, 0, v4
	v_fmac_f32_e32 v244, v52, v109
	v_mfma_f32_32x32x16_bf16 v[16:31], v[36:39], v[100:103], v[16:31]
	v_max_i32_e32 v109, 0, v5
	v_fmac_f32_e32 v244, v53, v109
	v_max_i32_e32 v109, 0, v6
	v_fmac_f32_e32 v244, v54, v109
	v_max_i32_e32 v109, 0, v7
	v_fmac_f32_e32 v244, v55, v109
	v_max_i32_e32 v109, 0, v8
	v_fmac_f32_e32 v244, v56, v109
	v_max_i32_e32 v109, 0, v9
	v_fmac_f32_e32 v244, v57, v109
	v_mfma_f32_32x32x16_bf16 v[16:31], v[40:43], v[92:95], v[16:31]
	v_max_i32_e32 v109, 0, v10
	v_fmac_f32_e32 v244, v58, v109
	v_max_i32_e32 v109, 0, v11
	v_fmac_f32_e32 v244, v59, v109
	v_max_i32_e32 v109, 0, v12
	v_fmac_f32_e32 v244, v60, v109
	v_max_i32_e32 v109, 0, v13
	v_fmac_f32_e32 v244, v61, v109
	v_mfma_f32_32x32x16_bf16 v[16:31], v[44:47], v[84:87], v[16:31]
	v_max_i32_e32 v109, 0, v14
	v_fmac_f32_e32 v244, v62, v109
	v_max_i32_e32 v109, 0, v15
	v_fmac_f32_e32 v244, v63, v109
.Lixj69:
.LBB0_1414:
.LBB0_1416:
	s_waitcnt lgkmcnt(0)
	ds_read_b128 v[100:103], v131 offset:0x4800
	ds_read_b128 v[92:95], v131 offset:0x4820
	ds_read_b128 v[84:87], v131 offset:0x4840
	ds_read_b128 v[108:111], v131 offset:0x4860
	s_cmpk_gt_u32 s95, 0x65
	s_cselect_b64 s[64:65], -1, 0
	s_cmpk_lt_u32 s95, 0x66
	s_cbranch_scc1 .Lixc68
	v_mfma_f32_32x32x16_bf16 v[0:15], v[32:35], v[96:99], 0
	s_not_b64 s[52:53], s[60:61]
	v_max_i32_e32 v97, 0, v16
	v_fma_f32 v245, v48, v97, 0
	v_max_i32_e32 v97, 0, v17
	v_fmac_f32_e32 v245, v49, v97
	v_max_i32_e32 v97, 0, v18
	v_fmac_f32_e32 v245, v50, v97
	v_max_i32_e32 v97, 0, v19
	v_fmac_f32_e32 v245, v51, v97
	v_max_i32_e32 v97, 0, v20
	v_fmac_f32_e32 v245, v52, v97
	v_mfma_f32_32x32x16_bf16 v[0:15], v[36:39], v[88:91], v[0:15]
	v_max_i32_e32 v97, 0, v21
	v_fmac_f32_e32 v245, v53, v97
	v_max_i32_e32 v97, 0, v22
	v_fmac_f32_e32 v245, v54, v97
	v_max_i32_e32 v97, 0, v23
	v_fmac_f32_e32 v245, v55, v97
	v_max_i32_e32 v97, 0, v24
	v_fmac_f32_e32 v245, v56, v97
	v_max_i32_e32 v97, 0, v25
	v_fmac_f32_e32 v245, v57, v97
	v_mfma_f32_32x32x16_bf16 v[0:15], v[40:43], v[80:83], v[0:15]
	v_max_i32_e32 v97, 0, v26
	v_fmac_f32_e32 v245, v58, v97
	v_max_i32_e32 v97, 0, v27
	v_fmac_f32_e32 v245, v59, v97
	v_max_i32_e32 v97, 0, v28
	v_fmac_f32_e32 v245, v60, v97
	v_max_i32_e32 v97, 0, v29
	v_fmac_f32_e32 v245, v61, v97
	v_mfma_f32_32x32x16_bf16 v[0:15], v[44:47], v[104:107], v[0:15]
	v_max_i32_e32 v97, 0, v30
	v_fmac_f32_e32 v245, v62, v97
	v_max_i32_e32 v97, 0, v31
	v_fmac_f32_e32 v245, v63, v97
.Lixj68:
.LBB0_1420:
.LBB0_1422:
	s_waitcnt lgkmcnt(0)
	ds_read_b128 v[96:99], v131 offset:0x5a00
	ds_read_b128 v[88:91], v131 offset:0x5a20
	ds_read_b128 v[80:83], v131 offset:0x5a40
	ds_read_b128 v[104:107], v131 offset:0x5a60
	s_cmpk_gt_u32 s95, 0x67
	s_cselect_b64 s[60:61], -1, 0
	s_cmpk_lt_u32 s95, 0x68
	s_cbranch_scc1 .Lixc67
	v_mfma_f32_32x32x16_bf16 v[16:31], v[32:35], v[100:103], 0
	s_not_b64 s[52:53], s[64:65]
	v_max_i32_e32 v101, 0, v0
	v_fma_f32 v246, v48, v101, 0
	v_max_i32_e32 v101, 0, v1
	v_fmac_f32_e32 v246, v49, v101
	v_max_i32_e32 v101, 0, v2
	v_fmac_f32_e32 v246, v50, v101
	v_max_i32_e32 v101, 0, v3
	v_fmac_f32_e32 v246, v51, v101
	v_max_i32_e32 v101, 0, v4
	v_fmac_f32_e32 v246, v52, v101
	v_mfma_f32_32x32x16_bf16 v[16:31], v[36:39], v[92:95], v[16:31]
	v_max_i32_e32 v101, 0, v5
	v_fmac_f32_e32 v246, v53, v101
	v_max_i32_e32 v101, 0, v6
	v_fmac_f32_e32 v246, v54, v101
	v_max_i32_e32 v101, 0, v7
	v_fmac_f32_e32 v246, v55, v101
	v_max_i32_e32 v101, 0, v8
	v_fmac_f32_e32 v246, v56, v101
	v_max_i32_e32 v101, 0, v9
	v_fmac_f32_e32 v246, v57, v101
	v_mfma_f32_32x32x16_bf16 v[16:31], v[40:43], v[84:87], v[16:31]
	v_max_i32_e32 v101, 0, v10
	v_fmac_f32_e32 v246, v58, v101
	v_max_i32_e32 v101, 0, v11
	v_fmac_f32_e32 v246, v59, v101
	v_max_i32_e32 v101, 0, v12
	v_fmac_f32_e32 v246, v60, v101
	v_max_i32_e32 v101, 0, v13
	v_fmac_f32_e32 v246, v61, v101
	v_mfma_f32_32x32x16_bf16 v[16:31], v[44:47], v[108:111], v[16:31]
	v_max_i32_e32 v101, 0, v14
	v_fmac_f32_e32 v246, v62, v101
	v_max_i32_e32 v101, 0, v15
	v_fmac_f32_e32 v246, v63, v101
.Lixj67:
.LBB0_1426:
.LBB0_1428:
	s_waitcnt lgkmcnt(0)
	ds_read_b128 v[100:103], v131 offset:0x6c00
	ds_read_b128 v[92:95], v131 offset:0x6c20
	ds_read_b128 v[84:87], v131 offset:0x6c40
	ds_read_b128 v[108:111], v131 offset:0x6c60
	s_cmpk_gt_u32 s95, 0x69
	s_cselect_b64 s[64:65], -1, 0
	s_cmpk_lt_u32 s95, 0x6a
	s_cbranch_scc1 .Lixc66
	v_mfma_f32_32x32x16_bf16 v[0:15], v[32:35], v[96:99], 0
	s_not_b64 s[52:53], s[60:61]
	v_max_i32_e32 v97, 0, v16
	v_fma_f32 v247, v48, v97, 0
	v_max_i32_e32 v97, 0, v17
	v_fmac_f32_e32 v247, v49, v97
	v_max_i32_e32 v97, 0, v18
	v_fmac_f32_e32 v247, v50, v97
	v_max_i32_e32 v97, 0, v19
	v_fmac_f32_e32 v247, v51, v97
	v_max_i32_e32 v97, 0, v20
	v_fmac_f32_e32 v247, v52, v97
	v_mfma_f32_32x32x16_bf16 v[0:15], v[36:39], v[88:91], v[0:15]
	v_max_i32_e32 v97, 0, v21
	v_fmac_f32_e32 v247, v53, v97
	v_max_i32_e32 v97, 0, v22
	v_fmac_f32_e32 v247, v54, v97
	v_max_i32_e32 v97, 0, v23
	v_fmac_f32_e32 v247, v55, v97
	v_max_i32_e32 v97, 0, v24
	v_fmac_f32_e32 v247, v56, v97
	v_max_i32_e32 v97, 0, v25
	v_fmac_f32_e32 v247, v57, v97
	v_mfma_f32_32x32x16_bf16 v[0:15], v[40:43], v[80:83], v[0:15]
	v_max_i32_e32 v97, 0, v26
	v_fmac_f32_e32 v247, v58, v97
	v_max_i32_e32 v97, 0, v27
	v_fmac_f32_e32 v247, v59, v97
	v_max_i32_e32 v97, 0, v28
	v_fmac_f32_e32 v247, v60, v97
	v_max_i32_e32 v97, 0, v29
	v_fmac_f32_e32 v247, v61, v97
	v_mfma_f32_32x32x16_bf16 v[0:15], v[44:47], v[104:107], v[0:15]
	v_max_i32_e32 v97, 0, v30
	v_fmac_f32_e32 v247, v62, v97
	v_max_i32_e32 v97, 0, v31
	v_fmac_f32_e32 v247, v63, v97
.Lixj66:
.LBB0_1432:
.LBB0_1434:
	s_waitcnt lgkmcnt(0)
	ds_read_b128 v[96:99], v131 offset:0x7e00
	ds_read_b128 v[88:91], v131 offset:0x7e20
	ds_read_b128 v[80:83], v131 offset:0x7e40
	ds_read_b128 v[104:107], v131 offset:0x7e60
	s_cmpk_gt_u32 s95, 0x6b
	s_cselect_b64 s[60:61], -1, 0
	s_cmpk_lt_u32 s95, 0x6c
	s_cbranch_scc1 .Lixc65
	v_mfma_f32_32x32x16_bf16 v[16:31], v[32:35], v[100:103], 0
	v_cndmask_b32_e64 v101, 0, 1, s[64:65]
	v_cmp_ne_u32_e64 s[52:53], 1, v101
	s_andn2_b64 vcc, exec, s[64:65]
	v_max_i32_e32 v101, 0, v0
	v_fma_f32 v102, v48, v101, 0
	v_max_i32_e32 v101, 0, v1
	v_fmac_f32_e32 v102, v49, v101
	v_max_i32_e32 v101, 0, v2
	v_fmac_f32_e32 v102, v50, v101
	v_max_i32_e32 v101, 0, v3
	v_fmac_f32_e32 v102, v51, v101
	v_max_i32_e32 v101, 0, v4
	v_fmac_f32_e32 v102, v52, v101
	v_mfma_f32_32x32x16_bf16 v[16:31], v[36:39], v[92:95], v[16:31]
	v_max_i32_e32 v101, 0, v5
	v_fmac_f32_e32 v102, v53, v101
	v_max_i32_e32 v101, 0, v6
	v_fmac_f32_e32 v102, v54, v101
	v_max_i32_e32 v101, 0, v7
	v_fmac_f32_e32 v102, v55, v101
	v_max_i32_e32 v101, 0, v8
	v_fmac_f32_e32 v102, v56, v101
	v_max_i32_e32 v101, 0, v9
	v_fmac_f32_e32 v102, v57, v101
	v_mfma_f32_32x32x16_bf16 v[16:31], v[40:43], v[84:87], v[16:31]
	v_max_i32_e32 v101, 0, v10
	v_fmac_f32_e32 v102, v58, v101
	v_max_i32_e32 v101, 0, v11
	v_fmac_f32_e32 v102, v59, v101
	v_max_i32_e32 v101, 0, v12
	v_fmac_f32_e32 v102, v60, v101
	v_max_i32_e32 v101, 0, v13
	v_fmac_f32_e32 v102, v61, v101
	v_mfma_f32_32x32x16_bf16 v[16:31], v[44:47], v[108:111], v[16:31]
	v_max_i32_e32 v101, 0, v14
	s_cmp_eq_u32 s58, 54
	v_fmac_f32_e32 v102, v62, v101
	v_max_i32_e32 v101, 0, v15
	s_cselect_b64 s[64:65], -1, 0
	v_cmp_gt_i32_e32 vcc, v180, v203
	v_fmac_f32_e32 v102, v63, v101
	s_and_b64 vcc, s[64:65], vcc
	v_cndmask_b32_e32 v248, v102, v197, vcc
.Lixj65:
.LBB0_1438:
.LBB0_1440:
	s_waitcnt lgkmcnt(0)
	s_cmpk_lt_u32 s95, 0x6e
	s_cbranch_scc1 .Lixc64
	v_mfma_f32_32x32x16_bf16 v[0:15], v[32:35], v[96:99], 0
	s_not_b64 s[52:53], s[60:61]
	v_max_i32_e32 v97, 0, v16
	v_fma_f32 v249, v48, v97, 0
	v_max_i32_e32 v97, 0, v17
	v_fmac_f32_e32 v249, v49, v97
	v_max_i32_e32 v97, 0, v18
	v_fmac_f32_e32 v249, v50, v97
	v_max_i32_e32 v97, 0, v19
	v_fmac_f32_e32 v249, v51, v97
	v_max_i32_e32 v97, 0, v20
	v_fmac_f32_e32 v249, v52, v97
	v_mfma_f32_32x32x16_bf16 v[0:15], v[36:39], v[88:91], v[0:15]
	v_max_i32_e32 v97, 0, v21
	v_fmac_f32_e32 v249, v53, v97
	v_max_i32_e32 v97, 0, v22
	v_fmac_f32_e32 v249, v54, v97
	v_max_i32_e32 v97, 0, v23
	v_fmac_f32_e32 v249, v55, v97
	v_max_i32_e32 v97, 0, v24
	v_fmac_f32_e32 v249, v56, v97
	v_max_i32_e32 v97, 0, v25
	v_fmac_f32_e32 v249, v57, v97
	v_mfma_f32_32x32x16_bf16 v[0:15], v[40:43], v[80:83], v[0:15]
	v_max_i32_e32 v97, 0, v26
	v_fmac_f32_e32 v249, v58, v97
	v_max_i32_e32 v97, 0, v27
	v_fmac_f32_e32 v249, v59, v97
	v_max_i32_e32 v97, 0, v28
	v_fmac_f32_e32 v249, v60, v97
	v_max_i32_e32 v97, 0, v29
	v_fmac_f32_e32 v249, v61, v97
	v_mfma_f32_32x32x16_bf16 v[0:15], v[44:47], v[104:107], v[0:15]
	v_max_i32_e32 v97, 0, v30
	v_fmac_f32_e32 v249, v62, v97
	v_max_i32_e32 v97, 0, v31
	v_fmac_f32_e32 v249, v63, v97

.Lixj63:
	s_waitcnt lgkmcnt(0)
	ds_read_b128 v[96:99], v134 offset:0x3600
	ds_read_b128 v[88:91], v134 offset:0x3620
	ds_read_b128 v[80:83], v134 offset:0x3640
	ds_read_b128 v[104:107], v134 offset:0x3660
	s_cmpk_gt_u32 s95, 0x73
	s_cselect_b64 s[60:61], -1, 0
	s_cmpk_lt_u32 s95, 0x74
	s_cbranch_scc1 .Lixc62
	v_mfma_f32_32x32x16_bf16 v[16:31], v[32:35], v[108:111], 0
	s_not_b64 s[52:53], s[62:63]
	v_max_i32_e32 v109, 0, v0
	v_fma_f32 v252, v48, v109, 0
	v_max_i32_e32 v109, 0, v1
	v_fmac_f32_e32 v252, v49, v109
	v_max_i32_e32 v109, 0, v2
	v_fmac_f32_e32 v252, v50, v109
	v_max_i32_e32 v109, 0, v3
	v_fmac_f32_e32 v252, v51, v109
	v_max_i32_e32 v109, 0, v4
	v_fmac_f32_e32 v252, v52, v109
	v_mfma_f32_32x32x16_bf16 v[16:31], v[36:39], v[100:103], v[16:31]
	v_max_i32_e32 v109, 0, v5
	v_fmac_f32_e32 v252, v53, v109
	v_max_i32_e32 v109, 0, v6
	v_fmac_f32_e32 v252, v54, v109
	v_max_i32_e32 v109, 0, v7
	v_fmac_f32_e32 v252, v55, v109
	v_max_i32_e32 v109, 0, v8
	v_fmac_f32_e32 v252, v56, v109
	v_max_i32_e32 v109, 0, v9
	v_fmac_f32_e32 v252, v57, v109
	v_mfma_f32_32x32x16_bf16 v[16:31], v[40:43], v[92:95], v[16:31]
	v_max_i32_e32 v109, 0, v10
	v_fmac_f32_e32 v252, v58, v109
	v_max_i32_e32 v109, 0, v11
	v_fmac_f32_e32 v252, v59, v109
	v_max_i32_e32 v109, 0, v12
	v_fmac_f32_e32 v252, v60, v109
	v_max_i32_e32 v109, 0, v13
	v_fmac_f32_e32 v252, v61, v109
	v_mfma_f32_32x32x16_bf16 v[16:31], v[44:47], v[84:87], v[16:31]
	v_max_i32_e32 v109, 0, v14
	v_fmac_f32_e32 v252, v62, v109
	v_max_i32_e32 v109, 0, v15
	v_fmac_f32_e32 v252, v63, v109
.Lixj62:
.LBB0_1456:
.LBB0_1458:
	s_waitcnt lgkmcnt(0)
	ds_read_b128 v[100:103], v134 offset:0x4800
	ds_read_b128 v[92:95], v134 offset:0x4820
	ds_read_b128 v[84:87], v134 offset:0x4840
	ds_read_b128 v[108:111], v134 offset:0x4860
	s_cmpk_gt_u32 s95, 0x75
	s_cselect_b64 s[62:63], -1, 0
	s_cmpk_lt_u32 s95, 0x76
	s_cbranch_scc1 .Lixc61
	v_mfma_f32_32x32x16_bf16 v[0:15], v[32:35], v[96:99], 0
	s_not_b64 s[52:53], s[60:61]
	v_max_i32_e32 v97, 0, v16
	v_fma_f32 v253, v48, v97, 0
	v_max_i32_e32 v97, 0, v17
	v_fmac_f32_e32 v253, v49, v97
	v_max_i32_e32 v97, 0, v18
	v_fmac_f32_e32 v253, v50, v97
	v_max_i32_e32 v97, 0, v19
	v_fmac_f32_e32 v253, v51, v97
	v_max_i32_e32 v97, 0, v20
	v_fmac_f32_e32 v253, v52, v97
	v_mfma_f32_32x32x16_bf16 v[0:15], v[36:39], v[88:91], v[0:15]
	v_max_i32_e32 v97, 0, v21
	v_fmac_f32_e32 v253, v53, v97
	v_max_i32_e32 v97, 0, v22
	v_fmac_f32_e32 v253, v54, v97
	v_max_i32_e32 v97, 0, v23
	v_fmac_f32_e32 v253, v55, v97
	v_max_i32_e32 v97, 0, v24
	v_fmac_f32_e32 v253, v56, v97
	v_max_i32_e32 v97, 0, v25
	v_fmac_f32_e32 v253, v57, v97
	v_mfma_f32_32x32x16_bf16 v[0:15], v[40:43], v[80:83], v[0:15]
	v_max_i32_e32 v97, 0, v26
	v_fmac_f32_e32 v253, v58, v97
	v_max_i32_e32 v97, 0, v27
	v_fmac_f32_e32 v253, v59, v97
	v_max_i32_e32 v97, 0, v28
	v_fmac_f32_e32 v253, v60, v97
	v_max_i32_e32 v97, 0, v29
	v_fmac_f32_e32 v253, v61, v97
	v_mfma_f32_32x32x16_bf16 v[0:15], v[44:47], v[104:107], v[0:15]
	v_max_i32_e32 v97, 0, v30
	v_fmac_f32_e32 v253, v62, v97
	v_max_i32_e32 v97, 0, v31
	v_fmac_f32_e32 v253, v63, v97
.Lixj61:
.LBB0_1462:
.LBB0_1464:
	s_waitcnt lgkmcnt(0)
	ds_read_b128 v[96:99], v134 offset:0x5a00
	ds_read_b128 v[88:91], v134 offset:0x5a20
	ds_read_b128 v[80:83], v134 offset:0x5a40
	ds_read_b128 v[104:107], v134 offset:0x5a60
	s_cmpk_gt_u32 s95, 0x77
	s_cselect_b64 s[60:61], -1, 0
	s_cmpk_lt_u32 s95, 0x78
	s_cbranch_scc1 .Lixc60
	v_mfma_f32_32x32x16_bf16 v[16:31], v[32:35], v[100:103], 0
	s_not_b64 s[52:53], s[62:63]
	v_max_i32_e32 v101, 0, v0
	v_fma_f32 v215, v48, v101, 0
	v_max_i32_e32 v101, 0, v1
	v_fmac_f32_e32 v215, v49, v101
	v_max_i32_e32 v101, 0, v2
	v_fmac_f32_e32 v215, v50, v101
	v_max_i32_e32 v101, 0, v3
	v_fmac_f32_e32 v215, v51, v101
	v_max_i32_e32 v101, 0, v4
	v_fmac_f32_e32 v215, v52, v101
	v_mfma_f32_32x32x16_bf16 v[16:31], v[36:39], v[92:95], v[16:31]
	v_max_i32_e32 v101, 0, v5
	v_fmac_f32_e32 v215, v53, v101
	v_max_i32_e32 v101, 0, v6
	v_fmac_f32_e32 v215, v54, v101
	v_max_i32_e32 v101, 0, v7
	v_fmac_f32_e32 v215, v55, v101
	v_max_i32_e32 v101, 0, v8
	v_fmac_f32_e32 v215, v56, v101
	v_max_i32_e32 v101, 0, v9
	v_fmac_f32_e32 v215, v57, v101
	v_mfma_f32_32x32x16_bf16 v[16:31], v[40:43], v[84:87], v[16:31]
	v_max_i32_e32 v101, 0, v10
	v_fmac_f32_e32 v215, v58, v101
	v_max_i32_e32 v101, 0, v11
	v_fmac_f32_e32 v215, v59, v101
	v_max_i32_e32 v101, 0, v12
	v_fmac_f32_e32 v215, v60, v101
	v_max_i32_e32 v101, 0, v13
	v_fmac_f32_e32 v215, v61, v101
	v_mfma_f32_32x32x16_bf16 v[16:31], v[44:47], v[108:111], v[16:31]
	v_max_i32_e32 v101, 0, v14
	v_fmac_f32_e32 v215, v62, v101
	v_max_i32_e32 v101, 0, v15
	v_fmac_f32_e32 v215, v63, v101
.Lixj60:
.LBB0_1468:
.LBB0_1470:
	s_waitcnt lgkmcnt(0)
	ds_read_b128 v[100:103], v134 offset:0x6c00
	ds_read_b128 v[92:95], v134 offset:0x6c20
	ds_read_b128 v[84:87], v134 offset:0x6c40
	ds_read_b128 v[108:111], v134 offset:0x6c60
	s_cmpk_gt_u32 s95, 0x79
	s_cselect_b64 s[62:63], -1, 0
	s_cmpk_lt_u32 s95, 0x7a
	s_cbranch_scc1 .Lixc59
	v_mfma_f32_32x32x16_bf16 v[0:15], v[32:35], v[96:99], 0
	s_not_b64 s[52:53], s[60:61]
	v_max_i32_e32 v97, 0, v16
	v_fma_f32 v133, v48, v97, 0
	v_max_i32_e32 v97, 0, v17
	v_fmac_f32_e32 v133, v49, v97
	v_max_i32_e32 v97, 0, v18
	v_fmac_f32_e32 v133, v50, v97
	v_max_i32_e32 v97, 0, v19
	v_fmac_f32_e32 v133, v51, v97
	v_max_i32_e32 v97, 0, v20
	v_fmac_f32_e32 v133, v52, v97
	v_mfma_f32_32x32x16_bf16 v[0:15], v[36:39], v[88:91], v[0:15]
	v_max_i32_e32 v97, 0, v21
	v_fmac_f32_e32 v133, v53, v97
	v_max_i32_e32 v97, 0, v22
	v_fmac_f32_e32 v133, v54, v97
	v_max_i32_e32 v97, 0, v23
	v_fmac_f32_e32 v133, v55, v97
	v_max_i32_e32 v97, 0, v24
	v_fmac_f32_e32 v133, v56, v97
	v_max_i32_e32 v97, 0, v25
	v_fmac_f32_e32 v133, v57, v97
	v_mfma_f32_32x32x16_bf16 v[0:15], v[40:43], v[80:83], v[0:15]
	v_max_i32_e32 v97, 0, v26
	v_fmac_f32_e32 v133, v58, v97
	v_max_i32_e32 v97, 0, v27
	v_fmac_f32_e32 v133, v59, v97
	v_max_i32_e32 v97, 0, v28
	v_fmac_f32_e32 v133, v60, v97
	v_max_i32_e32 v97, 0, v29
	v_fmac_f32_e32 v133, v61, v97
	v_mfma_f32_32x32x16_bf16 v[0:15], v[44:47], v[104:107], v[0:15]
	v_max_i32_e32 v97, 0, v30
	v_fmac_f32_e32 v133, v62, v97
	v_max_i32_e32 v97, 0, v31
	v_fmac_f32_e32 v133, v63, v97
.Lixj59:
.LBB0_1474:
.LBB0_1476:
	s_waitcnt lgkmcnt(0)
	ds_read_b128 v[96:99], v134 offset:0x7e00
	ds_read_b128 v[88:91], v134 offset:0x7e20
	ds_read_b128 v[80:83], v134 offset:0x7e40
	ds_read_b128 v[104:107], v134 offset:0x7e60
	s_cmpk_gt_u32 s95, 0x7b
	s_cselect_b64 s[60:61], -1, 0
	s_cmpk_lt_u32 s95, 0x7c
	s_cbranch_scc1 .Lixc58
	v_mfma_f32_32x32x16_bf16 v[16:31], v[32:35], v[100:103], 0
	v_cndmask_b32_e64 v101, 0, 1, s[62:63]
	v_cmp_ne_u32_e64 s[52:53], 1, v101
	s_andn2_b64 vcc, exec, s[62:63]
	v_max_i32_e32 v101, 0, v0
	v_fma_f32 v102, v48, v101, 0
	v_max_i32_e32 v101, 0, v1
	v_fmac_f32_e32 v102, v49, v101
	v_max_i32_e32 v101, 0, v2
	v_fmac_f32_e32 v102, v50, v101
	v_max_i32_e32 v101, 0, v3
	v_fmac_f32_e32 v102, v51, v101
	v_max_i32_e32 v101, 0, v4
	v_fmac_f32_e32 v102, v52, v101
	v_mfma_f32_32x32x16_bf16 v[16:31], v[36:39], v[92:95], v[16:31]
	v_max_i32_e32 v101, 0, v5
	v_fmac_f32_e32 v102, v53, v101
	v_max_i32_e32 v101, 0, v6
	v_fmac_f32_e32 v102, v54, v101
	v_max_i32_e32 v101, 0, v7
	v_fmac_f32_e32 v102, v55, v101
	v_max_i32_e32 v101, 0, v8
	v_fmac_f32_e32 v102, v56, v101
	v_max_i32_e32 v101, 0, v9
	v_fmac_f32_e32 v102, v57, v101
	v_mfma_f32_32x32x16_bf16 v[16:31], v[40:43], v[84:87], v[16:31]
	v_max_i32_e32 v101, 0, v10
	v_fmac_f32_e32 v102, v58, v101
	v_max_i32_e32 v101, 0, v11
	v_fmac_f32_e32 v102, v59, v101
	v_max_i32_e32 v101, 0, v12
	v_fmac_f32_e32 v102, v60, v101
	v_max_i32_e32 v101, 0, v13
	v_fmac_f32_e32 v102, v61, v101
	v_mfma_f32_32x32x16_bf16 v[16:31], v[44:47], v[108:111], v[16:31]
	v_max_i32_e32 v101, 0, v14
	s_cmp_eq_u32 s58, 62
	v_fmac_f32_e32 v102, v62, v101
	v_max_i32_e32 v101, 0, v15
	s_cselect_b64 s[62:63], -1, 0
	v_cmp_gt_i32_e32 vcc, v188, v203
	v_fmac_f32_e32 v102, v63, v101
	s_and_b64 vcc, s[62:63], vcc
	v_cndmask_b32_e32 v84, v102, v197, vcc
.Lixj58:
.LBB0_1480:
.LBB0_1482:
	s_waitcnt lgkmcnt(0)
	s_cmpk_lt_u32 s95, 0x7e
	s_cbranch_scc1 .Lixc57
	v_mfma_f32_32x32x16_bf16 v[0:15], v[32:35], v[96:99], 0
	v_cndmask_b32_e64 v97, 0, 1, s[60:61]
	v_cmp_ne_u32_e64 s[52:53], 1, v97
	s_andn2_b64 vcc, exec, s[60:61]
	v_max_i32_e32 v97, 0, v16
	v_fma_f32 v98, v48, v97, 0
	v_max_i32_e32 v97, 0, v17
	v_fmac_f32_e32 v98, v49, v97
	v_max_i32_e32 v97, 0, v18
	v_fmac_f32_e32 v98, v50, v97
	v_max_i32_e32 v97, 0, v19
	v_fmac_f32_e32 v98, v51, v97
	v_max_i32_e32 v97, 0, v20
	v_fmac_f32_e32 v98, v52, v97
	v_mfma_f32_32x32x16_bf16 v[0:15], v[36:39], v[88:91], v[0:15]
	v_max_i32_e32 v97, 0, v21
	v_fmac_f32_e32 v98, v53, v97
	v_max_i32_e32 v97, 0, v22
	v_fmac_f32_e32 v98, v54, v97
	v_max_i32_e32 v97, 0, v23
	v_fmac_f32_e32 v98, v55, v97
	v_max_i32_e32 v97, 0, v24
	v_fmac_f32_e32 v98, v56, v97
	v_max_i32_e32 v97, 0, v25
	v_fmac_f32_e32 v98, v57, v97
	v_mfma_f32_32x32x16_bf16 v[0:15], v[40:43], v[80:83], v[0:15]
	v_max_i32_e32 v97, 0, v26
	v_fmac_f32_e32 v98, v58, v97
	v_max_i32_e32 v97, 0, v27
	v_fmac_f32_e32 v98, v59, v97
	v_max_i32_e32 v97, 0, v28
	v_fmac_f32_e32 v98, v60, v97
	v_max_i32_e32 v97, 0, v29
	v_fmac_f32_e32 v98, v61, v97
	v_mfma_f32_32x32x16_bf16 v[0:15], v[44:47], v[104:107], v[0:15]
	v_max_i32_e32 v97, 0, v30
	s_cmp_eq_u32 s58, 63
	v_fmac_f32_e32 v98, v62, v97
	v_max_i32_e32 v97, 0, v31
	s_cselect_b64 s[60:61], -1, 0
	v_cmp_gt_i32_e32 vcc, v189, v203
	v_fmac_f32_e32 v98, v63, v97
	s_and_b64 vcc, s[60:61], vcc
	v_cndmask_b32_e32 v80, v98, v197, vcc
.Lixj57:
.LBB0_1486:
.LBB0_1488:
	s_barrier
	s_cmp_lg_u32 s58, 64
	v_mov_b32_e32 v16, 0xff800000
	s_cbranch_scc0 .LBB0_1514
	s_branch .LBB0_1515

.Lixj55:
.LBB0_1750:
.LBB0_1752:
	s_waitcnt lgkmcnt(0)
	ds_read_b128 v[112:115], v131 offset:0x4800
	ds_read_b128 v[88:91], v131 offset:0x4820
	ds_read_b128 v[80:83], v131 offset:0x4840
	ds_read_b128 v[116:119], v131 offset:0x4860
	s_cmp_gt_u32 s94, 5
	s_cselect_b64 s[68:69], -1, 0
	s_cmp_lt_u32 s94, 6
	s_cbranch_scc1 .Lixc54
	v_mfma_f32_32x32x16_bf16 v[0:15], v[32:35], v[104:107], 0
	v_cndmask_b32_e64 v105, 0, 1, s[66:67]
	v_cmp_ne_u32_e64 s[52:53], 1, v105
	s_andn2_b64 vcc, exec, s[66:67]
	v_max_i32_e32 v105, 0, v16
	v_fma_f32 v106, v48, v105, 0
	v_max_i32_e32 v105, 0, v17
	v_fmac_f32_e32 v106, v49, v105
	v_max_i32_e32 v105, 0, v18
	v_fmac_f32_e32 v106, v50, v105
	v_max_i32_e32 v105, 0, v19
	v_fmac_f32_e32 v106, v51, v105
	v_max_i32_e32 v105, 0, v20
	v_fmac_f32_e32 v106, v52, v105
	v_mfma_f32_32x32x16_bf16 v[0:15], v[36:39], v[100:103], v[0:15]
	v_max_i32_e32 v105, 0, v21
	v_fmac_f32_e32 v106, v53, v105
	v_max_i32_e32 v105, 0, v22
	v_fmac_f32_e32 v106, v54, v105
	v_max_i32_e32 v105, 0, v23
	v_fmac_f32_e32 v106, v55, v105
	v_max_i32_e32 v105, 0, v24
	v_fmac_f32_e32 v106, v56, v105
	v_max_i32_e32 v105, 0, v25
	v_fmac_f32_e32 v106, v57, v105
	v_mfma_f32_32x32x16_bf16 v[0:15], v[40:43], v[96:99], v[0:15]
	v_max_i32_e32 v105, 0, v26
	v_fmac_f32_e32 v106, v58, v105
	v_max_i32_e32 v105, 0, v27
	v_fmac_f32_e32 v106, v59, v105
	v_max_i32_e32 v105, 0, v28
	v_fmac_f32_e32 v106, v60, v105
	v_max_i32_e32 v105, 0, v29
	v_fmac_f32_e32 v106, v61, v105
	v_mfma_f32_32x32x16_bf16 v[0:15], v[44:47], v[108:111], v[0:15]
	v_max_i32_e32 v105, 0, v30
	v_fmac_f32_e32 v106, v62, v105
	v_max_i32_e32 v105, 0, v31
	v_fmac_f32_e32 v106, v63, v105
	s_cmp_eq_u32 s60, 3
	v_or_b32_e32 v105, 64, v130
	s_cselect_b64 s[0:1], -1, 0
	v_cmp_gt_i32_e32 vcc, v105, v203
	s_and_b64 vcc, s[0:1], vcc
	s_nop 0
	v_cndmask_b32_e32 v202, v106, v197, vcc
.Lixj54:
.LBB0_1756:
.LBB0_1758:
	s_waitcnt lgkmcnt(0)
	ds_read_b128 v[96:99], v131 offset:0x5a00
	ds_read_b128 v[92:95], v131 offset:0x5a20
	ds_read_b128 v[84:87], v131 offset:0x5a40
	ds_read_b128 v[104:107], v131 offset:0x5a60
	s_cmp_gt_u32 s94, 7
	s_cselect_b64 s[66:67], -1, 0
	s_cmp_lt_u32 s94, 8
	s_cbranch_scc1 .Lixc53
	v_mfma_f32_32x32x16_bf16 v[16:31], v[32:35], v[112:115], 0
	v_cndmask_b32_e64 v113, 0, 1, s[68:69]
	v_cmp_ne_u32_e64 s[52:53], 1, v113
	s_andn2_b64 vcc, exec, s[68:69]
	v_max_i32_e32 v113, 0, v0
	v_fma_f32 v114, v48, v113, 0
	v_max_i32_e32 v113, 0, v1
	v_fmac_f32_e32 v114, v49, v113
	v_max_i32_e32 v113, 0, v2
	v_fmac_f32_e32 v114, v50, v113
	v_max_i32_e32 v113, 0, v3
	v_fmac_f32_e32 v114, v51, v113
	v_max_i32_e32 v113, 0, v4
	v_fmac_f32_e32 v114, v52, v113
	v_mfma_f32_32x32x16_bf16 v[16:31], v[36:39], v[88:91], v[16:31]
	v_max_i32_e32 v113, 0, v5
	v_fmac_f32_e32 v114, v53, v113
	v_max_i32_e32 v113, 0, v6
	v_fmac_f32_e32 v114, v54, v113
	v_max_i32_e32 v113, 0, v7
	v_fmac_f32_e32 v114, v55, v113
	v_max_i32_e32 v113, 0, v8
	v_fmac_f32_e32 v114, v56, v113
	v_max_i32_e32 v113, 0, v9
	v_fmac_f32_e32 v114, v57, v113
	v_mfma_f32_32x32x16_bf16 v[16:31], v[40:43], v[80:83], v[16:31]
	v_max_i32_e32 v113, 0, v10
	v_fmac_f32_e32 v114, v58, v113
	v_max_i32_e32 v113, 0, v11
	v_fmac_f32_e32 v114, v59, v113
	v_max_i32_e32 v113, 0, v12
	v_fmac_f32_e32 v114, v60, v113
	v_max_i32_e32 v113, 0, v13
	v_fmac_f32_e32 v114, v61, v113
	v_mfma_f32_32x32x16_bf16 v[16:31], v[44:47], v[116:119], v[16:31]
	v_max_i32_e32 v113, 0, v14
	v_fmac_f32_e32 v114, v62, v113
	v_max_i32_e32 v113, 0, v15
	v_fmac_f32_e32 v114, v63, v113
	s_cmp_eq_u32 s60, 4
	v_or_b32_e32 v113, 0x60, v130
	s_cselect_b64 s[0:1], -1, 0
	v_cmp_gt_i32_e32 vcc, v113, v203
	s_and_b64 vcc, s[0:1], vcc
	s_nop 0
	v_cndmask_b32_e32 v112, v114, v197, vcc
.Lixj53:
.LBB0_1762:
.LBB0_1764:
	s_waitcnt lgkmcnt(0)
	ds_read_b128 v[100:103], v131 offset:0x6c00
	ds_read_b128 v[88:91], v131 offset:0x6c20
	ds_read_b128 v[80:83], v131 offset:0x6c40
	ds_read_b128 v[108:111], v131 offset:0x6c60
	s_cmp_gt_u32 s94, 9
	s_cselect_b64 s[68:69], -1, 0
	s_cmp_lt_u32 s94, 10
	s_cbranch_scc1 .Lixc52
	v_mfma_f32_32x32x16_bf16 v[0:15], v[32:35], v[96:99], 0
	v_cndmask_b32_e64 v97, 0, 1, s[66:67]
	v_cmp_ne_u32_e64 s[52:53], 1, v97
	s_andn2_b64 vcc, exec, s[66:67]
	v_max_i32_e32 v97, 0, v16
	v_fma_f32 v98, v48, v97, 0
	v_max_i32_e32 v97, 0, v17
	v_fmac_f32_e32 v98, v49, v97
	v_max_i32_e32 v97, 0, v18
	v_fmac_f32_e32 v98, v50, v97
	v_max_i32_e32 v97, 0, v19
	v_fmac_f32_e32 v98, v51, v97
	v_max_i32_e32 v97, 0, v20
	v_fmac_f32_e32 v98, v52, v97
	v_mfma_f32_32x32x16_bf16 v[0:15], v[36:39], v[92:95], v[0:15]
	v_max_i32_e32 v97, 0, v21
	v_fmac_f32_e32 v98, v53, v97
	v_max_i32_e32 v97, 0, v22
	v_fmac_f32_e32 v98, v54, v97
	v_max_i32_e32 v97, 0, v23
	v_fmac_f32_e32 v98, v55, v97
	v_max_i32_e32 v97, 0, v24
	v_fmac_f32_e32 v98, v56, v97
	v_max_i32_e32 v97, 0, v25
	v_fmac_f32_e32 v98, v57, v97
	v_mfma_f32_32x32x16_bf16 v[0:15], v[40:43], v[84:87], v[0:15]
	v_max_i32_e32 v97, 0, v26
	v_fmac_f32_e32 v98, v58, v97
	v_max_i32_e32 v97, 0, v27
	v_fmac_f32_e32 v98, v59, v97
	v_max_i32_e32 v97, 0, v28
	v_fmac_f32_e32 v98, v60, v97
	v_max_i32_e32 v97, 0, v29
	v_fmac_f32_e32 v98, v61, v97
	v_mfma_f32_32x32x16_bf16 v[0:15], v[44:47], v[104:107], v[0:15]
	v_max_i32_e32 v97, 0, v30
	v_fmac_f32_e32 v98, v62, v97
	v_max_i32_e32 v97, 0, v31
	v_fmac_f32_e32 v98, v63, v97
	s_cmp_eq_u32 s60, 5
	v_or_b32_e32 v97, 0x80, v130
	s_cselect_b64 s[0:1], -1, 0
	v_cmp_gt_i32_e32 vcc, v97, v203
	s_and_b64 vcc, s[0:1], vcc
	s_nop 0
	v_cndmask_b32_e32 v113, v98, v197, vcc
.Lixj52:
.LBB0_1768:
.LBB0_1770:
	s_waitcnt lgkmcnt(0)
	ds_read_b128 v[96:99], v131 offset:0x7e00
	ds_read_b128 v[92:95], v131 offset:0x7e20
	ds_read_b128 v[84:87], v131 offset:0x7e40
	ds_read_b128 v[104:107], v131 offset:0x7e60
	s_cmp_gt_u32 s94, 11
	s_cselect_b64 s[66:67], -1, 0
	s_cmp_lt_u32 s94, 12
	s_cbranch_scc1 .Lixc51
	v_mfma_f32_32x32x16_bf16 v[16:31], v[32:35], v[100:103], 0
	v_cndmask_b32_e64 v101, 0, 1, s[68:69]
	v_cmp_ne_u32_e64 s[52:53], 1, v101
	s_andn2_b64 vcc, exec, s[68:69]
	v_max_i32_e32 v101, 0, v0
	v_fma_f32 v102, v48, v101, 0
	v_max_i32_e32 v101, 0, v1
	v_fmac_f32_e32 v102, v49, v101
	v_max_i32_e32 v101, 0, v2
	v_fmac_f32_e32 v102, v50, v101
	v_max_i32_e32 v101, 0, v3
	v_fmac_f32_e32 v102, v51, v101
	v_max_i32_e32 v101, 0, v4
	v_fmac_f32_e32 v102, v52, v101
	v_mfma_f32_32x32x16_bf16 v[16:31], v[36:39], v[88:91], v[16:31]
	v_max_i32_e32 v101, 0, v5
	v_fmac_f32_e32 v102, v53, v101
	v_max_i32_e32 v101, 0, v6
	v_fmac_f32_e32 v102, v54, v101
	v_max_i32_e32 v101, 0, v7
	v_fmac_f32_e32 v102, v55, v101
	v_max_i32_e32 v101, 0, v8
	v_fmac_f32_e32 v102, v56, v101
	v_max_i32_e32 v101, 0, v9
	v_fmac_f32_e32 v102, v57, v101
	v_mfma_f32_32x32x16_bf16 v[16:31], v[40:43], v[80:83], v[16:31]
	v_max_i32_e32 v101, 0, v10
	v_fmac_f32_e32 v102, v58, v101
	v_max_i32_e32 v101, 0, v11
	v_fmac_f32_e32 v102, v59, v101
	v_max_i32_e32 v101, 0, v12
	v_fmac_f32_e32 v102, v60, v101
	v_max_i32_e32 v101, 0, v13
	v_fmac_f32_e32 v102, v61, v101
	v_mfma_f32_32x32x16_bf16 v[16:31], v[44:47], v[108:111], v[16:31]
	v_max_i32_e32 v101, 0, v14
	v_fmac_f32_e32 v102, v62, v101
	v_max_i32_e32 v101, 0, v15
	v_fmac_f32_e32 v102, v63, v101
	s_cmp_eq_u32 s60, 6
	v_or_b32_e32 v101, 0xa0, v130
	s_cselect_b64 s[0:1], -1, 0
	v_cmp_gt_i32_e32 vcc, v101, v203
	s_and_b64 vcc, s[0:1], vcc
	s_nop 0
	v_cndmask_b32_e32 v114, v102, v197, vcc
.Lixj51:
.LBB0_1774:
.LBB0_1776:
	s_waitcnt lgkmcnt(0)
	s_cmp_lt_u32 s94, 14
	s_cbranch_scc1 .Lixc50
	v_mfma_f32_32x32x16_bf16 v[0:15], v[32:35], v[96:99], 0
	v_cndmask_b32_e64 v97, 0, 1, s[66:67]
	v_cmp_ne_u32_e64 s[52:53], 1, v97
	s_andn2_b64 vcc, exec, s[66:67]
	v_max_i32_e32 v97, 0, v16
	v_fma_f32 v98, v48, v97, 0
	v_max_i32_e32 v97, 0, v17
	v_fmac_f32_e32 v98, v49, v97
	v_max_i32_e32 v97, 0, v18
	v_fmac_f32_e32 v98, v50, v97
	v_max_i32_e32 v97, 0, v19
	v_fmac_f32_e32 v98, v51, v97
	v_max_i32_e32 v97, 0, v20
	v_fmac_f32_e32 v98, v52, v97
	v_mfma_f32_32x32x16_bf16 v[0:15], v[36:39], v[92:95], v[0:15]
	v_max_i32_e32 v97, 0, v21
	v_fmac_f32_e32 v98, v53, v97
	v_max_i32_e32 v97, 0, v22
	v_fmac_f32_e32 v98, v54, v97
	v_max_i32_e32 v97, 0, v23
	v_fmac_f32_e32 v98, v55, v97
	v_max_i32_e32 v97, 0, v24
	v_fmac_f32_e32 v98, v56, v97
	v_max_i32_e32 v97, 0, v25
	v_fmac_f32_e32 v98, v57, v97
	v_mfma_f32_32x32x16_bf16 v[0:15], v[40:43], v[84:87], v[0:15]
	v_max_i32_e32 v97, 0, v26
	v_fmac_f32_e32 v98, v58, v97
	v_max_i32_e32 v97, 0, v27
	v_fmac_f32_e32 v98, v59, v97
	v_max_i32_e32 v97, 0, v28
	v_fmac_f32_e32 v98, v60, v97
	v_max_i32_e32 v97, 0, v29
	v_fmac_f32_e32 v98, v61, v97
	v_mfma_f32_32x32x16_bf16 v[0:15], v[44:47], v[104:107], v[0:15]
	v_max_i32_e32 v97, 0, v30
	s_cmp_eq_u32 s60, 7
	v_fmac_f32_e32 v98, v62, v97
	v_max_i32_e32 v97, 0, v31
	s_cselect_b64 s[0:1], -1, 0
	v_cmp_gt_i32_e32 vcc, v132, v203
	v_fmac_f32_e32 v98, v63, v97
	s_and_b64 vcc, s[0:1], vcc
	v_cndmask_b32_e32 v115, v98, v197, vcc
.Lixj50:
.LBB0_1780:
.LBB0_1782:
	v_cndmask_b32_e64 v16, 0, 1, s[64:65]
	v_cmp_ne_u32_e64 s[52:53], 1, v16
	s_andn2_b64 vcc, exec, s[64:65]
	s_cbranch_vccnz .LBB0_1784
	s_waitcnt vmcnt(3)
	ds_write_b128 v193, v[64:67] offset:36864
	s_waitcnt vmcnt(2)
	ds_write_b128 v194, v[68:71] offset:36864
	s_waitcnt vmcnt(1)
	ds_write_b128 v195, v[72:75] offset:36864
	s_waitcnt vmcnt(0)
	ds_write_b128 v196, v[76:79] offset:36864

.Lixj49:
	s_waitcnt lgkmcnt(0)
	ds_read_b128 v[96:99], v134 offset:0x3600
	ds_read_b128 v[88:91], v134 offset:0x3620
	ds_read_b128 v[80:83], v134 offset:0x3640
	ds_read_b128 v[104:107], v134 offset:0x3660
	s_cmp_gt_u32 s94, 19
	s_cselect_b64 s[66:67], -1, 0
	s_cmp_lt_u32 s94, 20
	s_cbranch_scc1 .Lixc48
	v_mfma_f32_32x32x16_bf16 v[16:31], v[32:35], v[108:111], 0
	s_not_b64 s[54:55], s[0:1]
	v_max_i32_e32 v109, 0, v0
	v_fma_f32 v118, v48, v109, 0
	v_max_i32_e32 v109, 0, v1
	v_fmac_f32_e32 v118, v49, v109
	v_max_i32_e32 v109, 0, v2
	v_fmac_f32_e32 v118, v50, v109
	v_max_i32_e32 v109, 0, v3
	v_fmac_f32_e32 v118, v51, v109
	v_max_i32_e32 v109, 0, v4
	v_fmac_f32_e32 v118, v52, v109
	v_mfma_f32_32x32x16_bf16 v[16:31], v[36:39], v[100:103], v[16:31]
	v_max_i32_e32 v109, 0, v5
	v_fmac_f32_e32 v118, v53, v109
	v_max_i32_e32 v109, 0, v6
	v_fmac_f32_e32 v118, v54, v109
	v_max_i32_e32 v109, 0, v7
	v_fmac_f32_e32 v118, v55, v109
	v_max_i32_e32 v109, 0, v8
	v_fmac_f32_e32 v118, v56, v109
	v_max_i32_e32 v109, 0, v9
	v_fmac_f32_e32 v118, v57, v109
	v_mfma_f32_32x32x16_bf16 v[16:31], v[40:43], v[92:95], v[16:31]
	v_max_i32_e32 v109, 0, v10
	v_fmac_f32_e32 v118, v58, v109
	v_max_i32_e32 v109, 0, v11
	v_fmac_f32_e32 v118, v59, v109
	v_max_i32_e32 v109, 0, v12
	v_fmac_f32_e32 v118, v60, v109
	v_max_i32_e32 v109, 0, v13
	v_fmac_f32_e32 v118, v61, v109
	v_mfma_f32_32x32x16_bf16 v[16:31], v[44:47], v[84:87], v[16:31]
	v_max_i32_e32 v109, 0, v14
	v_fmac_f32_e32 v118, v62, v109
	v_max_i32_e32 v109, 0, v15
	v_fmac_f32_e32 v118, v63, v109
.Lixj48:
.LBB0_1797:
.LBB0_1799:
	s_waitcnt lgkmcnt(0)
	ds_read_b128 v[100:103], v134 offset:0x4800
	ds_read_b128 v[92:95], v134 offset:0x4820
	ds_read_b128 v[84:87], v134 offset:0x4840
	ds_read_b128 v[108:111], v134 offset:0x4860
	s_cmp_gt_u32 s94, 21
	s_cselect_b64 s[68:69], -1, 0
	s_cmp_lt_u32 s94, 22
	s_cbranch_scc1 .Lixc47
	v_mfma_f32_32x32x16_bf16 v[0:15], v[32:35], v[96:99], 0
	s_not_b64 s[54:55], s[66:67]
	v_max_i32_e32 v97, 0, v16
	v_fma_f32 v119, v48, v97, 0
	v_max_i32_e32 v97, 0, v17
	v_fmac_f32_e32 v119, v49, v97
	v_max_i32_e32 v97, 0, v18
	v_fmac_f32_e32 v119, v50, v97
	v_max_i32_e32 v97, 0, v19
	v_fmac_f32_e32 v119, v51, v97
	v_max_i32_e32 v97, 0, v20
	v_fmac_f32_e32 v119, v52, v97
	v_mfma_f32_32x32x16_bf16 v[0:15], v[36:39], v[88:91], v[0:15]
	v_max_i32_e32 v97, 0, v21
	v_fmac_f32_e32 v119, v53, v97
	v_max_i32_e32 v97, 0, v22
	v_fmac_f32_e32 v119, v54, v97
	v_max_i32_e32 v97, 0, v23
	v_fmac_f32_e32 v119, v55, v97
	v_max_i32_e32 v97, 0, v24
	v_fmac_f32_e32 v119, v56, v97
	v_max_i32_e32 v97, 0, v25
	v_fmac_f32_e32 v119, v57, v97
	v_mfma_f32_32x32x16_bf16 v[0:15], v[40:43], v[80:83], v[0:15]
	v_max_i32_e32 v97, 0, v26
	v_fmac_f32_e32 v119, v58, v97
	v_max_i32_e32 v97, 0, v27
	v_fmac_f32_e32 v119, v59, v97
	v_max_i32_e32 v97, 0, v28
	v_fmac_f32_e32 v119, v60, v97
	v_max_i32_e32 v97, 0, v29
	v_fmac_f32_e32 v119, v61, v97
	v_mfma_f32_32x32x16_bf16 v[0:15], v[44:47], v[104:107], v[0:15]
	v_max_i32_e32 v97, 0, v30
	v_fmac_f32_e32 v119, v62, v97
	v_max_i32_e32 v97, 0, v31
	v_fmac_f32_e32 v119, v63, v97
.Lixj47:
.LBB0_1803:
.LBB0_1805:
	s_waitcnt lgkmcnt(0)
	ds_read_b128 v[96:99], v134 offset:0x5a00
	ds_read_b128 v[88:91], v134 offset:0x5a20
	ds_read_b128 v[80:83], v134 offset:0x5a40
	ds_read_b128 v[104:107], v134 offset:0x5a60
	s_cmp_gt_u32 s94, 23
	s_cselect_b64 s[66:67], -1, 0
	s_cmp_lt_u32 s94, 24
	s_cbranch_scc1 .Lixc46
	v_mfma_f32_32x32x16_bf16 v[16:31], v[32:35], v[100:103], 0
	s_not_b64 s[54:55], s[68:69]
	v_max_i32_e32 v101, 0, v0
	v_fma_f32 v205, v48, v101, 0
	v_max_i32_e32 v101, 0, v1
	v_fmac_f32_e32 v205, v49, v101
	v_max_i32_e32 v101, 0, v2
	v_fmac_f32_e32 v205, v50, v101
	v_max_i32_e32 v101, 0, v3
	v_fmac_f32_e32 v205, v51, v101
	v_max_i32_e32 v101, 0, v4
	v_fmac_f32_e32 v205, v52, v101
	v_mfma_f32_32x32x16_bf16 v[16:31], v[36:39], v[92:95], v[16:31]
	v_max_i32_e32 v101, 0, v5
	v_fmac_f32_e32 v205, v53, v101
	v_max_i32_e32 v101, 0, v6
	v_fmac_f32_e32 v205, v54, v101
	v_max_i32_e32 v101, 0, v7
	v_fmac_f32_e32 v205, v55, v101
	v_max_i32_e32 v101, 0, v8
	v_fmac_f32_e32 v205, v56, v101
	v_max_i32_e32 v101, 0, v9
	v_fmac_f32_e32 v205, v57, v101
	v_mfma_f32_32x32x16_bf16 v[16:31], v[40:43], v[84:87], v[16:31]
	v_max_i32_e32 v101, 0, v10
	v_fmac_f32_e32 v205, v58, v101
	v_max_i32_e32 v101, 0, v11
	v_fmac_f32_e32 v205, v59, v101
	v_max_i32_e32 v101, 0, v12
	v_fmac_f32_e32 v205, v60, v101
	v_max_i32_e32 v101, 0, v13
	v_fmac_f32_e32 v205, v61, v101
	v_mfma_f32_32x32x16_bf16 v[16:31], v[44:47], v[108:111], v[16:31]
	v_max_i32_e32 v101, 0, v14
	v_fmac_f32_e32 v205, v62, v101
	v_max_i32_e32 v101, 0, v15
	v_fmac_f32_e32 v205, v63, v101
.Lixj46:
.LBB0_1809:
.LBB0_1811:
	s_waitcnt lgkmcnt(0)
	ds_read_b128 v[100:103], v134 offset:0x6c00
	ds_read_b128 v[92:95], v134 offset:0x6c20
	ds_read_b128 v[84:87], v134 offset:0x6c40
	ds_read_b128 v[108:111], v134 offset:0x6c60
	s_cmp_gt_u32 s94, 25
	s_cselect_b64 s[68:69], -1, 0
	s_cmp_lt_u32 s94, 26
	s_cbranch_scc1 .Lixc45
	v_mfma_f32_32x32x16_bf16 v[0:15], v[32:35], v[96:99], 0
	s_not_b64 s[54:55], s[66:67]
	v_max_i32_e32 v97, 0, v16
	v_fma_f32 v206, v48, v97, 0
	v_max_i32_e32 v97, 0, v17
	v_fmac_f32_e32 v206, v49, v97
	v_max_i32_e32 v97, 0, v18
	v_fmac_f32_e32 v206, v50, v97
	v_max_i32_e32 v97, 0, v19
	v_fmac_f32_e32 v206, v51, v97
	v_max_i32_e32 v97, 0, v20
	v_fmac_f32_e32 v206, v52, v97
	v_mfma_f32_32x32x16_bf16 v[0:15], v[36:39], v[88:91], v[0:15]
	v_max_i32_e32 v97, 0, v21
	v_fmac_f32_e32 v206, v53, v97
	v_max_i32_e32 v97, 0, v22
	v_fmac_f32_e32 v206, v54, v97
	v_max_i32_e32 v97, 0, v23
	v_fmac_f32_e32 v206, v55, v97
	v_max_i32_e32 v97, 0, v24
	v_fmac_f32_e32 v206, v56, v97
	v_max_i32_e32 v97, 0, v25
	v_fmac_f32_e32 v206, v57, v97
	v_mfma_f32_32x32x16_bf16 v[0:15], v[40:43], v[80:83], v[0:15]
	v_max_i32_e32 v97, 0, v26
	v_fmac_f32_e32 v206, v58, v97
	v_max_i32_e32 v97, 0, v27
	v_fmac_f32_e32 v206, v59, v97
	v_max_i32_e32 v97, 0, v28
	v_fmac_f32_e32 v206, v60, v97
	v_max_i32_e32 v97, 0, v29
	v_fmac_f32_e32 v206, v61, v97
	v_mfma_f32_32x32x16_bf16 v[0:15], v[44:47], v[104:107], v[0:15]
	v_max_i32_e32 v97, 0, v30
	v_fmac_f32_e32 v206, v62, v97
	v_max_i32_e32 v97, 0, v31
	v_fmac_f32_e32 v206, v63, v97
.Lixj45:
.LBB0_1815:
.LBB0_1817:
	s_waitcnt lgkmcnt(0)
	ds_read_b128 v[96:99], v134 offset:0x7e00
	ds_read_b128 v[88:91], v134 offset:0x7e20
	ds_read_b128 v[80:83], v134 offset:0x7e40
	ds_read_b128 v[104:107], v134 offset:0x7e60
	s_cmp_gt_u32 s94, 27
	s_cselect_b64 s[66:67], -1, 0
	s_cmp_lt_u32 s94, 28
	s_cbranch_scc1 .Lixc44
	v_mfma_f32_32x32x16_bf16 v[16:31], v[32:35], v[100:103], 0
	s_not_b64 s[54:55], s[68:69]
	v_max_i32_e32 v101, 0, v0
	v_fma_f32 v207, v48, v101, 0
	v_max_i32_e32 v101, 0, v1
	v_fmac_f32_e32 v207, v49, v101
	v_max_i32_e32 v101, 0, v2
	v_fmac_f32_e32 v207, v50, v101
	v_max_i32_e32 v101, 0, v3
	v_fmac_f32_e32 v207, v51, v101
	v_max_i32_e32 v101, 0, v4
	v_fmac_f32_e32 v207, v52, v101
	v_mfma_f32_32x32x16_bf16 v[16:31], v[36:39], v[92:95], v[16:31]
	v_max_i32_e32 v101, 0, v5
	v_fmac_f32_e32 v207, v53, v101
	v_max_i32_e32 v101, 0, v6
	v_fmac_f32_e32 v207, v54, v101
	v_max_i32_e32 v101, 0, v7
	v_fmac_f32_e32 v207, v55, v101
	v_max_i32_e32 v101, 0, v8
	v_fmac_f32_e32 v207, v56, v101
	v_max_i32_e32 v101, 0, v9
	v_fmac_f32_e32 v207, v57, v101
	v_mfma_f32_32x32x16_bf16 v[16:31], v[40:43], v[84:87], v[16:31]
	v_max_i32_e32 v101, 0, v10
	v_fmac_f32_e32 v207, v58, v101
	v_max_i32_e32 v101, 0, v11
	v_fmac_f32_e32 v207, v59, v101
	v_max_i32_e32 v101, 0, v12
	v_fmac_f32_e32 v207, v60, v101
	v_max_i32_e32 v101, 0, v13
	v_fmac_f32_e32 v207, v61, v101
	v_mfma_f32_32x32x16_bf16 v[16:31], v[44:47], v[108:111], v[16:31]
	v_max_i32_e32 v101, 0, v14
	v_fmac_f32_e32 v207, v62, v101
	v_max_i32_e32 v101, 0, v15
	v_fmac_f32_e32 v207, v63, v101
.Lixj44:
.LBB0_1821:
.LBB0_1823:
	s_waitcnt lgkmcnt(0)
	s_cmp_lt_u32 s94, 30
	s_cbranch_scc1 .Lixc43
	v_mfma_f32_32x32x16_bf16 v[0:15], v[32:35], v[96:99], 0
	v_cndmask_b32_e64 v97, 0, 1, s[66:67]
	v_cmp_ne_u32_e64 s[54:55], 1, v97
	s_andn2_b64 vcc, exec, s[66:67]
	v_max_i32_e32 v97, 0, v16
	v_fma_f32 v98, v48, v97, 0
	v_max_i32_e32 v97, 0, v17
	v_fmac_f32_e32 v98, v49, v97
	v_max_i32_e32 v97, 0, v18
	v_fmac_f32_e32 v98, v50, v97
	v_max_i32_e32 v97, 0, v19
	v_fmac_f32_e32 v98, v51, v97
	v_max_i32_e32 v97, 0, v20
	v_fmac_f32_e32 v98, v52, v97
	v_mfma_f32_32x32x16_bf16 v[0:15], v[36:39], v[88:91], v[0:15]
	v_max_i32_e32 v97, 0, v21
	v_fmac_f32_e32 v98, v53, v97
	v_max_i32_e32 v97, 0, v22
	v_fmac_f32_e32 v98, v54, v97
	v_max_i32_e32 v97, 0, v23
	v_fmac_f32_e32 v98, v55, v97
	v_max_i32_e32 v97, 0, v24
	v_fmac_f32_e32 v98, v56, v97
	v_max_i32_e32 v97, 0, v25
	v_fmac_f32_e32 v98, v57, v97
	v_mfma_f32_32x32x16_bf16 v[0:15], v[40:43], v[80:83], v[0:15]
	v_max_i32_e32 v97, 0, v26
	v_fmac_f32_e32 v98, v58, v97
	v_max_i32_e32 v97, 0, v27
	v_fmac_f32_e32 v98, v59, v97
	v_max_i32_e32 v97, 0, v28
	v_fmac_f32_e32 v98, v60, v97
	v_max_i32_e32 v97, 0, v29
	v_fmac_f32_e32 v98, v61, v97
	v_mfma_f32_32x32x16_bf16 v[0:15], v[44:47], v[104:107], v[0:15]
	v_max_i32_e32 v97, 0, v30
	s_cmp_eq_u32 s60, 15
	v_fmac_f32_e32 v98, v62, v97
	v_max_i32_e32 v97, 0, v31
	s_cselect_b64 s[0:1], -1, 0
	v_cmp_gt_i32_e32 vcc, v141, v203
	v_fmac_f32_e32 v98, v63, v97
	s_and_b64 vcc, s[0:1], vcc
	v_cndmask_b32_e32 v208, v98, v197, vcc
.Lixj43:
.LBB0_1827:
.LBB0_1829:
	s_andn2_b64 vcc, exec, s[64:65]
	s_cbranch_vccnz .LBB0_1831
	s_waitcnt vmcnt(3)
	ds_write_b128 v193, v[64:67]
	s_waitcnt vmcnt(2)
	ds_write_b128 v194, v[68:71]
	s_waitcnt vmcnt(1)
	ds_write_b128 v195, v[72:75]
	s_waitcnt vmcnt(0)
	ds_write_b128 v196, v[76:79]

.Lixj42:
	s_waitcnt lgkmcnt(0)
	ds_read_b128 v[96:99], v131 offset:0x3600
	ds_read_b128 v[88:91], v131 offset:0x3620
	ds_read_b128 v[80:83], v131 offset:0x3640
	ds_read_b128 v[104:107], v131 offset:0x3660
	s_cmp_gt_u32 s94, 35
	s_cselect_b64 s[66:67], -1, 0
	s_cmp_lt_u32 s94, 36
	s_cbranch_scc1 .Lixc41
	v_mfma_f32_32x32x16_bf16 v[16:31], v[32:35], v[108:111], 0
	s_not_b64 s[54:55], s[0:1]
	v_max_i32_e32 v109, 0, v0
	v_fma_f32 v211, v48, v109, 0
	v_max_i32_e32 v109, 0, v1
	v_fmac_f32_e32 v211, v49, v109
	v_max_i32_e32 v109, 0, v2
	v_fmac_f32_e32 v211, v50, v109
	v_max_i32_e32 v109, 0, v3
	v_fmac_f32_e32 v211, v51, v109
	v_max_i32_e32 v109, 0, v4
	v_fmac_f32_e32 v211, v52, v109
	v_mfma_f32_32x32x16_bf16 v[16:31], v[36:39], v[100:103], v[16:31]
	v_max_i32_e32 v109, 0, v5
	v_fmac_f32_e32 v211, v53, v109
	v_max_i32_e32 v109, 0, v6
	v_fmac_f32_e32 v211, v54, v109
	v_max_i32_e32 v109, 0, v7
	v_fmac_f32_e32 v211, v55, v109
	v_max_i32_e32 v109, 0, v8
	v_fmac_f32_e32 v211, v56, v109
	v_max_i32_e32 v109, 0, v9
	v_fmac_f32_e32 v211, v57, v109
	v_mfma_f32_32x32x16_bf16 v[16:31], v[40:43], v[92:95], v[16:31]
	v_max_i32_e32 v109, 0, v10
	v_fmac_f32_e32 v211, v58, v109
	v_max_i32_e32 v109, 0, v11
	v_fmac_f32_e32 v211, v59, v109
	v_max_i32_e32 v109, 0, v12
	v_fmac_f32_e32 v211, v60, v109
	v_max_i32_e32 v109, 0, v13
	v_fmac_f32_e32 v211, v61, v109
	v_mfma_f32_32x32x16_bf16 v[16:31], v[44:47], v[84:87], v[16:31]
	v_max_i32_e32 v109, 0, v14
	v_fmac_f32_e32 v211, v62, v109
	v_max_i32_e32 v109, 0, v15
	v_fmac_f32_e32 v211, v63, v109
.Lixj41:
.LBB0_1841:
.LBB0_1843:
	s_waitcnt lgkmcnt(0)
	ds_read_b128 v[100:103], v131 offset:0x4800
	ds_read_b128 v[92:95], v131 offset:0x4820
	ds_read_b128 v[84:87], v131 offset:0x4840
	ds_read_b128 v[108:111], v131 offset:0x4860
	s_cmp_gt_u32 s94, 37
	s_cselect_b64 s[68:69], -1, 0
	s_cmp_lt_u32 s94, 38
	s_cbranch_scc1 .Lixc40
	v_mfma_f32_32x32x16_bf16 v[0:15], v[32:35], v[96:99], 0
	s_not_b64 s[54:55], s[66:67]
	v_max_i32_e32 v97, 0, v16
	v_fma_f32 v212, v48, v97, 0
	v_max_i32_e32 v97, 0, v17
	v_fmac_f32_e32 v212, v49, v97
	v_max_i32_e32 v97, 0, v18
	v_fmac_f32_e32 v212, v50, v97
	v_max_i32_e32 v97, 0, v19
	v_fmac_f32_e32 v212, v51, v97
	v_max_i32_e32 v97, 0, v20
	v_fmac_f32_e32 v212, v52, v97
	v_mfma_f32_32x32x16_bf16 v[0:15], v[36:39], v[88:91], v[0:15]
	v_max_i32_e32 v97, 0, v21
	v_fmac_f32_e32 v212, v53, v97
	v_max_i32_e32 v97, 0, v22
	v_fmac_f32_e32 v212, v54, v97
	v_max_i32_e32 v97, 0, v23
	v_fmac_f32_e32 v212, v55, v97
	v_max_i32_e32 v97, 0, v24
	v_fmac_f32_e32 v212, v56, v97
	v_max_i32_e32 v97, 0, v25
	v_fmac_f32_e32 v212, v57, v97
	v_mfma_f32_32x32x16_bf16 v[0:15], v[40:43], v[80:83], v[0:15]
	v_max_i32_e32 v97, 0, v26
	v_fmac_f32_e32 v212, v58, v97
	v_max_i32_e32 v97, 0, v27
	v_fmac_f32_e32 v212, v59, v97
	v_max_i32_e32 v97, 0, v28
	v_fmac_f32_e32 v212, v60, v97
	v_max_i32_e32 v97, 0, v29
	v_fmac_f32_e32 v212, v61, v97
	v_mfma_f32_32x32x16_bf16 v[0:15], v[44:47], v[104:107], v[0:15]
	v_max_i32_e32 v97, 0, v30
	v_fmac_f32_e32 v212, v62, v97
	v_max_i32_e32 v97, 0, v31
	v_fmac_f32_e32 v212, v63, v97
.Lixj40:
.LBB0_1847:
.LBB0_1849:
	s_waitcnt lgkmcnt(0)
	ds_read_b128 v[96:99], v131 offset:0x5a00
	ds_read_b128 v[88:91], v131 offset:0x5a20
	ds_read_b128 v[80:83], v131 offset:0x5a40
	ds_read_b128 v[104:107], v131 offset:0x5a60
	s_cmp_gt_u32 s94, 39
	s_cselect_b64 s[66:67], -1, 0
	s_cmp_lt_u32 s94, 40
	s_cbranch_scc1 .Lixc39
	v_mfma_f32_32x32x16_bf16 v[16:31], v[32:35], v[100:103], 0
	s_not_b64 s[54:55], s[68:69]
	v_max_i32_e32 v101, 0, v0
	v_fma_f32 v213, v48, v101, 0
	v_max_i32_e32 v101, 0, v1
	v_fmac_f32_e32 v213, v49, v101
	v_max_i32_e32 v101, 0, v2
	v_fmac_f32_e32 v213, v50, v101
	v_max_i32_e32 v101, 0, v3
	v_fmac_f32_e32 v213, v51, v101
	v_max_i32_e32 v101, 0, v4
	v_fmac_f32_e32 v213, v52, v101
	v_mfma_f32_32x32x16_bf16 v[16:31], v[36:39], v[92:95], v[16:31]
	v_max_i32_e32 v101, 0, v5
	v_fmac_f32_e32 v213, v53, v101
	v_max_i32_e32 v101, 0, v6
	v_fmac_f32_e32 v213, v54, v101
	v_max_i32_e32 v101, 0, v7
	v_fmac_f32_e32 v213, v55, v101
	v_max_i32_e32 v101, 0, v8
	v_fmac_f32_e32 v213, v56, v101
	v_max_i32_e32 v101, 0, v9
	v_fmac_f32_e32 v213, v57, v101
	v_mfma_f32_32x32x16_bf16 v[16:31], v[40:43], v[84:87], v[16:31]
	v_max_i32_e32 v101, 0, v10
	v_fmac_f32_e32 v213, v58, v101
	v_max_i32_e32 v101, 0, v11
	v_fmac_f32_e32 v213, v59, v101
	v_max_i32_e32 v101, 0, v12
	v_fmac_f32_e32 v213, v60, v101
	v_max_i32_e32 v101, 0, v13
	v_fmac_f32_e32 v213, v61, v101
	v_mfma_f32_32x32x16_bf16 v[16:31], v[44:47], v[108:111], v[16:31]
	v_max_i32_e32 v101, 0, v14
	v_fmac_f32_e32 v213, v62, v101
	v_max_i32_e32 v101, 0, v15
	v_fmac_f32_e32 v213, v63, v101
.Lixj39:
.LBB0_1853:
.LBB0_1855:
	s_waitcnt lgkmcnt(0)
	ds_read_b128 v[100:103], v131 offset:0x6c00
	ds_read_b128 v[92:95], v131 offset:0x6c20
	ds_read_b128 v[84:87], v131 offset:0x6c40
	ds_read_b128 v[108:111], v131 offset:0x6c60
	s_cmp_gt_u32 s94, 41
	s_cselect_b64 s[68:69], -1, 0
	s_cmp_lt_u32 s94, 42
	s_cbranch_scc1 .Lixc38
	v_mfma_f32_32x32x16_bf16 v[0:15], v[32:35], v[96:99], 0
	s_not_b64 s[54:55], s[66:67]
	v_max_i32_e32 v97, 0, v16
	v_fma_f32 v214, v48, v97, 0
	v_max_i32_e32 v97, 0, v17
	v_fmac_f32_e32 v214, v49, v97
	v_max_i32_e32 v97, 0, v18
	v_fmac_f32_e32 v214, v50, v97
	v_max_i32_e32 v97, 0, v19
	v_fmac_f32_e32 v214, v51, v97
	v_max_i32_e32 v97, 0, v20
	v_fmac_f32_e32 v214, v52, v97
	v_mfma_f32_32x32x16_bf16 v[0:15], v[36:39], v[88:91], v[0:15]
	v_max_i32_e32 v97, 0, v21
	v_fmac_f32_e32 v214, v53, v97
	v_max_i32_e32 v97, 0, v22
	v_fmac_f32_e32 v214, v54, v97
	v_max_i32_e32 v97, 0, v23
	v_fmac_f32_e32 v214, v55, v97
	v_max_i32_e32 v97, 0, v24
	v_fmac_f32_e32 v214, v56, v97
	v_max_i32_e32 v97, 0, v25
	v_fmac_f32_e32 v214, v57, v97
	v_mfma_f32_32x32x16_bf16 v[0:15], v[40:43], v[80:83], v[0:15]
	v_max_i32_e32 v97, 0, v26
	v_fmac_f32_e32 v214, v58, v97
	v_max_i32_e32 v97, 0, v27
	v_fmac_f32_e32 v214, v59, v97
	v_max_i32_e32 v97, 0, v28
	v_fmac_f32_e32 v214, v60, v97
	v_max_i32_e32 v97, 0, v29
	v_fmac_f32_e32 v214, v61, v97
	v_mfma_f32_32x32x16_bf16 v[0:15], v[44:47], v[104:107], v[0:15]
	v_max_i32_e32 v97, 0, v30
	v_fmac_f32_e32 v214, v62, v97
	v_max_i32_e32 v97, 0, v31
	v_fmac_f32_e32 v214, v63, v97
.Lixj38:
.LBB0_1859:
.LBB0_1861:
	s_waitcnt lgkmcnt(0)
	ds_read_b128 v[96:99], v131 offset:0x7e00
	ds_read_b128 v[88:91], v131 offset:0x7e20
	ds_read_b128 v[80:83], v131 offset:0x7e40
	ds_read_b128 v[104:107], v131 offset:0x7e60
	s_cmp_gt_u32 s94, 43
	s_cselect_b64 s[66:67], -1, 0
	s_cmp_lt_u32 s94, 44
	s_cbranch_scc1 .Lixc37
	v_mfma_f32_32x32x16_bf16 v[16:31], v[32:35], v[100:103], 0
	s_not_b64 s[54:55], s[68:69]
	v_max_i32_e32 v101, 0, v0
	v_fma_f32 v216, v48, v101, 0
	v_max_i32_e32 v101, 0, v1
	v_fmac_f32_e32 v216, v49, v101
	v_max_i32_e32 v101, 0, v2
	v_fmac_f32_e32 v216, v50, v101
	v_max_i32_e32 v101, 0, v3
	v_fmac_f32_e32 v216, v51, v101
	v_max_i32_e32 v101, 0, v4
	v_fmac_f32_e32 v216, v52, v101
	v_mfma_f32_32x32x16_bf16 v[16:31], v[36:39], v[92:95], v[16:31]
	v_max_i32_e32 v101, 0, v5
	v_fmac_f32_e32 v216, v53, v101
	v_max_i32_e32 v101, 0, v6
	v_fmac_f32_e32 v216, v54, v101
	v_max_i32_e32 v101, 0, v7
	v_fmac_f32_e32 v216, v55, v101
	v_max_i32_e32 v101, 0, v8
	v_fmac_f32_e32 v216, v56, v101
	v_max_i32_e32 v101, 0, v9
	v_fmac_f32_e32 v216, v57, v101
	v_mfma_f32_32x32x16_bf16 v[16:31], v[40:43], v[84:87], v[16:31]
	v_max_i32_e32 v101, 0, v10
	v_fmac_f32_e32 v216, v58, v101
	v_max_i32_e32 v101, 0, v11
	v_fmac_f32_e32 v216, v59, v101
	v_max_i32_e32 v101, 0, v12
	v_fmac_f32_e32 v216, v60, v101
	v_max_i32_e32 v101, 0, v13
	v_fmac_f32_e32 v216, v61, v101
	v_mfma_f32_32x32x16_bf16 v[16:31], v[44:47], v[108:111], v[16:31]
	v_max_i32_e32 v101, 0, v14
	v_fmac_f32_e32 v216, v62, v101
	v_max_i32_e32 v101, 0, v15
	v_fmac_f32_e32 v216, v63, v101
.Lixj37:
.LBB0_1865:
.LBB0_1867:
	s_waitcnt lgkmcnt(0)
	s_cmp_lt_u32 s94, 46
	s_cbranch_scc1 .Lixc36
	v_mfma_f32_32x32x16_bf16 v[0:15], v[32:35], v[96:99], 0
	v_cndmask_b32_e64 v97, 0, 1, s[66:67]
	v_cmp_ne_u32_e64 s[54:55], 1, v97
	s_andn2_b64 vcc, exec, s[66:67]
	v_max_i32_e32 v97, 0, v16
	v_fma_f32 v98, v48, v97, 0
	v_max_i32_e32 v97, 0, v17
	v_fmac_f32_e32 v98, v49, v97
	v_max_i32_e32 v97, 0, v18
	v_fmac_f32_e32 v98, v50, v97
	v_max_i32_e32 v97, 0, v19
	v_fmac_f32_e32 v98, v51, v97
	v_max_i32_e32 v97, 0, v20
	v_fmac_f32_e32 v98, v52, v97
	v_mfma_f32_32x32x16_bf16 v[0:15], v[36:39], v[88:91], v[0:15]
	v_max_i32_e32 v97, 0, v21
	v_fmac_f32_e32 v98, v53, v97
	v_max_i32_e32 v97, 0, v22
	v_fmac_f32_e32 v98, v54, v97
	v_max_i32_e32 v97, 0, v23
	v_fmac_f32_e32 v98, v55, v97
	v_max_i32_e32 v97, 0, v24
	v_fmac_f32_e32 v98, v56, v97
	v_max_i32_e32 v97, 0, v25
	v_fmac_f32_e32 v98, v57, v97
	v_mfma_f32_32x32x16_bf16 v[0:15], v[40:43], v[80:83], v[0:15]
	v_max_i32_e32 v97, 0, v26
	v_fmac_f32_e32 v98, v58, v97
	v_max_i32_e32 v97, 0, v27
	v_fmac_f32_e32 v98, v59, v97
	v_max_i32_e32 v97, 0, v28
	v_fmac_f32_e32 v98, v60, v97
	v_max_i32_e32 v97, 0, v29
	v_fmac_f32_e32 v98, v61, v97
	v_mfma_f32_32x32x16_bf16 v[0:15], v[44:47], v[104:107], v[0:15]
	v_max_i32_e32 v97, 0, v30
	s_cmp_eq_u32 s60, 23
	v_fmac_f32_e32 v98, v62, v97
	v_max_i32_e32 v97, 0, v31
	s_cselect_b64 s[0:1], -1, 0
	v_cmp_gt_i32_e32 vcc, v149, v203
	v_fmac_f32_e32 v98, v63, v97
	s_and_b64 vcc, s[0:1], vcc
	v_cndmask_b32_e32 v217, v98, v197, vcc
.Lixj36:
.LBB0_1871:
.LBB0_1873:
	s_andn2_b64 vcc, exec, s[64:65]
	s_cbranch_vccnz .LBB0_1875
	s_waitcnt vmcnt(3)
	ds_write_b128 v193, v[64:67] offset:36864
	s_waitcnt vmcnt(2)
	ds_write_b128 v194, v[68:71] offset:36864
	s_waitcnt vmcnt(1)
	ds_write_b128 v195, v[72:75] offset:36864
	s_waitcnt vmcnt(0)
	ds_write_b128 v196, v[76:79] offset:36864

.Lixj35:
	s_waitcnt lgkmcnt(0)
	ds_read_b128 v[96:99], v134 offset:0x3600
	ds_read_b128 v[88:91], v134 offset:0x3620
	ds_read_b128 v[80:83], v134 offset:0x3640
	ds_read_b128 v[104:107], v134 offset:0x3660
	s_cmp_gt_u32 s94, 51
	s_cselect_b64 s[66:67], -1, 0
	s_cmp_lt_u32 s94, 52
	s_cbranch_scc1 .Lixc34
	v_mfma_f32_32x32x16_bf16 v[16:31], v[32:35], v[108:111], 0
	s_not_b64 s[54:55], s[0:1]
	v_max_i32_e32 v109, 0, v0
	v_fma_f32 v220, v48, v109, 0
	v_max_i32_e32 v109, 0, v1
	v_fmac_f32_e32 v220, v49, v109
	v_max_i32_e32 v109, 0, v2
	v_fmac_f32_e32 v220, v50, v109
	v_max_i32_e32 v109, 0, v3
	v_fmac_f32_e32 v220, v51, v109
	v_max_i32_e32 v109, 0, v4
	v_fmac_f32_e32 v220, v52, v109
	v_mfma_f32_32x32x16_bf16 v[16:31], v[36:39], v[100:103], v[16:31]
	v_max_i32_e32 v109, 0, v5
	v_fmac_f32_e32 v220, v53, v109
	v_max_i32_e32 v109, 0, v6
	v_fmac_f32_e32 v220, v54, v109
	v_max_i32_e32 v109, 0, v7
	v_fmac_f32_e32 v220, v55, v109
	v_max_i32_e32 v109, 0, v8
	v_fmac_f32_e32 v220, v56, v109
	v_max_i32_e32 v109, 0, v9
	v_fmac_f32_e32 v220, v57, v109
	v_mfma_f32_32x32x16_bf16 v[16:31], v[40:43], v[92:95], v[16:31]
	v_max_i32_e32 v109, 0, v10
	v_fmac_f32_e32 v220, v58, v109
	v_max_i32_e32 v109, 0, v11
	v_fmac_f32_e32 v220, v59, v109
	v_max_i32_e32 v109, 0, v12
	v_fmac_f32_e32 v220, v60, v109
	v_max_i32_e32 v109, 0, v13
	v_fmac_f32_e32 v220, v61, v109
	v_mfma_f32_32x32x16_bf16 v[16:31], v[44:47], v[84:87], v[16:31]
	v_max_i32_e32 v109, 0, v14
	v_fmac_f32_e32 v220, v62, v109
	v_max_i32_e32 v109, 0, v15
	v_fmac_f32_e32 v220, v63, v109
.Lixj34:
.LBB0_1885:
.LBB0_1887:
	s_waitcnt lgkmcnt(0)
	ds_read_b128 v[100:103], v134 offset:0x4800
	ds_read_b128 v[92:95], v134 offset:0x4820
	ds_read_b128 v[84:87], v134 offset:0x4840
	ds_read_b128 v[108:111], v134 offset:0x4860
	s_cmp_gt_u32 s94, 53
	s_cselect_b64 s[68:69], -1, 0
	s_cmp_lt_u32 s94, 54
	s_cbranch_scc1 .Lixc33
	v_mfma_f32_32x32x16_bf16 v[0:15], v[32:35], v[96:99], 0
	s_not_b64 s[54:55], s[66:67]
	v_max_i32_e32 v97, 0, v16
	v_fma_f32 v221, v48, v97, 0
	v_max_i32_e32 v97, 0, v17
	v_fmac_f32_e32 v221, v49, v97
	v_max_i32_e32 v97, 0, v18
	v_fmac_f32_e32 v221, v50, v97
	v_max_i32_e32 v97, 0, v19
	v_fmac_f32_e32 v221, v51, v97
	v_max_i32_e32 v97, 0, v20
	v_fmac_f32_e32 v221, v52, v97
	v_mfma_f32_32x32x16_bf16 v[0:15], v[36:39], v[88:91], v[0:15]
	v_max_i32_e32 v97, 0, v21
	v_fmac_f32_e32 v221, v53, v97
	v_max_i32_e32 v97, 0, v22
	v_fmac_f32_e32 v221, v54, v97
	v_max_i32_e32 v97, 0, v23
	v_fmac_f32_e32 v221, v55, v97
	v_max_i32_e32 v97, 0, v24
	v_fmac_f32_e32 v221, v56, v97
	v_max_i32_e32 v97, 0, v25
	v_fmac_f32_e32 v221, v57, v97
	v_mfma_f32_32x32x16_bf16 v[0:15], v[40:43], v[80:83], v[0:15]
	v_max_i32_e32 v97, 0, v26
	v_fmac_f32_e32 v221, v58, v97
	v_max_i32_e32 v97, 0, v27
	v_fmac_f32_e32 v221, v59, v97
	v_max_i32_e32 v97, 0, v28
	v_fmac_f32_e32 v221, v60, v97
	v_max_i32_e32 v97, 0, v29
	v_fmac_f32_e32 v221, v61, v97
	v_mfma_f32_32x32x16_bf16 v[0:15], v[44:47], v[104:107], v[0:15]
	v_max_i32_e32 v97, 0, v30
	v_fmac_f32_e32 v221, v62, v97
	v_max_i32_e32 v97, 0, v31
	v_fmac_f32_e32 v221, v63, v97
.Lixj33:
.LBB0_1891:
.LBB0_1893:
	s_waitcnt lgkmcnt(0)
	ds_read_b128 v[96:99], v134 offset:0x5a00
	ds_read_b128 v[88:91], v134 offset:0x5a20
	ds_read_b128 v[80:83], v134 offset:0x5a40
	ds_read_b128 v[104:107], v134 offset:0x5a60
	s_cmp_gt_u32 s94, 55
	s_cselect_b64 s[66:67], -1, 0
	s_cmp_lt_u32 s94, 56
	s_cbranch_scc1 .Lixc32
	v_mfma_f32_32x32x16_bf16 v[16:31], v[32:35], v[100:103], 0
	s_not_b64 s[54:55], s[68:69]
	v_max_i32_e32 v101, 0, v0
	v_fma_f32 v222, v48, v101, 0
	v_max_i32_e32 v101, 0, v1
	v_fmac_f32_e32 v222, v49, v101
	v_max_i32_e32 v101, 0, v2
	v_fmac_f32_e32 v222, v50, v101
	v_max_i32_e32 v101, 0, v3
	v_fmac_f32_e32 v222, v51, v101
	v_max_i32_e32 v101, 0, v4
	v_fmac_f32_e32 v222, v52, v101
	v_mfma_f32_32x32x16_bf16 v[16:31], v[36:39], v[92:95], v[16:31]
	v_max_i32_e32 v101, 0, v5
	v_fmac_f32_e32 v222, v53, v101
	v_max_i32_e32 v101, 0, v6
	v_fmac_f32_e32 v222, v54, v101
	v_max_i32_e32 v101, 0, v7
	v_fmac_f32_e32 v222, v55, v101
	v_max_i32_e32 v101, 0, v8
	v_fmac_f32_e32 v222, v56, v101
	v_max_i32_e32 v101, 0, v9
	v_fmac_f32_e32 v222, v57, v101
	v_mfma_f32_32x32x16_bf16 v[16:31], v[40:43], v[84:87], v[16:31]
	v_max_i32_e32 v101, 0, v10
	v_fmac_f32_e32 v222, v58, v101
	v_max_i32_e32 v101, 0, v11
	v_fmac_f32_e32 v222, v59, v101
	v_max_i32_e32 v101, 0, v12
	v_fmac_f32_e32 v222, v60, v101
	v_max_i32_e32 v101, 0, v13
	v_fmac_f32_e32 v222, v61, v101
	v_mfma_f32_32x32x16_bf16 v[16:31], v[44:47], v[108:111], v[16:31]
	v_max_i32_e32 v101, 0, v14
	v_fmac_f32_e32 v222, v62, v101
	v_max_i32_e32 v101, 0, v15
	v_fmac_f32_e32 v222, v63, v101
.Lixj32:
.LBB0_1897:
.LBB0_1899:
	s_waitcnt lgkmcnt(0)
	ds_read_b128 v[100:103], v134 offset:0x6c00
	ds_read_b128 v[92:95], v134 offset:0x6c20
	ds_read_b128 v[84:87], v134 offset:0x6c40
	ds_read_b128 v[108:111], v134 offset:0x6c60
	s_cmp_gt_u32 s94, 57
	s_cselect_b64 s[68:69], -1, 0
	s_cmp_lt_u32 s94, 58
	s_cbranch_scc1 .Lixc31
	v_mfma_f32_32x32x16_bf16 v[0:15], v[32:35], v[96:99], 0
	s_not_b64 s[54:55], s[66:67]
	v_max_i32_e32 v97, 0, v16
	v_fma_f32 v223, v48, v97, 0
	v_max_i32_e32 v97, 0, v17
	v_fmac_f32_e32 v223, v49, v97
	v_max_i32_e32 v97, 0, v18
	v_fmac_f32_e32 v223, v50, v97
	v_max_i32_e32 v97, 0, v19
	v_fmac_f32_e32 v223, v51, v97
	v_max_i32_e32 v97, 0, v20
	v_fmac_f32_e32 v223, v52, v97
	v_mfma_f32_32x32x16_bf16 v[0:15], v[36:39], v[88:91], v[0:15]
	v_max_i32_e32 v97, 0, v21
	v_fmac_f32_e32 v223, v53, v97
	v_max_i32_e32 v97, 0, v22
	v_fmac_f32_e32 v223, v54, v97
	v_max_i32_e32 v97, 0, v23
	v_fmac_f32_e32 v223, v55, v97
	v_max_i32_e32 v97, 0, v24
	v_fmac_f32_e32 v223, v56, v97
	v_max_i32_e32 v97, 0, v25
	v_fmac_f32_e32 v223, v57, v97
	v_mfma_f32_32x32x16_bf16 v[0:15], v[40:43], v[80:83], v[0:15]
	v_max_i32_e32 v97, 0, v26
	v_fmac_f32_e32 v223, v58, v97
	v_max_i32_e32 v97, 0, v27
	v_fmac_f32_e32 v223, v59, v97
	v_max_i32_e32 v97, 0, v28
	v_fmac_f32_e32 v223, v60, v97
	v_max_i32_e32 v97, 0, v29
	v_fmac_f32_e32 v223, v61, v97
	v_mfma_f32_32x32x16_bf16 v[0:15], v[44:47], v[104:107], v[0:15]
	v_max_i32_e32 v97, 0, v30
	v_fmac_f32_e32 v223, v62, v97
	v_max_i32_e32 v97, 0, v31
	v_fmac_f32_e32 v223, v63, v97
.Lixj31:
.LBB0_1903:
.LBB0_1905:
	s_waitcnt lgkmcnt(0)
	ds_read_b128 v[96:99], v134 offset:0x7e00
	ds_read_b128 v[88:91], v134 offset:0x7e20
	ds_read_b128 v[80:83], v134 offset:0x7e40
	ds_read_b128 v[104:107], v134 offset:0x7e60
	s_cmp_gt_u32 s94, 59
	s_cselect_b64 s[66:67], -1, 0
	s_cmp_lt_u32 s94, 60
	s_cbranch_scc1 .Lixc30
	v_mfma_f32_32x32x16_bf16 v[16:31], v[32:35], v[100:103], 0
	s_not_b64 s[54:55], s[68:69]
	v_max_i32_e32 v101, 0, v0
	v_fma_f32 v224, v48, v101, 0
	v_max_i32_e32 v101, 0, v1
	v_fmac_f32_e32 v224, v49, v101
	v_max_i32_e32 v101, 0, v2
	v_fmac_f32_e32 v224, v50, v101
	v_max_i32_e32 v101, 0, v3
	v_fmac_f32_e32 v224, v51, v101
	v_max_i32_e32 v101, 0, v4
	v_fmac_f32_e32 v224, v52, v101
	v_mfma_f32_32x32x16_bf16 v[16:31], v[36:39], v[92:95], v[16:31]
	v_max_i32_e32 v101, 0, v5
	v_fmac_f32_e32 v224, v53, v101
	v_max_i32_e32 v101, 0, v6
	v_fmac_f32_e32 v224, v54, v101
	v_max_i32_e32 v101, 0, v7
	v_fmac_f32_e32 v224, v55, v101
	v_max_i32_e32 v101, 0, v8
	v_fmac_f32_e32 v224, v56, v101
	v_max_i32_e32 v101, 0, v9
	v_fmac_f32_e32 v224, v57, v101
	v_mfma_f32_32x32x16_bf16 v[16:31], v[40:43], v[84:87], v[16:31]
	v_max_i32_e32 v101, 0, v10
	v_fmac_f32_e32 v224, v58, v101
	v_max_i32_e32 v101, 0, v11
	v_fmac_f32_e32 v224, v59, v101
	v_max_i32_e32 v101, 0, v12
	v_fmac_f32_e32 v224, v60, v101
	v_max_i32_e32 v101, 0, v13
	v_fmac_f32_e32 v224, v61, v101
	v_mfma_f32_32x32x16_bf16 v[16:31], v[44:47], v[108:111], v[16:31]
	v_max_i32_e32 v101, 0, v14
	v_fmac_f32_e32 v224, v62, v101
	v_max_i32_e32 v101, 0, v15
	v_fmac_f32_e32 v224, v63, v101
.Lixj30:
.LBB0_1909:
.LBB0_1911:
	s_waitcnt lgkmcnt(0)
	s_cmp_lt_u32 s94, 62
	s_cbranch_scc1 .Lixc29
	v_mfma_f32_32x32x16_bf16 v[0:15], v[32:35], v[96:99], 0
	v_cndmask_b32_e64 v97, 0, 1, s[66:67]
	v_cmp_ne_u32_e64 s[54:55], 1, v97
	s_andn2_b64 vcc, exec, s[66:67]
	v_max_i32_e32 v97, 0, v16
	v_fma_f32 v98, v48, v97, 0
	v_max_i32_e32 v97, 0, v17
	v_fmac_f32_e32 v98, v49, v97
	v_max_i32_e32 v97, 0, v18
	v_fmac_f32_e32 v98, v50, v97
	v_max_i32_e32 v97, 0, v19
	v_fmac_f32_e32 v98, v51, v97
	v_max_i32_e32 v97, 0, v20
	v_fmac_f32_e32 v98, v52, v97
	v_mfma_f32_32x32x16_bf16 v[0:15], v[36:39], v[88:91], v[0:15]
	v_max_i32_e32 v97, 0, v21
	v_fmac_f32_e32 v98, v53, v97
	v_max_i32_e32 v97, 0, v22
	v_fmac_f32_e32 v98, v54, v97
	v_max_i32_e32 v97, 0, v23
	v_fmac_f32_e32 v98, v55, v97
	v_max_i32_e32 v97, 0, v24
	v_fmac_f32_e32 v98, v56, v97
	v_max_i32_e32 v97, 0, v25
	v_fmac_f32_e32 v98, v57, v97
	v_mfma_f32_32x32x16_bf16 v[0:15], v[40:43], v[80:83], v[0:15]
	v_max_i32_e32 v97, 0, v26
	v_fmac_f32_e32 v98, v58, v97
	v_max_i32_e32 v97, 0, v27
	v_fmac_f32_e32 v98, v59, v97
	v_max_i32_e32 v97, 0, v28
	v_fmac_f32_e32 v98, v60, v97
	v_max_i32_e32 v97, 0, v29
	v_fmac_f32_e32 v98, v61, v97
	v_mfma_f32_32x32x16_bf16 v[0:15], v[44:47], v[104:107], v[0:15]
	v_max_i32_e32 v97, 0, v30
	s_cmp_eq_u32 s60, 31
	v_fmac_f32_e32 v98, v62, v97
	v_max_i32_e32 v97, 0, v31
	s_cselect_b64 s[0:1], -1, 0
	v_cmp_gt_i32_e32 vcc, v157, v203
	v_fmac_f32_e32 v98, v63, v97
	s_and_b64 vcc, s[0:1], vcc
	v_cndmask_b32_e32 v225, v98, v197, vcc

.Lixj28:
	s_waitcnt lgkmcnt(0)
	ds_read_b128 v[96:99], v131 offset:0x3600
	ds_read_b128 v[88:91], v131 offset:0x3620
	ds_read_b128 v[80:83], v131 offset:0x3640
	ds_read_b128 v[104:107], v131 offset:0x3660
	s_cmpk_gt_u32 s94, 0x43
	s_cselect_b64 s[66:67], -1, 0
	s_cmpk_lt_u32 s94, 0x44
	s_cbranch_scc1 .Lixc27
	v_mfma_f32_32x32x16_bf16 v[16:31], v[32:35], v[108:111], 0
	s_not_b64 s[54:55], s[0:1]
	v_max_i32_e32 v109, 0, v0
	v_fma_f32 v228, v48, v109, 0
	v_max_i32_e32 v109, 0, v1
	v_fmac_f32_e32 v228, v49, v109
	v_max_i32_e32 v109, 0, v2
	v_fmac_f32_e32 v228, v50, v109
	v_max_i32_e32 v109, 0, v3
	v_fmac_f32_e32 v228, v51, v109
	v_max_i32_e32 v109, 0, v4
	v_fmac_f32_e32 v228, v52, v109
	v_mfma_f32_32x32x16_bf16 v[16:31], v[36:39], v[100:103], v[16:31]
	v_max_i32_e32 v109, 0, v5
	v_fmac_f32_e32 v228, v53, v109
	v_max_i32_e32 v109, 0, v6
	v_fmac_f32_e32 v228, v54, v109
	v_max_i32_e32 v109, 0, v7
	v_fmac_f32_e32 v228, v55, v109
	v_max_i32_e32 v109, 0, v8
	v_fmac_f32_e32 v228, v56, v109
	v_max_i32_e32 v109, 0, v9
	v_fmac_f32_e32 v228, v57, v109
	v_mfma_f32_32x32x16_bf16 v[16:31], v[40:43], v[92:95], v[16:31]
	v_max_i32_e32 v109, 0, v10
	v_fmac_f32_e32 v228, v58, v109
	v_max_i32_e32 v109, 0, v11
	v_fmac_f32_e32 v228, v59, v109
	v_max_i32_e32 v109, 0, v12
	v_fmac_f32_e32 v228, v60, v109
	v_max_i32_e32 v109, 0, v13
	v_fmac_f32_e32 v228, v61, v109
	v_mfma_f32_32x32x16_bf16 v[16:31], v[44:47], v[84:87], v[16:31]
	v_max_i32_e32 v109, 0, v14
	v_fmac_f32_e32 v228, v62, v109
	v_max_i32_e32 v109, 0, v15
	v_fmac_f32_e32 v228, v63, v109
.Lixj27:
.LBB0_1929:
.LBB0_1931:
	s_waitcnt lgkmcnt(0)
	ds_read_b128 v[100:103], v131 offset:0x4800
	ds_read_b128 v[92:95], v131 offset:0x4820
	ds_read_b128 v[84:87], v131 offset:0x4840
	ds_read_b128 v[108:111], v131 offset:0x4860
	s_cmpk_gt_u32 s94, 0x45
	s_cselect_b64 s[68:69], -1, 0
	s_cmpk_lt_u32 s94, 0x46
	s_cbranch_scc1 .Lixc26
	v_mfma_f32_32x32x16_bf16 v[0:15], v[32:35], v[96:99], 0
	s_not_b64 s[54:55], s[66:67]
	v_max_i32_e32 v97, 0, v16
	v_fma_f32 v229, v48, v97, 0
	v_max_i32_e32 v97, 0, v17
	v_fmac_f32_e32 v229, v49, v97
	v_max_i32_e32 v97, 0, v18
	v_fmac_f32_e32 v229, v50, v97
	v_max_i32_e32 v97, 0, v19
	v_fmac_f32_e32 v229, v51, v97
	v_max_i32_e32 v97, 0, v20
	v_fmac_f32_e32 v229, v52, v97
	v_mfma_f32_32x32x16_bf16 v[0:15], v[36:39], v[88:91], v[0:15]
	v_max_i32_e32 v97, 0, v21
	v_fmac_f32_e32 v229, v53, v97
	v_max_i32_e32 v97, 0, v22
	v_fmac_f32_e32 v229, v54, v97
	v_max_i32_e32 v97, 0, v23
	v_fmac_f32_e32 v229, v55, v97
	v_max_i32_e32 v97, 0, v24
	v_fmac_f32_e32 v229, v56, v97
	v_max_i32_e32 v97, 0, v25
	v_fmac_f32_e32 v229, v57, v97
	v_mfma_f32_32x32x16_bf16 v[0:15], v[40:43], v[80:83], v[0:15]
	v_max_i32_e32 v97, 0, v26
	v_fmac_f32_e32 v229, v58, v97
	v_max_i32_e32 v97, 0, v27
	v_fmac_f32_e32 v229, v59, v97
	v_max_i32_e32 v97, 0, v28
	v_fmac_f32_e32 v229, v60, v97
	v_max_i32_e32 v97, 0, v29
	v_fmac_f32_e32 v229, v61, v97
	v_mfma_f32_32x32x16_bf16 v[0:15], v[44:47], v[104:107], v[0:15]
	v_max_i32_e32 v97, 0, v30
	v_fmac_f32_e32 v229, v62, v97
	v_max_i32_e32 v97, 0, v31
	v_fmac_f32_e32 v229, v63, v97
.Lixj26:
.LBB0_1935:
.LBB0_1937:
	s_waitcnt lgkmcnt(0)
	ds_read_b128 v[96:99], v131 offset:0x5a00
	ds_read_b128 v[88:91], v131 offset:0x5a20
	ds_read_b128 v[80:83], v131 offset:0x5a40
	ds_read_b128 v[104:107], v131 offset:0x5a60
	s_cmpk_gt_u32 s94, 0x47
	s_cselect_b64 s[66:67], -1, 0
	s_cmpk_lt_u32 s94, 0x48
	s_cbranch_scc1 .Lixc25
	v_mfma_f32_32x32x16_bf16 v[16:31], v[32:35], v[100:103], 0
	s_not_b64 s[54:55], s[68:69]
	v_max_i32_e32 v101, 0, v0
	v_fma_f32 v230, v48, v101, 0
	v_max_i32_e32 v101, 0, v1
	v_fmac_f32_e32 v230, v49, v101
	v_max_i32_e32 v101, 0, v2
	v_fmac_f32_e32 v230, v50, v101
	v_max_i32_e32 v101, 0, v3
	v_fmac_f32_e32 v230, v51, v101
	v_max_i32_e32 v101, 0, v4
	v_fmac_f32_e32 v230, v52, v101
	v_mfma_f32_32x32x16_bf16 v[16:31], v[36:39], v[92:95], v[16:31]
	v_max_i32_e32 v101, 0, v5
	v_fmac_f32_e32 v230, v53, v101
	v_max_i32_e32 v101, 0, v6
	v_fmac_f32_e32 v230, v54, v101
	v_max_i32_e32 v101, 0, v7
	v_fmac_f32_e32 v230, v55, v101
	v_max_i32_e32 v101, 0, v8
	v_fmac_f32_e32 v230, v56, v101
	v_max_i32_e32 v101, 0, v9
	v_fmac_f32_e32 v230, v57, v101
	v_mfma_f32_32x32x16_bf16 v[16:31], v[40:43], v[84:87], v[16:31]
	v_max_i32_e32 v101, 0, v10
	v_fmac_f32_e32 v230, v58, v101
	v_max_i32_e32 v101, 0, v11
	v_fmac_f32_e32 v230, v59, v101
	v_max_i32_e32 v101, 0, v12
	v_fmac_f32_e32 v230, v60, v101
	v_max_i32_e32 v101, 0, v13
	v_fmac_f32_e32 v230, v61, v101
	v_mfma_f32_32x32x16_bf16 v[16:31], v[44:47], v[108:111], v[16:31]
	v_max_i32_e32 v101, 0, v14
	v_fmac_f32_e32 v230, v62, v101
	v_max_i32_e32 v101, 0, v15
	v_fmac_f32_e32 v230, v63, v101
.Lixj25:
.LBB0_1941:
.LBB0_1943:
	s_waitcnt lgkmcnt(0)
	ds_read_b128 v[100:103], v131 offset:0x6c00
	ds_read_b128 v[92:95], v131 offset:0x6c20
	ds_read_b128 v[84:87], v131 offset:0x6c40
	ds_read_b128 v[108:111], v131 offset:0x6c60
	s_cmpk_gt_u32 s94, 0x49
	s_cselect_b64 s[68:69], -1, 0
	s_cmpk_lt_u32 s94, 0x4a
	s_cbranch_scc1 .Lixc24
	v_mfma_f32_32x32x16_bf16 v[0:15], v[32:35], v[96:99], 0
	s_not_b64 s[54:55], s[66:67]
	v_max_i32_e32 v97, 0, v16
	v_fma_f32 v231, v48, v97, 0
	v_max_i32_e32 v97, 0, v17
	v_fmac_f32_e32 v231, v49, v97
	v_max_i32_e32 v97, 0, v18
	v_fmac_f32_e32 v231, v50, v97
	v_max_i32_e32 v97, 0, v19
	v_fmac_f32_e32 v231, v51, v97
	v_max_i32_e32 v97, 0, v20
	v_fmac_f32_e32 v231, v52, v97
	v_mfma_f32_32x32x16_bf16 v[0:15], v[36:39], v[88:91], v[0:15]
	v_max_i32_e32 v97, 0, v21
	v_fmac_f32_e32 v231, v53, v97
	v_max_i32_e32 v97, 0, v22
	v_fmac_f32_e32 v231, v54, v97
	v_max_i32_e32 v97, 0, v23
	v_fmac_f32_e32 v231, v55, v97
	v_max_i32_e32 v97, 0, v24
	v_fmac_f32_e32 v231, v56, v97
	v_max_i32_e32 v97, 0, v25
	v_fmac_f32_e32 v231, v57, v97
	v_mfma_f32_32x32x16_bf16 v[0:15], v[40:43], v[80:83], v[0:15]
	v_max_i32_e32 v97, 0, v26
	v_fmac_f32_e32 v231, v58, v97
	v_max_i32_e32 v97, 0, v27
	v_fmac_f32_e32 v231, v59, v97
	v_max_i32_e32 v97, 0, v28
	v_fmac_f32_e32 v231, v60, v97
	v_max_i32_e32 v97, 0, v29
	v_fmac_f32_e32 v231, v61, v97
	v_mfma_f32_32x32x16_bf16 v[0:15], v[44:47], v[104:107], v[0:15]
	v_max_i32_e32 v97, 0, v30
	v_fmac_f32_e32 v231, v62, v97
	v_max_i32_e32 v97, 0, v31
	v_fmac_f32_e32 v231, v63, v97
.Lixj24:
.LBB0_1947:
.LBB0_1949:
	s_waitcnt lgkmcnt(0)
	ds_read_b128 v[96:99], v131 offset:0x7e00
	ds_read_b128 v[88:91], v131 offset:0x7e20
	ds_read_b128 v[80:83], v131 offset:0x7e40
	ds_read_b128 v[104:107], v131 offset:0x7e60
	s_cmpk_gt_u32 s94, 0x4b
	s_cselect_b64 s[66:67], -1, 0
	s_cmpk_lt_u32 s94, 0x4c
	s_cbranch_scc1 .Lixc23
	v_mfma_f32_32x32x16_bf16 v[16:31], v[32:35], v[100:103], 0
	s_not_b64 s[54:55], s[68:69]
	v_max_i32_e32 v101, 0, v0
	v_fma_f32 v232, v48, v101, 0
	v_max_i32_e32 v101, 0, v1
	v_fmac_f32_e32 v232, v49, v101
	v_max_i32_e32 v101, 0, v2
	v_fmac_f32_e32 v232, v50, v101
	v_max_i32_e32 v101, 0, v3
	v_fmac_f32_e32 v232, v51, v101
	v_max_i32_e32 v101, 0, v4
	v_fmac_f32_e32 v232, v52, v101
	v_mfma_f32_32x32x16_bf16 v[16:31], v[36:39], v[92:95], v[16:31]
	v_max_i32_e32 v101, 0, v5
	v_fmac_f32_e32 v232, v53, v101
	v_max_i32_e32 v101, 0, v6
	v_fmac_f32_e32 v232, v54, v101
	v_max_i32_e32 v101, 0, v7
	v_fmac_f32_e32 v232, v55, v101
	v_max_i32_e32 v101, 0, v8
	v_fmac_f32_e32 v232, v56, v101
	v_max_i32_e32 v101, 0, v9
	v_fmac_f32_e32 v232, v57, v101
	v_mfma_f32_32x32x16_bf16 v[16:31], v[40:43], v[84:87], v[16:31]
	v_max_i32_e32 v101, 0, v10
	v_fmac_f32_e32 v232, v58, v101
	v_max_i32_e32 v101, 0, v11
	v_fmac_f32_e32 v232, v59, v101
	v_max_i32_e32 v101, 0, v12
	v_fmac_f32_e32 v232, v60, v101
	v_max_i32_e32 v101, 0, v13
	v_fmac_f32_e32 v232, v61, v101
	v_mfma_f32_32x32x16_bf16 v[16:31], v[44:47], v[108:111], v[16:31]
	v_max_i32_e32 v101, 0, v14
	v_fmac_f32_e32 v232, v62, v101
	v_max_i32_e32 v101, 0, v15
	v_fmac_f32_e32 v232, v63, v101
.Lixj23:
.LBB0_1953:
.LBB0_1955:
	s_waitcnt lgkmcnt(0)
	s_cmpk_lt_u32 s94, 0x4e
	s_cbranch_scc1 .Lixc22
	v_mfma_f32_32x32x16_bf16 v[0:15], v[32:35], v[96:99], 0
	v_cndmask_b32_e64 v97, 0, 1, s[66:67]
	v_cmp_ne_u32_e64 s[54:55], 1, v97
	s_andn2_b64 vcc, exec, s[66:67]
	v_max_i32_e32 v97, 0, v16
	v_fma_f32 v98, v48, v97, 0
	v_max_i32_e32 v97, 0, v17
	v_fmac_f32_e32 v98, v49, v97
	v_max_i32_e32 v97, 0, v18
	v_fmac_f32_e32 v98, v50, v97
	v_max_i32_e32 v97, 0, v19
	v_fmac_f32_e32 v98, v51, v97
	v_max_i32_e32 v97, 0, v20
	v_fmac_f32_e32 v98, v52, v97
	v_mfma_f32_32x32x16_bf16 v[0:15], v[36:39], v[88:91], v[0:15]
	v_max_i32_e32 v97, 0, v21
	v_fmac_f32_e32 v98, v53, v97
	v_max_i32_e32 v97, 0, v22
	v_fmac_f32_e32 v98, v54, v97
	v_max_i32_e32 v97, 0, v23
	v_fmac_f32_e32 v98, v55, v97
	v_max_i32_e32 v97, 0, v24
	v_fmac_f32_e32 v98, v56, v97
	v_max_i32_e32 v97, 0, v25
	v_fmac_f32_e32 v98, v57, v97
	v_mfma_f32_32x32x16_bf16 v[0:15], v[40:43], v[80:83], v[0:15]
	v_max_i32_e32 v97, 0, v26
	v_fmac_f32_e32 v98, v58, v97
	v_max_i32_e32 v97, 0, v27
	v_fmac_f32_e32 v98, v59, v97
	v_max_i32_e32 v97, 0, v28
	v_fmac_f32_e32 v98, v60, v97
	v_max_i32_e32 v97, 0, v29
	v_fmac_f32_e32 v98, v61, v97
	v_mfma_f32_32x32x16_bf16 v[0:15], v[44:47], v[104:107], v[0:15]
	v_max_i32_e32 v97, 0, v30
	s_cmp_eq_u32 s60, 39
	v_fmac_f32_e32 v98, v62, v97
	v_max_i32_e32 v97, 0, v31
	s_cselect_b64 s[0:1], -1, 0
	v_cmp_gt_i32_e32 vcc, v165, v203
	v_fmac_f32_e32 v98, v63, v97
	s_and_b64 vcc, s[0:1], vcc
	v_cndmask_b32_e32 v233, v98, v197, vcc

.Lixj21:
	s_waitcnt lgkmcnt(0)
	ds_read_b128 v[96:99], v134 offset:0x3600
	ds_read_b128 v[88:91], v134 offset:0x3620
	ds_read_b128 v[80:83], v134 offset:0x3640
	ds_read_b128 v[104:107], v134 offset:0x3660
	s_cmpk_gt_u32 s94, 0x53
	s_cselect_b64 s[66:67], -1, 0
	s_cmpk_lt_u32 s94, 0x54
	s_cbranch_scc1 .Lixc20
	v_mfma_f32_32x32x16_bf16 v[16:31], v[32:35], v[108:111], 0
	s_not_b64 s[54:55], s[0:1]
	v_max_i32_e32 v109, 0, v0
	v_fma_f32 v236, v48, v109, 0
	v_max_i32_e32 v109, 0, v1
	v_fmac_f32_e32 v236, v49, v109
	v_max_i32_e32 v109, 0, v2
	v_fmac_f32_e32 v236, v50, v109
	v_max_i32_e32 v109, 0, v3
	v_fmac_f32_e32 v236, v51, v109
	v_max_i32_e32 v109, 0, v4
	v_fmac_f32_e32 v236, v52, v109
	v_mfma_f32_32x32x16_bf16 v[16:31], v[36:39], v[100:103], v[16:31]
	v_max_i32_e32 v109, 0, v5
	v_fmac_f32_e32 v236, v53, v109
	v_max_i32_e32 v109, 0, v6
	v_fmac_f32_e32 v236, v54, v109
	v_max_i32_e32 v109, 0, v7
	v_fmac_f32_e32 v236, v55, v109
	v_max_i32_e32 v109, 0, v8
	v_fmac_f32_e32 v236, v56, v109
	v_max_i32_e32 v109, 0, v9
	v_fmac_f32_e32 v236, v57, v109
	v_mfma_f32_32x32x16_bf16 v[16:31], v[40:43], v[92:95], v[16:31]
	v_max_i32_e32 v109, 0, v10
	v_fmac_f32_e32 v236, v58, v109
	v_max_i32_e32 v109, 0, v11
	v_fmac_f32_e32 v236, v59, v109
	v_max_i32_e32 v109, 0, v12
	v_fmac_f32_e32 v236, v60, v109
	v_max_i32_e32 v109, 0, v13
	v_fmac_f32_e32 v236, v61, v109
	v_mfma_f32_32x32x16_bf16 v[16:31], v[44:47], v[84:87], v[16:31]
	v_max_i32_e32 v109, 0, v14
	v_fmac_f32_e32 v236, v62, v109
	v_max_i32_e32 v109, 0, v15
	v_fmac_f32_e32 v236, v63, v109
.Lixj20:
.LBB0_1973:
.LBB0_1975:
	s_waitcnt lgkmcnt(0)
	ds_read_b128 v[100:103], v134 offset:0x4800
	ds_read_b128 v[92:95], v134 offset:0x4820
	ds_read_b128 v[84:87], v134 offset:0x4840
	ds_read_b128 v[108:111], v134 offset:0x4860
	s_cmpk_gt_u32 s94, 0x55
	s_cselect_b64 s[68:69], -1, 0
	s_cmpk_lt_u32 s94, 0x56
	s_cbranch_scc1 .Lixc19
	v_mfma_f32_32x32x16_bf16 v[0:15], v[32:35], v[96:99], 0
	s_not_b64 s[54:55], s[66:67]
	v_max_i32_e32 v97, 0, v16
	v_fma_f32 v237, v48, v97, 0
	v_max_i32_e32 v97, 0, v17
	v_fmac_f32_e32 v237, v49, v97
	v_max_i32_e32 v97, 0, v18
	v_fmac_f32_e32 v237, v50, v97
	v_max_i32_e32 v97, 0, v19
	v_fmac_f32_e32 v237, v51, v97
	v_max_i32_e32 v97, 0, v20
	v_fmac_f32_e32 v237, v52, v97
	v_mfma_f32_32x32x16_bf16 v[0:15], v[36:39], v[88:91], v[0:15]
	v_max_i32_e32 v97, 0, v21
	v_fmac_f32_e32 v237, v53, v97
	v_max_i32_e32 v97, 0, v22
	v_fmac_f32_e32 v237, v54, v97
	v_max_i32_e32 v97, 0, v23
	v_fmac_f32_e32 v237, v55, v97
	v_max_i32_e32 v97, 0, v24
	v_fmac_f32_e32 v237, v56, v97
	v_max_i32_e32 v97, 0, v25
	v_fmac_f32_e32 v237, v57, v97
	v_mfma_f32_32x32x16_bf16 v[0:15], v[40:43], v[80:83], v[0:15]
	v_max_i32_e32 v97, 0, v26
	v_fmac_f32_e32 v237, v58, v97
	v_max_i32_e32 v97, 0, v27
	v_fmac_f32_e32 v237, v59, v97
	v_max_i32_e32 v97, 0, v28
	v_fmac_f32_e32 v237, v60, v97
	v_max_i32_e32 v97, 0, v29
	v_fmac_f32_e32 v237, v61, v97
	v_mfma_f32_32x32x16_bf16 v[0:15], v[44:47], v[104:107], v[0:15]
	v_max_i32_e32 v97, 0, v30
	v_fmac_f32_e32 v237, v62, v97
	v_max_i32_e32 v97, 0, v31
	v_fmac_f32_e32 v237, v63, v97
.Lixj19:
.LBB0_1979:
.LBB0_1981:
	s_waitcnt lgkmcnt(0)
	ds_read_b128 v[96:99], v134 offset:0x5a00
	ds_read_b128 v[88:91], v134 offset:0x5a20
	ds_read_b128 v[80:83], v134 offset:0x5a40
	ds_read_b128 v[104:107], v134 offset:0x5a60
	s_cmpk_gt_u32 s94, 0x57
	s_cselect_b64 s[66:67], -1, 0
	s_cmpk_lt_u32 s94, 0x58
	s_cbranch_scc1 .Lixc18
	v_mfma_f32_32x32x16_bf16 v[16:31], v[32:35], v[100:103], 0
	s_not_b64 s[54:55], s[68:69]
	v_max_i32_e32 v101, 0, v0
	v_fma_f32 v238, v48, v101, 0
	v_max_i32_e32 v101, 0, v1
	v_fmac_f32_e32 v238, v49, v101
	v_max_i32_e32 v101, 0, v2
	v_fmac_f32_e32 v238, v50, v101
	v_max_i32_e32 v101, 0, v3
	v_fmac_f32_e32 v238, v51, v101
	v_max_i32_e32 v101, 0, v4
	v_fmac_f32_e32 v238, v52, v101
	v_mfma_f32_32x32x16_bf16 v[16:31], v[36:39], v[92:95], v[16:31]
	v_max_i32_e32 v101, 0, v5
	v_fmac_f32_e32 v238, v53, v101
	v_max_i32_e32 v101, 0, v6
	v_fmac_f32_e32 v238, v54, v101
	v_max_i32_e32 v101, 0, v7
	v_fmac_f32_e32 v238, v55, v101
	v_max_i32_e32 v101, 0, v8
	v_fmac_f32_e32 v238, v56, v101
	v_max_i32_e32 v101, 0, v9
	v_fmac_f32_e32 v238, v57, v101
	v_mfma_f32_32x32x16_bf16 v[16:31], v[40:43], v[84:87], v[16:31]
	v_max_i32_e32 v101, 0, v10
	v_fmac_f32_e32 v238, v58, v101
	v_max_i32_e32 v101, 0, v11
	v_fmac_f32_e32 v238, v59, v101
	v_max_i32_e32 v101, 0, v12
	v_fmac_f32_e32 v238, v60, v101
	v_max_i32_e32 v101, 0, v13
	v_fmac_f32_e32 v238, v61, v101
	v_mfma_f32_32x32x16_bf16 v[16:31], v[44:47], v[108:111], v[16:31]
	v_max_i32_e32 v101, 0, v14
	v_fmac_f32_e32 v238, v62, v101
	v_max_i32_e32 v101, 0, v15
	v_fmac_f32_e32 v238, v63, v101
.Lixj18:
.LBB0_1985:
.LBB0_1987:
	s_waitcnt lgkmcnt(0)
	ds_read_b128 v[100:103], v134 offset:0x6c00
	ds_read_b128 v[92:95], v134 offset:0x6c20
	ds_read_b128 v[84:87], v134 offset:0x6c40
	ds_read_b128 v[108:111], v134 offset:0x6c60
	s_cmpk_gt_u32 s94, 0x59
	s_cselect_b64 s[68:69], -1, 0
	s_cmpk_lt_u32 s94, 0x5a
	s_cbranch_scc1 .Lixc17
	v_mfma_f32_32x32x16_bf16 v[0:15], v[32:35], v[96:99], 0
	s_not_b64 s[54:55], s[66:67]
	v_max_i32_e32 v97, 0, v16
	v_fma_f32 v239, v48, v97, 0
	v_max_i32_e32 v97, 0, v17
	v_fmac_f32_e32 v239, v49, v97
	v_max_i32_e32 v97, 0, v18
	v_fmac_f32_e32 v239, v50, v97
	v_max_i32_e32 v97, 0, v19
	v_fmac_f32_e32 v239, v51, v97
	v_max_i32_e32 v97, 0, v20
	v_fmac_f32_e32 v239, v52, v97
	v_mfma_f32_32x32x16_bf16 v[0:15], v[36:39], v[88:91], v[0:15]
	v_max_i32_e32 v97, 0, v21
	v_fmac_f32_e32 v239, v53, v97
	v_max_i32_e32 v97, 0, v22
	v_fmac_f32_e32 v239, v54, v97
	v_max_i32_e32 v97, 0, v23
	v_fmac_f32_e32 v239, v55, v97
	v_max_i32_e32 v97, 0, v24
	v_fmac_f32_e32 v239, v56, v97
	v_max_i32_e32 v97, 0, v25
	v_fmac_f32_e32 v239, v57, v97
	v_mfma_f32_32x32x16_bf16 v[0:15], v[40:43], v[80:83], v[0:15]
	v_max_i32_e32 v97, 0, v26
	v_fmac_f32_e32 v239, v58, v97
	v_max_i32_e32 v97, 0, v27
	v_fmac_f32_e32 v239, v59, v97
	v_max_i32_e32 v97, 0, v28
	v_fmac_f32_e32 v239, v60, v97
	v_max_i32_e32 v97, 0, v29
	v_fmac_f32_e32 v239, v61, v97
	v_mfma_f32_32x32x16_bf16 v[0:15], v[44:47], v[104:107], v[0:15]
	v_max_i32_e32 v97, 0, v30
	v_fmac_f32_e32 v239, v62, v97
	v_max_i32_e32 v97, 0, v31
	v_fmac_f32_e32 v239, v63, v97
.Lixj17:
.LBB0_1991:
.LBB0_1993:
	s_waitcnt lgkmcnt(0)
	ds_read_b128 v[96:99], v134 offset:0x7e00
	ds_read_b128 v[88:91], v134 offset:0x7e20
	ds_read_b128 v[80:83], v134 offset:0x7e40
	ds_read_b128 v[104:107], v134 offset:0x7e60
	s_cmpk_gt_u32 s94, 0x5b
	s_cselect_b64 s[66:67], -1, 0
	s_cmpk_lt_u32 s94, 0x5c
	s_cbranch_scc1 .Lixc16
	v_mfma_f32_32x32x16_bf16 v[16:31], v[32:35], v[100:103], 0
	s_not_b64 s[54:55], s[68:69]
	v_max_i32_e32 v101, 0, v0
	v_fma_f32 v240, v48, v101, 0
	v_max_i32_e32 v101, 0, v1
	v_fmac_f32_e32 v240, v49, v101
	v_max_i32_e32 v101, 0, v2
	v_fmac_f32_e32 v240, v50, v101
	v_max_i32_e32 v101, 0, v3
	v_fmac_f32_e32 v240, v51, v101
	v_max_i32_e32 v101, 0, v4
	v_fmac_f32_e32 v240, v52, v101
	v_mfma_f32_32x32x16_bf16 v[16:31], v[36:39], v[92:95], v[16:31]
	v_max_i32_e32 v101, 0, v5
	v_fmac_f32_e32 v240, v53, v101
	v_max_i32_e32 v101, 0, v6
	v_fmac_f32_e32 v240, v54, v101
	v_max_i32_e32 v101, 0, v7
	v_fmac_f32_e32 v240, v55, v101
	v_max_i32_e32 v101, 0, v8
	v_fmac_f32_e32 v240, v56, v101
	v_max_i32_e32 v101, 0, v9
	v_fmac_f32_e32 v240, v57, v101
	v_mfma_f32_32x32x16_bf16 v[16:31], v[40:43], v[84:87], v[16:31]
	v_max_i32_e32 v101, 0, v10
	v_fmac_f32_e32 v240, v58, v101
	v_max_i32_e32 v101, 0, v11
	v_fmac_f32_e32 v240, v59, v101
	v_max_i32_e32 v101, 0, v12
	v_fmac_f32_e32 v240, v60, v101
	v_max_i32_e32 v101, 0, v13
	v_fmac_f32_e32 v240, v61, v101
	v_mfma_f32_32x32x16_bf16 v[16:31], v[44:47], v[108:111], v[16:31]
	v_max_i32_e32 v101, 0, v14
	v_fmac_f32_e32 v240, v62, v101
	v_max_i32_e32 v101, 0, v15
	v_fmac_f32_e32 v240, v63, v101
.Lixj16:
.LBB0_1997:
.LBB0_1999:
	s_waitcnt lgkmcnt(0)
	s_cmpk_lt_u32 s94, 0x5e
	s_cbranch_scc1 .Lixc15
	v_mfma_f32_32x32x16_bf16 v[0:15], v[32:35], v[96:99], 0
	v_cndmask_b32_e64 v97, 0, 1, s[66:67]
	v_cmp_ne_u32_e64 s[54:55], 1, v97
	s_andn2_b64 vcc, exec, s[66:67]
	v_max_i32_e32 v97, 0, v16
	v_fma_f32 v98, v48, v97, 0
	v_max_i32_e32 v97, 0, v17
	v_fmac_f32_e32 v98, v49, v97
	v_max_i32_e32 v97, 0, v18
	v_fmac_f32_e32 v98, v50, v97
	v_max_i32_e32 v97, 0, v19
	v_fmac_f32_e32 v98, v51, v97
	v_max_i32_e32 v97, 0, v20
	v_fmac_f32_e32 v98, v52, v97
	v_mfma_f32_32x32x16_bf16 v[0:15], v[36:39], v[88:91], v[0:15]
	v_max_i32_e32 v97, 0, v21
	v_fmac_f32_e32 v98, v53, v97
	v_max_i32_e32 v97, 0, v22
	v_fmac_f32_e32 v98, v54, v97
	v_max_i32_e32 v97, 0, v23
	v_fmac_f32_e32 v98, v55, v97
	v_max_i32_e32 v97, 0, v24
	v_fmac_f32_e32 v98, v56, v97
	v_max_i32_e32 v97, 0, v25
	v_fmac_f32_e32 v98, v57, v97
	v_mfma_f32_32x32x16_bf16 v[0:15], v[40:43], v[80:83], v[0:15]
	v_max_i32_e32 v97, 0, v26
	v_fmac_f32_e32 v98, v58, v97
	v_max_i32_e32 v97, 0, v27
	v_fmac_f32_e32 v98, v59, v97
	v_max_i32_e32 v97, 0, v28
	v_fmac_f32_e32 v98, v60, v97
	v_max_i32_e32 v97, 0, v29
	v_fmac_f32_e32 v98, v61, v97
	v_mfma_f32_32x32x16_bf16 v[0:15], v[44:47], v[104:107], v[0:15]
	v_max_i32_e32 v97, 0, v30
	s_cmp_eq_u32 s60, 47
	v_fmac_f32_e32 v98, v62, v97
	v_max_i32_e32 v97, 0, v31
	s_cselect_b64 s[0:1], -1, 0
	v_cmp_gt_i32_e32 vcc, v173, v203
	v_fmac_f32_e32 v98, v63, v97
	s_and_b64 vcc, s[0:1], vcc
	v_cndmask_b32_e32 v241, v98, v197, vcc

.Lixj14:
	s_waitcnt lgkmcnt(0)
	ds_read_b128 v[96:99], v131 offset:0x3600
	ds_read_b128 v[88:91], v131 offset:0x3620
	ds_read_b128 v[80:83], v131 offset:0x3640
	ds_read_b128 v[104:107], v131 offset:0x3660
	s_cmpk_gt_u32 s94, 0x63
	s_cselect_b64 s[62:63], -1, 0
	s_cmpk_lt_u32 s94, 0x64
	s_cbranch_scc1 .Lixc13
	v_mfma_f32_32x32x16_bf16 v[16:31], v[32:35], v[108:111], 0
	s_not_b64 s[54:55], s[0:1]
	v_max_i32_e32 v109, 0, v0
	v_fma_f32 v244, v48, v109, 0
	v_max_i32_e32 v109, 0, v1
	v_fmac_f32_e32 v244, v49, v109
	v_max_i32_e32 v109, 0, v2
	v_fmac_f32_e32 v244, v50, v109
	v_max_i32_e32 v109, 0, v3
	v_fmac_f32_e32 v244, v51, v109
	v_max_i32_e32 v109, 0, v4
	v_fmac_f32_e32 v244, v52, v109
	v_mfma_f32_32x32x16_bf16 v[16:31], v[36:39], v[100:103], v[16:31]
	v_max_i32_e32 v109, 0, v5
	v_fmac_f32_e32 v244, v53, v109
	v_max_i32_e32 v109, 0, v6
	v_fmac_f32_e32 v244, v54, v109
	v_max_i32_e32 v109, 0, v7
	v_fmac_f32_e32 v244, v55, v109
	v_max_i32_e32 v109, 0, v8
	v_fmac_f32_e32 v244, v56, v109
	v_max_i32_e32 v109, 0, v9
	v_fmac_f32_e32 v244, v57, v109
	v_mfma_f32_32x32x16_bf16 v[16:31], v[40:43], v[92:95], v[16:31]
	v_max_i32_e32 v109, 0, v10
	v_fmac_f32_e32 v244, v58, v109
	v_max_i32_e32 v109, 0, v11
	v_fmac_f32_e32 v244, v59, v109
	v_max_i32_e32 v109, 0, v12
	v_fmac_f32_e32 v244, v60, v109
	v_max_i32_e32 v109, 0, v13
	v_fmac_f32_e32 v244, v61, v109
	v_mfma_f32_32x32x16_bf16 v[16:31], v[44:47], v[84:87], v[16:31]
	v_max_i32_e32 v109, 0, v14
	v_fmac_f32_e32 v244, v62, v109
	v_max_i32_e32 v109, 0, v15
	v_fmac_f32_e32 v244, v63, v109
.Lixj13:
.LBB0_2017:
.LBB0_2019:
	s_waitcnt lgkmcnt(0)
	ds_read_b128 v[100:103], v131 offset:0x4800
	ds_read_b128 v[92:95], v131 offset:0x4820
	ds_read_b128 v[84:87], v131 offset:0x4840
	ds_read_b128 v[108:111], v131 offset:0x4860
	s_cmpk_gt_u32 s94, 0x65
	s_cselect_b64 s[66:67], -1, 0
	s_cmpk_lt_u32 s94, 0x66
	s_cbranch_scc1 .Lixc12
	v_mfma_f32_32x32x16_bf16 v[0:15], v[32:35], v[96:99], 0
	s_not_b64 s[54:55], s[62:63]
	v_max_i32_e32 v97, 0, v16
	v_fma_f32 v245, v48, v97, 0
	v_max_i32_e32 v97, 0, v17
	v_fmac_f32_e32 v245, v49, v97
	v_max_i32_e32 v97, 0, v18
	v_fmac_f32_e32 v245, v50, v97
	v_max_i32_e32 v97, 0, v19
	v_fmac_f32_e32 v245, v51, v97
	v_max_i32_e32 v97, 0, v20
	v_fmac_f32_e32 v245, v52, v97
	v_mfma_f32_32x32x16_bf16 v[0:15], v[36:39], v[88:91], v[0:15]
	v_max_i32_e32 v97, 0, v21
	v_fmac_f32_e32 v245, v53, v97
	v_max_i32_e32 v97, 0, v22
	v_fmac_f32_e32 v245, v54, v97
	v_max_i32_e32 v97, 0, v23
	v_fmac_f32_e32 v245, v55, v97
	v_max_i32_e32 v97, 0, v24
	v_fmac_f32_e32 v245, v56, v97
	v_max_i32_e32 v97, 0, v25
	v_fmac_f32_e32 v245, v57, v97
	v_mfma_f32_32x32x16_bf16 v[0:15], v[40:43], v[80:83], v[0:15]
	v_max_i32_e32 v97, 0, v26
	v_fmac_f32_e32 v245, v58, v97
	v_max_i32_e32 v97, 0, v27
	v_fmac_f32_e32 v245, v59, v97
	v_max_i32_e32 v97, 0, v28
	v_fmac_f32_e32 v245, v60, v97
	v_max_i32_e32 v97, 0, v29
	v_fmac_f32_e32 v245, v61, v97
	v_mfma_f32_32x32x16_bf16 v[0:15], v[44:47], v[104:107], v[0:15]
	v_max_i32_e32 v97, 0, v30
	v_fmac_f32_e32 v245, v62, v97
	v_max_i32_e32 v97, 0, v31
	v_fmac_f32_e32 v245, v63, v97
.Lixj12:
.LBB0_2023:
.LBB0_2025:
	s_waitcnt lgkmcnt(0)
	ds_read_b128 v[96:99], v131 offset:0x5a00
	ds_read_b128 v[88:91], v131 offset:0x5a20
	ds_read_b128 v[80:83], v131 offset:0x5a40
	ds_read_b128 v[104:107], v131 offset:0x5a60
	s_cmpk_gt_u32 s94, 0x67
	s_cselect_b64 s[62:63], -1, 0
	s_cmpk_lt_u32 s94, 0x68
	s_cbranch_scc1 .Lixc11
	v_mfma_f32_32x32x16_bf16 v[16:31], v[32:35], v[100:103], 0
	s_not_b64 s[54:55], s[66:67]
	v_max_i32_e32 v101, 0, v0
	v_fma_f32 v246, v48, v101, 0
	v_max_i32_e32 v101, 0, v1
	v_fmac_f32_e32 v246, v49, v101
	v_max_i32_e32 v101, 0, v2
	v_fmac_f32_e32 v246, v50, v101
	v_max_i32_e32 v101, 0, v3
	v_fmac_f32_e32 v246, v51, v101
	v_max_i32_e32 v101, 0, v4
	v_fmac_f32_e32 v246, v52, v101
	v_mfma_f32_32x32x16_bf16 v[16:31], v[36:39], v[92:95], v[16:31]
	v_max_i32_e32 v101, 0, v5
	v_fmac_f32_e32 v246, v53, v101
	v_max_i32_e32 v101, 0, v6
	v_fmac_f32_e32 v246, v54, v101
	v_max_i32_e32 v101, 0, v7
	v_fmac_f32_e32 v246, v55, v101
	v_max_i32_e32 v101, 0, v8
	v_fmac_f32_e32 v246, v56, v101
	v_max_i32_e32 v101, 0, v9
	v_fmac_f32_e32 v246, v57, v101
	v_mfma_f32_32x32x16_bf16 v[16:31], v[40:43], v[84:87], v[16:31]
	v_max_i32_e32 v101, 0, v10
	v_fmac_f32_e32 v246, v58, v101
	v_max_i32_e32 v101, 0, v11
	v_fmac_f32_e32 v246, v59, v101
	v_max_i32_e32 v101, 0, v12
	v_fmac_f32_e32 v246, v60, v101
	v_max_i32_e32 v101, 0, v13
	v_fmac_f32_e32 v246, v61, v101
	v_mfma_f32_32x32x16_bf16 v[16:31], v[44:47], v[108:111], v[16:31]
	v_max_i32_e32 v101, 0, v14
	v_fmac_f32_e32 v246, v62, v101
	v_max_i32_e32 v101, 0, v15
	v_fmac_f32_e32 v246, v63, v101
.Lixj11:
.LBB0_2029:
.LBB0_2031:
	s_waitcnt lgkmcnt(0)
	ds_read_b128 v[100:103], v131 offset:0x6c00
	ds_read_b128 v[92:95], v131 offset:0x6c20
	ds_read_b128 v[84:87], v131 offset:0x6c40
	ds_read_b128 v[108:111], v131 offset:0x6c60
	s_cmpk_gt_u32 s94, 0x69
	s_cselect_b64 s[66:67], -1, 0
	s_cmpk_lt_u32 s94, 0x6a
	s_cbranch_scc1 .Lixc10
	v_mfma_f32_32x32x16_bf16 v[0:15], v[32:35], v[96:99], 0
	s_not_b64 s[54:55], s[62:63]
	v_max_i32_e32 v97, 0, v16
	v_fma_f32 v247, v48, v97, 0
	v_max_i32_e32 v97, 0, v17
	v_fmac_f32_e32 v247, v49, v97
	v_max_i32_e32 v97, 0, v18
	v_fmac_f32_e32 v247, v50, v97
	v_max_i32_e32 v97, 0, v19
	v_fmac_f32_e32 v247, v51, v97
	v_max_i32_e32 v97, 0, v20
	v_fmac_f32_e32 v247, v52, v97
	v_mfma_f32_32x32x16_bf16 v[0:15], v[36:39], v[88:91], v[0:15]
	v_max_i32_e32 v97, 0, v21
	v_fmac_f32_e32 v247, v53, v97
	v_max_i32_e32 v97, 0, v22
	v_fmac_f32_e32 v247, v54, v97
	v_max_i32_e32 v97, 0, v23
	v_fmac_f32_e32 v247, v55, v97
	v_max_i32_e32 v97, 0, v24
	v_fmac_f32_e32 v247, v56, v97
	v_max_i32_e32 v97, 0, v25
	v_fmac_f32_e32 v247, v57, v97
	v_mfma_f32_32x32x16_bf16 v[0:15], v[40:43], v[80:83], v[0:15]
	v_max_i32_e32 v97, 0, v26
	v_fmac_f32_e32 v247, v58, v97
	v_max_i32_e32 v97, 0, v27
	v_fmac_f32_e32 v247, v59, v97
	v_max_i32_e32 v97, 0, v28
	v_fmac_f32_e32 v247, v60, v97
	v_max_i32_e32 v97, 0, v29
	v_fmac_f32_e32 v247, v61, v97
	v_mfma_f32_32x32x16_bf16 v[0:15], v[44:47], v[104:107], v[0:15]
	v_max_i32_e32 v97, 0, v30
	v_fmac_f32_e32 v247, v62, v97
	v_max_i32_e32 v97, 0, v31
	v_fmac_f32_e32 v247, v63, v97
.Lixj10:
.LBB0_2035:
.LBB0_2037:
	s_waitcnt lgkmcnt(0)
	ds_read_b128 v[96:99], v131 offset:0x7e00
	ds_read_b128 v[88:91], v131 offset:0x7e20
	ds_read_b128 v[80:83], v131 offset:0x7e40
	ds_read_b128 v[104:107], v131 offset:0x7e60
	s_cmpk_gt_u32 s94, 0x6b
	s_cselect_b64 s[62:63], -1, 0
	s_cmpk_lt_u32 s94, 0x6c
	s_cbranch_scc1 .Lixc9
	v_mfma_f32_32x32x16_bf16 v[16:31], v[32:35], v[100:103], 0
	s_not_b64 s[54:55], s[66:67]
	v_max_i32_e32 v101, 0, v0
	v_fma_f32 v248, v48, v101, 0
	v_max_i32_e32 v101, 0, v1
	v_fmac_f32_e32 v248, v49, v101
	v_max_i32_e32 v101, 0, v2
	v_fmac_f32_e32 v248, v50, v101
	v_max_i32_e32 v101, 0, v3
	v_fmac_f32_e32 v248, v51, v101
	v_max_i32_e32 v101, 0, v4
	v_fmac_f32_e32 v248, v52, v101
	v_mfma_f32_32x32x16_bf16 v[16:31], v[36:39], v[92:95], v[16:31]
	v_max_i32_e32 v101, 0, v5
	v_fmac_f32_e32 v248, v53, v101
	v_max_i32_e32 v101, 0, v6
	v_fmac_f32_e32 v248, v54, v101
	v_max_i32_e32 v101, 0, v7
	v_fmac_f32_e32 v248, v55, v101
	v_max_i32_e32 v101, 0, v8
	v_fmac_f32_e32 v248, v56, v101
	v_max_i32_e32 v101, 0, v9
	v_fmac_f32_e32 v248, v57, v101
	v_mfma_f32_32x32x16_bf16 v[16:31], v[40:43], v[84:87], v[16:31]
	v_max_i32_e32 v101, 0, v10
	v_fmac_f32_e32 v248, v58, v101
	v_max_i32_e32 v101, 0, v11
	v_fmac_f32_e32 v248, v59, v101
	v_max_i32_e32 v101, 0, v12
	v_fmac_f32_e32 v248, v60, v101
	v_max_i32_e32 v101, 0, v13
	v_fmac_f32_e32 v248, v61, v101
	v_mfma_f32_32x32x16_bf16 v[16:31], v[44:47], v[108:111], v[16:31]
	v_max_i32_e32 v101, 0, v14
	v_fmac_f32_e32 v248, v62, v101
	v_max_i32_e32 v101, 0, v15
	v_fmac_f32_e32 v248, v63, v101
.Lixj9:
.LBB0_2041:
.LBB0_2043:
	s_waitcnt lgkmcnt(0)
	s_cmpk_lt_u32 s94, 0x6e
	s_cbranch_scc1 .Lixc8
	v_mfma_f32_32x32x16_bf16 v[0:15], v[32:35], v[96:99], 0
	v_cndmask_b32_e64 v97, 0, 1, s[62:63]
	v_cmp_ne_u32_e64 s[54:55], 1, v97
	s_andn2_b64 vcc, exec, s[62:63]
	v_max_i32_e32 v97, 0, v16
	v_fma_f32 v98, v48, v97, 0
	v_max_i32_e32 v97, 0, v17
	v_fmac_f32_e32 v98, v49, v97
	v_max_i32_e32 v97, 0, v18
	v_fmac_f32_e32 v98, v50, v97
	v_max_i32_e32 v97, 0, v19
	v_fmac_f32_e32 v98, v51, v97
	v_max_i32_e32 v97, 0, v20
	v_fmac_f32_e32 v98, v52, v97
	v_mfma_f32_32x32x16_bf16 v[0:15], v[36:39], v[88:91], v[0:15]
	v_max_i32_e32 v97, 0, v21
	v_fmac_f32_e32 v98, v53, v97
	v_max_i32_e32 v97, 0, v22
	v_fmac_f32_e32 v98, v54, v97
	v_max_i32_e32 v97, 0, v23
	v_fmac_f32_e32 v98, v55, v97
	v_max_i32_e32 v97, 0, v24
	v_fmac_f32_e32 v98, v56, v97
	v_max_i32_e32 v97, 0, v25
	v_fmac_f32_e32 v98, v57, v97
	v_mfma_f32_32x32x16_bf16 v[0:15], v[40:43], v[80:83], v[0:15]
	v_max_i32_e32 v97, 0, v26
	v_fmac_f32_e32 v98, v58, v97
	v_max_i32_e32 v97, 0, v27
	v_fmac_f32_e32 v98, v59, v97
	v_max_i32_e32 v97, 0, v28
	v_fmac_f32_e32 v98, v60, v97
	v_max_i32_e32 v97, 0, v29
	v_fmac_f32_e32 v98, v61, v97
	v_mfma_f32_32x32x16_bf16 v[0:15], v[44:47], v[104:107], v[0:15]
	v_max_i32_e32 v97, 0, v30
	s_cmp_eq_u32 s60, 55
	v_fmac_f32_e32 v98, v62, v97
	v_max_i32_e32 v97, 0, v31
	s_cselect_b64 s[0:1], -1, 0
	v_cmp_gt_i32_e32 vcc, v181, v203
	v_fmac_f32_e32 v98, v63, v97
	s_and_b64 vcc, s[0:1], vcc
	v_cndmask_b32_e32 v249, v98, v197, vcc

.Lixj7:
	s_waitcnt lgkmcnt(0)
	ds_read_b128 v[96:99], v134 offset:0x3600
	ds_read_b128 v[88:91], v134 offset:0x3620
	ds_read_b128 v[80:83], v134 offset:0x3640
	ds_read_b128 v[104:107], v134 offset:0x3660
	s_cmpk_gt_u32 s94, 0x73
	s_cselect_b64 s[62:63], -1, 0
	s_cmpk_lt_u32 s94, 0x74
	s_cbranch_scc1 .Lixc6
	v_mfma_f32_32x32x16_bf16 v[16:31], v[32:35], v[108:111], 0
	s_not_b64 s[54:55], s[0:1]
	v_max_i32_e32 v109, 0, v0
	v_fma_f32 v252, v48, v109, 0
	v_max_i32_e32 v109, 0, v1
	v_fmac_f32_e32 v252, v49, v109
	v_max_i32_e32 v109, 0, v2
	v_fmac_f32_e32 v252, v50, v109
	v_max_i32_e32 v109, 0, v3
	v_fmac_f32_e32 v252, v51, v109
	v_max_i32_e32 v109, 0, v4
	v_fmac_f32_e32 v252, v52, v109
	v_mfma_f32_32x32x16_bf16 v[16:31], v[36:39], v[100:103], v[16:31]
	v_max_i32_e32 v109, 0, v5
	v_fmac_f32_e32 v252, v53, v109
	v_max_i32_e32 v109, 0, v6
	v_fmac_f32_e32 v252, v54, v109
	v_max_i32_e32 v109, 0, v7
	v_fmac_f32_e32 v252, v55, v109
	v_max_i32_e32 v109, 0, v8
	v_fmac_f32_e32 v252, v56, v109
	v_max_i32_e32 v109, 0, v9
	v_fmac_f32_e32 v252, v57, v109
	v_mfma_f32_32x32x16_bf16 v[16:31], v[40:43], v[92:95], v[16:31]
	v_max_i32_e32 v109, 0, v10
	v_fmac_f32_e32 v252, v58, v109
	v_max_i32_e32 v109, 0, v11
	v_fmac_f32_e32 v252, v59, v109
	v_max_i32_e32 v109, 0, v12
	v_fmac_f32_e32 v252, v60, v109
	v_max_i32_e32 v109, 0, v13
	v_fmac_f32_e32 v252, v61, v109
	v_mfma_f32_32x32x16_bf16 v[16:31], v[44:47], v[84:87], v[16:31]
	v_max_i32_e32 v109, 0, v14
	v_fmac_f32_e32 v252, v62, v109
	v_max_i32_e32 v109, 0, v15
	v_fmac_f32_e32 v252, v63, v109
.Lixj6:
.LBB0_2059:
.LBB0_2061:
	s_waitcnt lgkmcnt(0)
	ds_read_b128 v[100:103], v134 offset:0x4800
	ds_read_b128 v[92:95], v134 offset:0x4820
	ds_read_b128 v[84:87], v134 offset:0x4840
	ds_read_b128 v[108:111], v134 offset:0x4860
	s_cmpk_gt_u32 s94, 0x75
	s_cselect_b64 s[64:65], -1, 0
	s_cmpk_lt_u32 s94, 0x76
	s_cbranch_scc1 .Lixc5
	v_mfma_f32_32x32x16_bf16 v[0:15], v[32:35], v[96:99], 0
	s_not_b64 s[54:55], s[62:63]
	v_max_i32_e32 v97, 0, v16
	v_fma_f32 v253, v48, v97, 0
	v_max_i32_e32 v97, 0, v17
	v_fmac_f32_e32 v253, v49, v97
	v_max_i32_e32 v97, 0, v18
	v_fmac_f32_e32 v253, v50, v97
	v_max_i32_e32 v97, 0, v19
	v_fmac_f32_e32 v253, v51, v97
	v_max_i32_e32 v97, 0, v20
	v_fmac_f32_e32 v253, v52, v97
	v_mfma_f32_32x32x16_bf16 v[0:15], v[36:39], v[88:91], v[0:15]
	v_max_i32_e32 v97, 0, v21
	v_fmac_f32_e32 v253, v53, v97
	v_max_i32_e32 v97, 0, v22
	v_fmac_f32_e32 v253, v54, v97
	v_max_i32_e32 v97, 0, v23
	v_fmac_f32_e32 v253, v55, v97
	v_max_i32_e32 v97, 0, v24
	v_fmac_f32_e32 v253, v56, v97
	v_max_i32_e32 v97, 0, v25
	v_fmac_f32_e32 v253, v57, v97
	v_mfma_f32_32x32x16_bf16 v[0:15], v[40:43], v[80:83], v[0:15]
	v_max_i32_e32 v97, 0, v26
	v_fmac_f32_e32 v253, v58, v97
	v_max_i32_e32 v97, 0, v27
	v_fmac_f32_e32 v253, v59, v97
	v_max_i32_e32 v97, 0, v28
	v_fmac_f32_e32 v253, v60, v97
	v_max_i32_e32 v97, 0, v29
	v_fmac_f32_e32 v253, v61, v97
	v_mfma_f32_32x32x16_bf16 v[0:15], v[44:47], v[104:107], v[0:15]
	v_max_i32_e32 v97, 0, v30
	v_fmac_f32_e32 v253, v62, v97
	v_max_i32_e32 v97, 0, v31
	v_fmac_f32_e32 v253, v63, v97
.Lixj5:
.LBB0_2065:
.LBB0_2067:
	s_waitcnt lgkmcnt(0)
	ds_read_b128 v[96:99], v134 offset:0x5a00
	ds_read_b128 v[88:91], v134 offset:0x5a20
	ds_read_b128 v[80:83], v134 offset:0x5a40
	ds_read_b128 v[104:107], v134 offset:0x5a60
	s_cmpk_gt_u32 s94, 0x77
	s_cselect_b64 s[62:63], -1, 0
	s_cmpk_lt_u32 s94, 0x78
	s_cbranch_scc1 .Lixc4
	v_mfma_f32_32x32x16_bf16 v[16:31], v[32:35], v[100:103], 0
	s_not_b64 s[54:55], s[64:65]
	v_max_i32_e32 v101, 0, v0
	v_fma_f32 v215, v48, v101, 0
	v_max_i32_e32 v101, 0, v1
	v_fmac_f32_e32 v215, v49, v101
	v_max_i32_e32 v101, 0, v2
	v_fmac_f32_e32 v215, v50, v101
	v_max_i32_e32 v101, 0, v3
	v_fmac_f32_e32 v215, v51, v101
	v_max_i32_e32 v101, 0, v4
	v_fmac_f32_e32 v215, v52, v101
	v_mfma_f32_32x32x16_bf16 v[16:31], v[36:39], v[92:95], v[16:31]
	v_max_i32_e32 v101, 0, v5
	v_fmac_f32_e32 v215, v53, v101
	v_max_i32_e32 v101, 0, v6
	v_fmac_f32_e32 v215, v54, v101
	v_max_i32_e32 v101, 0, v7
	v_fmac_f32_e32 v215, v55, v101
	v_max_i32_e32 v101, 0, v8
	v_fmac_f32_e32 v215, v56, v101
	v_max_i32_e32 v101, 0, v9
	v_fmac_f32_e32 v215, v57, v101
	v_mfma_f32_32x32x16_bf16 v[16:31], v[40:43], v[84:87], v[16:31]
	v_max_i32_e32 v101, 0, v10
	v_fmac_f32_e32 v215, v58, v101
	v_max_i32_e32 v101, 0, v11
	v_fmac_f32_e32 v215, v59, v101
	v_max_i32_e32 v101, 0, v12
	v_fmac_f32_e32 v215, v60, v101
	v_max_i32_e32 v101, 0, v13
	v_fmac_f32_e32 v215, v61, v101
	v_mfma_f32_32x32x16_bf16 v[16:31], v[44:47], v[108:111], v[16:31]
	v_max_i32_e32 v101, 0, v14
	v_fmac_f32_e32 v215, v62, v101
	v_max_i32_e32 v101, 0, v15
	v_fmac_f32_e32 v215, v63, v101
.Lixj4:
.LBB0_2071:
.LBB0_2073:
	s_waitcnt lgkmcnt(0)
	ds_read_b128 v[100:103], v134 offset:0x6c00
	ds_read_b128 v[92:95], v134 offset:0x6c20
	ds_read_b128 v[84:87], v134 offset:0x6c40
	ds_read_b128 v[108:111], v134 offset:0x6c60
	s_cmpk_gt_u32 s94, 0x79
	s_cselect_b64 s[64:65], -1, 0
	s_cmpk_lt_u32 s94, 0x7a
	s_cbranch_scc1 .Lixc3
	v_mfma_f32_32x32x16_bf16 v[0:15], v[32:35], v[96:99], 0
	s_not_b64 s[54:55], s[62:63]
	v_max_i32_e32 v97, 0, v16
	v_fma_f32 v133, v48, v97, 0
	v_max_i32_e32 v97, 0, v17
	v_fmac_f32_e32 v133, v49, v97
	v_max_i32_e32 v97, 0, v18
	v_fmac_f32_e32 v133, v50, v97
	v_max_i32_e32 v97, 0, v19
	v_fmac_f32_e32 v133, v51, v97
	v_max_i32_e32 v97, 0, v20
	v_fmac_f32_e32 v133, v52, v97
	v_mfma_f32_32x32x16_bf16 v[0:15], v[36:39], v[88:91], v[0:15]
	v_max_i32_e32 v97, 0, v21
	v_fmac_f32_e32 v133, v53, v97
	v_max_i32_e32 v97, 0, v22
	v_fmac_f32_e32 v133, v54, v97
	v_max_i32_e32 v97, 0, v23
	v_fmac_f32_e32 v133, v55, v97
	v_max_i32_e32 v97, 0, v24
	v_fmac_f32_e32 v133, v56, v97
	v_max_i32_e32 v97, 0, v25
	v_fmac_f32_e32 v133, v57, v97
	v_mfma_f32_32x32x16_bf16 v[0:15], v[40:43], v[80:83], v[0:15]
	v_max_i32_e32 v97, 0, v26
	v_fmac_f32_e32 v133, v58, v97
	v_max_i32_e32 v97, 0, v27
	v_fmac_f32_e32 v133, v59, v97
	v_max_i32_e32 v97, 0, v28
	v_fmac_f32_e32 v133, v60, v97
	v_max_i32_e32 v97, 0, v29
	v_fmac_f32_e32 v133, v61, v97
	v_mfma_f32_32x32x16_bf16 v[0:15], v[44:47], v[104:107], v[0:15]
	v_max_i32_e32 v97, 0, v30
	v_fmac_f32_e32 v133, v62, v97
	v_max_i32_e32 v97, 0, v31
	v_fmac_f32_e32 v133, v63, v97
.Lixj3:
.LBB0_2077:
.LBB0_2079:
	s_waitcnt lgkmcnt(0)
	ds_read_b128 v[96:99], v134 offset:0x7e00
	ds_read_b128 v[88:91], v134 offset:0x7e20
	ds_read_b128 v[80:83], v134 offset:0x7e40
	ds_read_b128 v[104:107], v134 offset:0x7e60
	s_cmpk_gt_u32 s94, 0x7b
	s_cselect_b64 s[62:63], -1, 0
	s_cmpk_lt_u32 s94, 0x7c
	s_cbranch_scc1 .Lixc2
	v_mfma_f32_32x32x16_bf16 v[16:31], v[32:35], v[100:103], 0
	s_not_b64 s[54:55], s[64:65]
	v_max_i32_e32 v101, 0, v0
	v_fma_f32 v84, v48, v101, 0
	v_max_i32_e32 v101, 0, v1
	v_fmac_f32_e32 v84, v49, v101
	v_max_i32_e32 v101, 0, v2
	v_fmac_f32_e32 v84, v50, v101
	v_max_i32_e32 v101, 0, v3
	v_fmac_f32_e32 v84, v51, v101
	v_max_i32_e32 v101, 0, v4
	v_fmac_f32_e32 v84, v52, v101
	v_mfma_f32_32x32x16_bf16 v[16:31], v[36:39], v[92:95], v[16:31]
	v_max_i32_e32 v101, 0, v5
	v_fmac_f32_e32 v84, v53, v101
	v_max_i32_e32 v101, 0, v6
	v_fmac_f32_e32 v84, v54, v101
	v_max_i32_e32 v101, 0, v7
	v_fmac_f32_e32 v84, v55, v101
	v_max_i32_e32 v101, 0, v8
	v_fmac_f32_e32 v84, v56, v101
	v_max_i32_e32 v101, 0, v9
	v_fmac_f32_e32 v84, v57, v101
	v_mfma_f32_32x32x16_bf16 v[16:31], v[40:43], v[84:87], v[16:31]
	v_max_i32_e32 v101, 0, v10
	v_fmac_f32_e32 v84, v58, v101
	v_max_i32_e32 v101, 0, v11
	v_fmac_f32_e32 v84, v59, v101
	v_max_i32_e32 v101, 0, v12
	v_fmac_f32_e32 v84, v60, v101
	v_max_i32_e32 v101, 0, v13
	v_fmac_f32_e32 v84, v61, v101
	v_mfma_f32_32x32x16_bf16 v[16:31], v[44:47], v[108:111], v[16:31]
	v_max_i32_e32 v101, 0, v14
	v_fmac_f32_e32 v84, v62, v101
	v_max_i32_e32 v101, 0, v15
	v_fmac_f32_e32 v84, v63, v101
.Lixj2:
.LBB0_2083:
.LBB0_2085:
	s_waitcnt lgkmcnt(0)
	s_cmpk_lt_u32 s94, 0x7e
	s_cbranch_scc1 .Lixc1
	v_mfma_f32_32x32x16_bf16 v[0:15], v[32:35], v[96:99], 0
	v_cndmask_b32_e64 v97, 0, 1, s[62:63]
	v_cmp_ne_u32_e64 s[54:55], 1, v97
	s_andn2_b64 vcc, exec, s[62:63]
	v_max_i32_e32 v97, 0, v16
	v_fma_f32 v98, v48, v97, 0
	v_max_i32_e32 v97, 0, v17
	v_fmac_f32_e32 v98, v49, v97
	v_max_i32_e32 v97, 0, v18
	v_fmac_f32_e32 v98, v50, v97
	v_max_i32_e32 v97, 0, v19
	v_fmac_f32_e32 v98, v51, v97
	v_max_i32_e32 v97, 0, v20
	v_fmac_f32_e32 v98, v52, v97
	v_mfma_f32_32x32x16_bf16 v[0:15], v[36:39], v[88:91], v[0:15]
	v_max_i32_e32 v97, 0, v21
	v_fmac_f32_e32 v98, v53, v97
	v_max_i32_e32 v97, 0, v22
	v_fmac_f32_e32 v98, v54, v97
	v_max_i32_e32 v97, 0, v23
	v_fmac_f32_e32 v98, v55, v97
	v_max_i32_e32 v97, 0, v24
	v_fmac_f32_e32 v98, v56, v97
	v_max_i32_e32 v97, 0, v25
	v_fmac_f32_e32 v98, v57, v97
	v_mfma_f32_32x32x16_bf16 v[0:15], v[40:43], v[80:83], v[0:15]
	v_max_i32_e32 v97, 0, v26
	v_fmac_f32_e32 v98, v58, v97
	v_max_i32_e32 v97, 0, v27
	v_fmac_f32_e32 v98, v59, v97
	v_max_i32_e32 v97, 0, v28
	v_fmac_f32_e32 v98, v60, v97
	v_max_i32_e32 v97, 0, v29
	v_fmac_f32_e32 v98, v61, v97
	v_mfma_f32_32x32x16_bf16 v[0:15], v[44:47], v[104:107], v[0:15]
	v_max_i32_e32 v97, 0, v30
	s_cmp_eq_u32 s60, 63
	v_fmac_f32_e32 v98, v62, v97
	v_max_i32_e32 v97, 0, v31
	s_cselect_b64 s[0:1], -1, 0
	v_cmp_gt_i32_e32 vcc, v189, v203
	v_fmac_f32_e32 v98, v63, v97
	s_and_b64 vcc, s[0:1], vcc
	v_cndmask_b32_e32 v80, v98, v197, vcc
.Lixj1:
.LBB0_2089:
.LBB0_2091:
	s_barrier
	s_cmp_lg_u32 s60, 64
	v_mov_b32_e32 v16, 0xff800000
	s_cbranch_scc0 .LBB0_2117
	s_branch .LBB0_2118
